# K-loop LDS-DMA loads use SGPR base + 32-bit VGPR offset (saddr form) instead of a 64-bit VALU add per load; +0x80 chains become scalar adds; M0 wait states filled with ds_reads
# speedup vs baseline: 1.0246x; 1.0105x over previous
.LBB0_122:
	v_mov_b64_e32 v[0:1], 0x180
	s_ashr_i32 s15, s14, 31
	v_cmp_lt_i64_e32 vcc, s[16:17], v[0:1]
	s_lshl_b64 s[16:17], s[14:15], 19
	s_add_u32 s16, s30, s16
	s_addc_u32 s17, s31, s17
	s_and_b64 s[18:19], vcc, exec
	s_cselect_b32 s7, s17, s21
	s_cselect_b32 s9, s16, s20
	s_ashr_i32 s13, s12, 31
	s_lshl_b64 s[18:19], s[12:13], 19
	s_add_u32 s18, s34, s18
	s_addc_u32 s19, s35, s19
	s_and_b64 s[22:23], vcc, exec
	s_cselect_b32 s13, s19, s3
	s_cselect_b32 s15, s18, s2
	s_add_u32 s20, s20, 0x40080
	s_addc_u32 s21, s21, 0
	s_add_u32 s50, s2, 0x100
	s_addc_u32 s51, s3, 0
	s_mov_b32 s52, -2
	s_add_u32 s2, s20, 0xfffc0080
	s_addc_u32 s3, s21, -1
	s_add_i32 s53, 0, 0x10000
	v_add_u32_e32 v36, s53, v164
	ds_read_b128 v[24:27], v36
	ds_read_b128 v[28:31], v36 offset:1024
	ds_read_b128 v[32:35], v36 offset:2048
	ds_read_b128 v[36:39], v36 offset:3072
	s_cmp_eq_u32 s52, 12
	s_cselect_b32 s23, s7, s3
	s_cselect_b32 s22, s9, s2
	s_cselect_b32 s3, s13, s51
	s_cselect_b32 s2, s15, s50
	s_add_i32 m0, s37, 0xc000
	ds_read_b128 v[154:157], v165
	ds_read_b128 v[158:161], v165 offset:1024
	ds_read_b128 v[180:183], v165 offset:2048
	ds_read_b128 v[184:187], v165 offset:3072
	ds_read_b128 v[188:191], v165 offset:4096
	ds_read_b128 v[192:195], v165 offset:5120
	ds_read_b128 v[196:199], v165 offset:6144
	global_load_lds_dwordx4 v150, s[20:21]
	s_add_i32 m0, s37, 0xe000
	ds_read_b128 v[200:203], v165 offset:7168
	global_load_lds_dwordx4 v152, s[20:21]
	s_waitcnt lgkmcnt(8)
	s_barrier
	s_waitcnt lgkmcnt(0)
	v_mfma_f32_16x16x32_bf16 v[140:143], v[24:27], v[154:157], 0
	v_mfma_f32_16x16x32_bf16 v[136:139], v[32:35], v[154:157], 0
	v_mfma_f32_16x16x32_bf16 v[124:127], v[24:27], v[180:183], 0
	v_mfma_f32_16x16x32_bf16 v[120:123], v[32:35], v[180:183], 0
	v_mfma_f32_16x16x32_bf16 v[108:111], v[24:27], v[188:191], 0
	v_mfma_f32_16x16x32_bf16 v[104:107], v[32:35], v[188:191], 0
	v_mfma_f32_16x16x32_bf16 v[92:95], v[24:27], v[196:199], 0
	v_mfma_f32_16x16x32_bf16 v[88:91], v[32:35], v[196:199], 0
	v_mfma_f32_16x16x32_bf16 v[140:143], v[28:31], v[158:161], v[140:143]
	v_mfma_f32_16x16x32_bf16 v[136:139], v[36:39], v[158:161], v[136:139]
	v_mfma_f32_16x16x32_bf16 v[124:127], v[28:31], v[184:187], v[124:127]
	v_mfma_f32_16x16x32_bf16 v[120:123], v[36:39], v[184:187], v[120:123]
	v_mfma_f32_16x16x32_bf16 v[108:111], v[28:31], v[192:195], v[108:111]
	v_mfma_f32_16x16x32_bf16 v[104:107], v[36:39], v[192:195], v[104:107]
	v_mfma_f32_16x16x32_bf16 v[92:95], v[28:31], v[200:203], v[92:95]
	v_mfma_f32_16x16x32_bf16 v[88:91], v[36:39], v[200:203], v[88:91]
	s_barrier
	s_add_i32 s56, 0, 0x14000
	v_add_u32_e32 v166, s56, v164
	s_add_i32 s53, s53, s36
	ds_read_b128 v[204:207], v166
	ds_read_b128 v[208:211], v166 offset:1024
	ds_read_b128 v[212:215], v166 offset:2048
	ds_read_b128 v[216:219], v166 offset:3072
	s_mov_b32 m0, s53
	s_add_u32 s98, s2, 0x80
	s_addc_u32 s99, s3, 0
	global_load_lds_dwordx4 v168, s[2:3]
	s_add_i32 m0, s53, 0x2000
	s_nop 0
	global_load_lds_dwordx4 v148, s[2:3]
	s_barrier
	s_waitcnt lgkmcnt(0)
	v_mfma_f32_16x16x32_bf16 v[132:135], v[204:207], v[154:157], 0
	v_mfma_f32_16x16x32_bf16 v[128:131], v[212:215], v[154:157], 0
	v_mfma_f32_16x16x32_bf16 v[116:119], v[204:207], v[180:183], 0
	v_mfma_f32_16x16x32_bf16 v[112:115], v[212:215], v[180:183], 0
	v_mfma_f32_16x16x32_bf16 v[100:103], v[204:207], v[188:191], 0
	v_mfma_f32_16x16x32_bf16 v[96:99], v[212:215], v[188:191], 0
	v_mfma_f32_16x16x32_bf16 v[84:87], v[204:207], v[196:199], 0
	v_mfma_f32_16x16x32_bf16 v[80:83], v[212:215], v[196:199], 0
	v_mfma_f32_16x16x32_bf16 v[132:135], v[208:211], v[158:161], v[132:135]
	v_mfma_f32_16x16x32_bf16 v[128:131], v[216:219], v[158:161], v[128:131]
	v_mfma_f32_16x16x32_bf16 v[116:119], v[208:211], v[184:187], v[116:119]
	v_mfma_f32_16x16x32_bf16 v[112:115], v[216:219], v[184:187], v[112:115]
	v_mfma_f32_16x16x32_bf16 v[100:103], v[208:211], v[192:195], v[100:103]
	v_mfma_f32_16x16x32_bf16 v[96:99], v[216:219], v[192:195], v[96:99]
	v_mfma_f32_16x16x32_bf16 v[84:87], v[208:211], v[200:203], v[84:87]
	v_mfma_f32_16x16x32_bf16 v[80:83], v[216:219], v[200:203], v[80:83]
	s_mov_b32 m0, s37
	s_add_u32 s100, s22, 0x80
	s_addc_u32 s101, s23, 0
	s_barrier
	ds_read_b128 v[154:157], v165 offset:16384
	ds_read_b128 v[158:161], v165 offset:17408
	ds_read_b128 v[180:183], v165 offset:18432
	ds_read_b128 v[184:187], v165 offset:19456
	ds_read_b128 v[188:191], v165 offset:20480
	ds_read_b128 v[192:195], v165 offset:21504
	ds_read_b128 v[196:199], v165 offset:22528
	global_load_lds_dwordx4 v144, s[22:23]
	s_mov_b32 m0, s38
	ds_read_b128 v[200:203], v165 offset:23552
	global_load_lds_dwordx4 v146, s[22:23]
	s_barrier
	s_waitcnt lgkmcnt(0)
	v_mfma_f32_16x16x32_bf16 v[76:79], v[24:27], v[154:157], 0
	v_mfma_f32_16x16x32_bf16 v[72:75], v[32:35], v[154:157], 0
	v_mfma_f32_16x16x32_bf16 v[60:63], v[24:27], v[180:183], 0
	v_mfma_f32_16x16x32_bf16 v[56:59], v[32:35], v[180:183], 0
	v_mfma_f32_16x16x32_bf16 v[44:47], v[24:27], v[188:191], 0
	v_mfma_f32_16x16x32_bf16 v[40:43], v[32:35], v[188:191], 0
	v_mfma_f32_16x16x32_bf16 v[12:15], v[24:27], v[196:199], 0
	v_mfma_f32_16x16x32_bf16 v[8:11], v[32:35], v[196:199], 0
	v_mfma_f32_16x16x32_bf16 v[76:79], v[28:31], v[158:161], v[76:79]
	v_mfma_f32_16x16x32_bf16 v[72:75], v[36:39], v[158:161], v[72:75]
	v_mfma_f32_16x16x32_bf16 v[60:63], v[28:31], v[184:187], v[60:63]
	v_mfma_f32_16x16x32_bf16 v[56:59], v[36:39], v[184:187], v[56:59]
	v_mfma_f32_16x16x32_bf16 v[44:47], v[28:31], v[192:195], v[44:47]
	v_mfma_f32_16x16x32_bf16 v[40:43], v[36:39], v[192:195], v[40:43]
	v_mfma_f32_16x16x32_bf16 v[12:15], v[28:31], v[200:203], v[12:15]
	v_mfma_f32_16x16x32_bf16 v[8:11], v[36:39], v[200:203], v[8:11]
	s_barrier
	s_add_i32 s53, s56, s36
	s_mov_b32 m0, s53
	s_add_u32 s54, s2, 0x40000
	s_addc_u32 s55, s3, 0
	global_load_lds_dwordx4 v168, s[54:55]
	s_add_i32 m0, s53, 0x2000
	s_nop 0
	global_load_lds_dwordx4 v148, s[54:55]
	s_waitcnt vmcnt(6)
	s_barrier
	v_mfma_f32_16x16x32_bf16 v[20:23], v[204:207], v[188:191], 0
	v_mfma_f32_16x16x32_bf16 v[16:19], v[212:215], v[188:191], 0
	v_mfma_f32_16x16x32_bf16 v[4:7], v[204:207], v[196:199], 0
	v_mfma_f32_16x16x32_bf16 v[0:3], v[212:215], v[196:199], 0
	v_mfma_f32_16x16x32_bf16 v[24:27], v[204:207], v[154:157], 0
	v_mfma_f32_16x16x32_bf16 v[28:31], v[212:215], v[154:157], 0
	v_mfma_f32_16x16x32_bf16 v[32:35], v[204:207], v[180:183], 0
	v_mfma_f32_16x16x32_bf16 v[36:39], v[212:215], v[180:183], 0
	v_mfma_f32_16x16x32_bf16 v[20:23], v[208:211], v[192:195], v[20:23]
	v_mfma_f32_16x16x32_bf16 v[16:19], v[216:219], v[192:195], v[16:19]
	v_mfma_f32_16x16x32_bf16 v[4:7], v[208:211], v[200:203], v[4:7]
	v_mfma_f32_16x16x32_bf16 v[0:3], v[216:219], v[200:203], v[0:3]
	v_mfma_f32_16x16x32_bf16 v[24:27], v[208:211], v[158:161], v[24:27]
	v_mfma_f32_16x16x32_bf16 v[28:31], v[216:219], v[158:161], v[28:31]
	v_mfma_f32_16x16x32_bf16 v[32:35], v[208:211], v[184:187], v[32:35]
	v_mfma_f32_16x16x32_bf16 v[36:39], v[216:219], v[184:187], v[36:39]
	s_add_i32 s53, 0, 0x18000
	v_add_u32_e32 v68, s53, v164
	s_barrier
	ds_read_b128 v[48:51], v68
	ds_read_b128 v[52:55], v68 offset:1024
	ds_read_b128 v[64:67], v68 offset:2048
	ds_read_b128 v[68:71], v68 offset:3072
	s_add_u32 s22, s22, 0x40000
	s_addc_u32 s23, s23, 0
	s_mov_b32 m0, s39
	ds_read_b128 v[154:157], v165 offset:32768
	ds_read_b128 v[158:161], v165 offset:33792
	ds_read_b128 v[180:183], v165 offset:34816
	ds_read_b128 v[184:187], v165 offset:35840
	ds_read_b128 v[188:191], v165 offset:36864
	ds_read_b128 v[192:195], v165 offset:37888
	ds_read_b128 v[196:199], v165 offset:38912
	global_load_lds_dwordx4 v144, s[22:23]
	s_mov_b32 m0, s40
	ds_read_b128 v[200:203], v165 offset:39936
	global_load_lds_dwordx4 v146, s[22:23]
	s_waitcnt lgkmcnt(8)
	s_barrier
	s_waitcnt lgkmcnt(0)
	v_mfma_f32_16x16x32_bf16 v[140:143], v[48:51], v[154:157], v[140:143]
	v_mfma_f32_16x16x32_bf16 v[136:139], v[64:67], v[154:157], v[136:139]
	v_mfma_f32_16x16x32_bf16 v[124:127], v[48:51], v[180:183], v[124:127]
	v_mfma_f32_16x16x32_bf16 v[120:123], v[64:67], v[180:183], v[120:123]
	v_mfma_f32_16x16x32_bf16 v[108:111], v[48:51], v[188:191], v[108:111]
	v_mfma_f32_16x16x32_bf16 v[104:107], v[64:67], v[188:191], v[104:107]
	v_mfma_f32_16x16x32_bf16 v[92:95], v[48:51], v[196:199], v[92:95]
	v_mfma_f32_16x16x32_bf16 v[88:91], v[64:67], v[196:199], v[88:91]
	v_mfma_f32_16x16x32_bf16 v[140:143], v[52:55], v[158:161], v[140:143]
	v_mfma_f32_16x16x32_bf16 v[136:139], v[68:71], v[158:161], v[136:139]
	v_mfma_f32_16x16x32_bf16 v[124:127], v[52:55], v[184:187], v[124:127]
	v_mfma_f32_16x16x32_bf16 v[120:123], v[68:71], v[184:187], v[120:123]
	v_mfma_f32_16x16x32_bf16 v[108:111], v[52:55], v[192:195], v[108:111]
	v_mfma_f32_16x16x32_bf16 v[104:107], v[68:71], v[192:195], v[104:107]
	v_mfma_f32_16x16x32_bf16 v[92:95], v[52:55], v[200:203], v[92:95]
	v_mfma_f32_16x16x32_bf16 v[88:91], v[68:71], v[200:203], v[88:91]
	s_barrier
	s_add_i32 s22, 0, 0x1c000
	s_add_i32 s23, s53, s36
	v_add_u32_e32 v216, s22, v164
	s_mov_b32 m0, s23
	ds_read_b128 v[204:207], v216
	ds_read_b128 v[208:211], v216 offset:1024
	ds_read_b128 v[212:215], v216 offset:2048
	global_load_lds_dwordx4 v168, s[98:99]
	s_add_i32 m0, s23, 0x2000
	ds_read_b128 v[216:219], v216 offset:3072
	global_load_lds_dwordx4 v148, s[98:99]
	s_barrier
	s_waitcnt lgkmcnt(0)
	v_mfma_f32_16x16x32_bf16 v[132:135], v[204:207], v[154:157], v[132:135]
	v_mfma_f32_16x16x32_bf16 v[128:131], v[212:215], v[154:157], v[128:131]
	v_mfma_f32_16x16x32_bf16 v[116:119], v[204:207], v[180:183], v[116:119]
	v_mfma_f32_16x16x32_bf16 v[112:115], v[212:215], v[180:183], v[112:115]
	v_mfma_f32_16x16x32_bf16 v[100:103], v[204:207], v[188:191], v[100:103]
	v_mfma_f32_16x16x32_bf16 v[96:99], v[212:215], v[188:191], v[96:99]
	v_mfma_f32_16x16x32_bf16 v[84:87], v[204:207], v[196:199], v[84:87]
	v_mfma_f32_16x16x32_bf16 v[80:83], v[212:215], v[196:199], v[80:83]
	v_mfma_f32_16x16x32_bf16 v[132:135], v[208:211], v[158:161], v[132:135]
	v_mfma_f32_16x16x32_bf16 v[128:131], v[216:219], v[158:161], v[128:131]
	v_mfma_f32_16x16x32_bf16 v[116:119], v[208:211], v[184:187], v[116:119]
	v_mfma_f32_16x16x32_bf16 v[112:115], v[216:219], v[184:187], v[112:115]
	v_mfma_f32_16x16x32_bf16 v[100:103], v[208:211], v[192:195], v[100:103]
	v_mfma_f32_16x16x32_bf16 v[96:99], v[216:219], v[192:195], v[96:99]
	v_mfma_f32_16x16x32_bf16 v[84:87], v[208:211], v[200:203], v[84:87]
	v_mfma_f32_16x16x32_bf16 v[80:83], v[216:219], v[200:203], v[80:83]
	s_mov_b32 m0, s45
	s_barrier
	ds_read_b128 v[154:157], v165 offset:49152
	ds_read_b128 v[158:161], v165 offset:50176
	ds_read_b128 v[180:183], v165 offset:51200
	ds_read_b128 v[184:187], v165 offset:52224
	ds_read_b128 v[188:191], v165 offset:53248
	ds_read_b128 v[192:195], v165 offset:54272
	ds_read_b128 v[196:199], v165 offset:55296
	global_load_lds_dwordx4 v144, s[100:101]
	s_mov_b32 m0, s46
	ds_read_b128 v[200:203], v165 offset:56320
	global_load_lds_dwordx4 v146, s[100:101]
	s_barrier
	s_waitcnt lgkmcnt(0)
	v_mfma_f32_16x16x32_bf16 v[76:79], v[48:51], v[154:157], v[76:79]
	v_mfma_f32_16x16x32_bf16 v[72:75], v[64:67], v[154:157], v[72:75]
	v_mfma_f32_16x16x32_bf16 v[60:63], v[48:51], v[180:183], v[60:63]
	v_mfma_f32_16x16x32_bf16 v[56:59], v[64:67], v[180:183], v[56:59]
	v_mfma_f32_16x16x32_bf16 v[44:47], v[48:51], v[188:191], v[44:47]
	v_mfma_f32_16x16x32_bf16 v[40:43], v[64:67], v[188:191], v[40:43]
	v_mfma_f32_16x16x32_bf16 v[12:15], v[48:51], v[196:199], v[12:15]
	v_mfma_f32_16x16x32_bf16 v[8:11], v[64:67], v[196:199], v[8:11]
	v_mfma_f32_16x16x32_bf16 v[76:79], v[52:55], v[158:161], v[76:79]
	v_mfma_f32_16x16x32_bf16 v[72:75], v[68:71], v[158:161], v[72:75]
	v_mfma_f32_16x16x32_bf16 v[60:63], v[52:55], v[184:187], v[60:63]
	v_mfma_f32_16x16x32_bf16 v[56:59], v[68:71], v[184:187], v[56:59]
	v_mfma_f32_16x16x32_bf16 v[44:47], v[52:55], v[192:195], v[44:47]
	v_mfma_f32_16x16x32_bf16 v[40:43], v[68:71], v[192:195], v[40:43]
	v_mfma_f32_16x16x32_bf16 v[12:15], v[52:55], v[200:203], v[12:15]
	v_mfma_f32_16x16x32_bf16 v[8:11], v[68:71], v[200:203], v[8:11]
	s_barrier
	s_add_i32 s22, s22, s36
	s_mov_b32 m0, s22
	s_add_u32 s2, s2, 0x40080
	s_addc_u32 s3, s3, 0
	global_load_lds_dwordx4 v168, s[2:3]
	s_add_i32 m0, s22, 0x2000
	s_nop 0
	global_load_lds_dwordx4 v148, s[2:3]
	s_waitcnt vmcnt(6)
	s_barrier
	v_mfma_f32_16x16x32_bf16 v[24:27], v[204:207], v[154:157], v[24:27]
	v_mfma_f32_16x16x32_bf16 v[68:71], v[208:211], v[158:161], v[24:27]
	v_mfma_f32_16x16x32_bf16 v[24:27], v[212:215], v[154:157], v[28:31]
	v_mfma_f32_16x16x32_bf16 v[64:67], v[216:219], v[158:161], v[24:27]
	v_mfma_f32_16x16x32_bf16 v[24:27], v[204:207], v[180:183], v[32:35]
	v_mfma_f32_16x16x32_bf16 v[52:55], v[208:211], v[184:187], v[24:27]
	v_mfma_f32_16x16x32_bf16 v[24:27], v[212:215], v[180:183], v[36:39]
	v_mfma_f32_16x16x32_bf16 v[20:23], v[204:207], v[188:191], v[20:23]
	v_mfma_f32_16x16x32_bf16 v[16:19], v[212:215], v[188:191], v[16:19]
	v_mfma_f32_16x16x32_bf16 v[4:7], v[204:207], v[196:199], v[4:7]
	v_mfma_f32_16x16x32_bf16 v[0:3], v[212:215], v[196:199], v[0:3]
	v_mfma_f32_16x16x32_bf16 v[48:51], v[216:219], v[184:187], v[24:27]
	v_mfma_f32_16x16x32_bf16 v[20:23], v[208:211], v[192:195], v[20:23]
	v_mfma_f32_16x16x32_bf16 v[16:19], v[216:219], v[192:195], v[16:19]
	v_mfma_f32_16x16x32_bf16 v[4:7], v[208:211], v[200:203], v[4:7]
	v_mfma_f32_16x16x32_bf16 v[0:3], v[216:219], v[200:203], v[0:3]
	s_add_i32 s52, s52, 2
	s_add_u32 s20, s20, 0x100
	s_addc_u32 s21, s21, 0
	s_add_u32 s50, s50, 0x100
	s_addc_u32 s51, s51, 0
	s_cmp_gt_u32 s52, 13
	s_barrier
.LBB0_123:
	s_add_u32 s2, s20, 0xfffc0080
	s_addc_u32 s3, s21, -1
	s_add_i32 s53, 0, 0x10000
	v_add_u32_e32 v36, s53, v164
	ds_read_b128 v[24:27], v36
	ds_read_b128 v[28:31], v36 offset:1024
	ds_read_b128 v[32:35], v36 offset:2048
	ds_read_b128 v[36:39], v36 offset:3072
	s_cmp_eq_u32 s52, 12
	s_cselect_b32 s23, s7, s3
	s_cselect_b32 s22, s9, s2
	s_cselect_b32 s3, s13, s51
	s_cselect_b32 s2, s15, s50
	s_add_i32 m0, s37, 0xc000
	ds_read_b128 v[154:157], v165
	ds_read_b128 v[158:161], v165 offset:1024
	ds_read_b128 v[180:183], v165 offset:2048
	ds_read_b128 v[184:187], v165 offset:3072
	ds_read_b128 v[188:191], v165 offset:4096
	ds_read_b128 v[192:195], v165 offset:5120
	ds_read_b128 v[196:199], v165 offset:6144
	global_load_lds_dwordx4 v150, s[20:21]
	s_add_i32 m0, s37, 0xe000
	ds_read_b128 v[200:203], v165 offset:7168
	global_load_lds_dwordx4 v152, s[20:21]
	s_waitcnt lgkmcnt(8)
	s_barrier
	s_waitcnt lgkmcnt(0)
	v_mfma_f32_16x16x32_bf16 v[140:143], v[24:27], v[154:157], v[140:143]
	v_mfma_f32_16x16x32_bf16 v[136:139], v[32:35], v[154:157], v[136:139]
	v_mfma_f32_16x16x32_bf16 v[124:127], v[24:27], v[180:183], v[124:127]
	v_mfma_f32_16x16x32_bf16 v[120:123], v[32:35], v[180:183], v[120:123]
	v_mfma_f32_16x16x32_bf16 v[108:111], v[24:27], v[188:191], v[108:111]
	v_mfma_f32_16x16x32_bf16 v[104:107], v[32:35], v[188:191], v[104:107]
	v_mfma_f32_16x16x32_bf16 v[92:95], v[24:27], v[196:199], v[92:95]
	v_mfma_f32_16x16x32_bf16 v[88:91], v[32:35], v[196:199], v[88:91]
	v_mfma_f32_16x16x32_bf16 v[140:143], v[28:31], v[158:161], v[140:143]
	v_mfma_f32_16x16x32_bf16 v[136:139], v[36:39], v[158:161], v[136:139]
	v_mfma_f32_16x16x32_bf16 v[124:127], v[28:31], v[184:187], v[124:127]
	v_mfma_f32_16x16x32_bf16 v[120:123], v[36:39], v[184:187], v[120:123]
	v_mfma_f32_16x16x32_bf16 v[108:111], v[28:31], v[192:195], v[108:111]
	v_mfma_f32_16x16x32_bf16 v[104:107], v[36:39], v[192:195], v[104:107]
	v_mfma_f32_16x16x32_bf16 v[92:95], v[28:31], v[200:203], v[92:95]
	v_mfma_f32_16x16x32_bf16 v[88:91], v[36:39], v[200:203], v[88:91]
	s_barrier
	s_add_i32 s56, 0, 0x14000
	v_add_u32_e32 v166, s56, v164
	s_add_i32 s53, s53, s36
	ds_read_b128 v[204:207], v166
	ds_read_b128 v[208:211], v166 offset:1024
	ds_read_b128 v[212:215], v166 offset:2048
	ds_read_b128 v[216:219], v166 offset:3072
	s_mov_b32 m0, s53
	s_add_u32 s98, s2, 0x80
	s_addc_u32 s99, s3, 0
	global_load_lds_dwordx4 v168, s[2:3]
	s_add_i32 m0, s53, 0x2000
	s_nop 0
	global_load_lds_dwordx4 v148, s[2:3]
	s_barrier
	s_waitcnt lgkmcnt(0)
	v_mfma_f32_16x16x32_bf16 v[132:135], v[204:207], v[154:157], v[132:135]
	v_mfma_f32_16x16x32_bf16 v[128:131], v[212:215], v[154:157], v[128:131]
	v_mfma_f32_16x16x32_bf16 v[116:119], v[204:207], v[180:183], v[116:119]
	v_mfma_f32_16x16x32_bf16 v[112:115], v[212:215], v[180:183], v[112:115]
	v_mfma_f32_16x16x32_bf16 v[100:103], v[204:207], v[188:191], v[100:103]
	v_mfma_f32_16x16x32_bf16 v[96:99], v[212:215], v[188:191], v[96:99]
	v_mfma_f32_16x16x32_bf16 v[84:87], v[204:207], v[196:199], v[84:87]
	v_mfma_f32_16x16x32_bf16 v[80:83], v[212:215], v[196:199], v[80:83]
	v_mfma_f32_16x16x32_bf16 v[132:135], v[208:211], v[158:161], v[132:135]
	v_mfma_f32_16x16x32_bf16 v[128:131], v[216:219], v[158:161], v[128:131]
	v_mfma_f32_16x16x32_bf16 v[116:119], v[208:211], v[184:187], v[116:119]
	v_mfma_f32_16x16x32_bf16 v[112:115], v[216:219], v[184:187], v[112:115]
	v_mfma_f32_16x16x32_bf16 v[100:103], v[208:211], v[192:195], v[100:103]
	v_mfma_f32_16x16x32_bf16 v[96:99], v[216:219], v[192:195], v[96:99]
	v_mfma_f32_16x16x32_bf16 v[84:87], v[208:211], v[200:203], v[84:87]
	v_mfma_f32_16x16x32_bf16 v[80:83], v[216:219], v[200:203], v[80:83]
	s_mov_b32 m0, s37
	s_add_u32 s100, s22, 0x80
	s_addc_u32 s101, s23, 0
	s_barrier
	ds_read_b128 v[154:157], v165 offset:16384
	ds_read_b128 v[158:161], v165 offset:17408
	ds_read_b128 v[180:183], v165 offset:18432
	ds_read_b128 v[184:187], v165 offset:19456
	ds_read_b128 v[188:191], v165 offset:20480
	ds_read_b128 v[192:195], v165 offset:21504
	ds_read_b128 v[196:199], v165 offset:22528
	global_load_lds_dwordx4 v144, s[22:23]
	s_mov_b32 m0, s38
	ds_read_b128 v[200:203], v165 offset:23552
	global_load_lds_dwordx4 v146, s[22:23]
	s_barrier
	s_waitcnt lgkmcnt(0)
	v_mfma_f32_16x16x32_bf16 v[76:79], v[24:27], v[154:157], v[76:79]
	v_mfma_f32_16x16x32_bf16 v[72:75], v[32:35], v[154:157], v[72:75]
	v_mfma_f32_16x16x32_bf16 v[60:63], v[24:27], v[180:183], v[60:63]
	v_mfma_f32_16x16x32_bf16 v[56:59], v[32:35], v[180:183], v[56:59]
	v_mfma_f32_16x16x32_bf16 v[44:47], v[24:27], v[188:191], v[44:47]
	v_mfma_f32_16x16x32_bf16 v[40:43], v[32:35], v[188:191], v[40:43]
	v_mfma_f32_16x16x32_bf16 v[12:15], v[24:27], v[196:199], v[12:15]
	v_mfma_f32_16x16x32_bf16 v[8:11], v[32:35], v[196:199], v[8:11]
	v_mfma_f32_16x16x32_bf16 v[76:79], v[28:31], v[158:161], v[76:79]
	v_mfma_f32_16x16x32_bf16 v[72:75], v[36:39], v[158:161], v[72:75]
	v_mfma_f32_16x16x32_bf16 v[60:63], v[28:31], v[184:187], v[60:63]
	v_mfma_f32_16x16x32_bf16 v[56:59], v[36:39], v[184:187], v[56:59]
	v_mfma_f32_16x16x32_bf16 v[44:47], v[28:31], v[192:195], v[44:47]
	v_mfma_f32_16x16x32_bf16 v[40:43], v[36:39], v[192:195], v[40:43]
	v_mfma_f32_16x16x32_bf16 v[12:15], v[28:31], v[200:203], v[12:15]
	v_mfma_f32_16x16x32_bf16 v[8:11], v[36:39], v[200:203], v[8:11]
	s_barrier
	s_add_i32 s53, s56, s36
	s_mov_b32 m0, s53
	s_add_u32 s54, s2, 0x40000
	s_addc_u32 s55, s3, 0
	global_load_lds_dwordx4 v168, s[54:55]
	s_add_i32 m0, s53, 0x2000
	s_nop 0
	global_load_lds_dwordx4 v148, s[54:55]
	s_waitcnt vmcnt(6)
	s_barrier
	v_mfma_f32_16x16x32_bf16 v[20:23], v[204:207], v[188:191], v[20:23]
	v_mfma_f32_16x16x32_bf16 v[16:19], v[212:215], v[188:191], v[16:19]
	v_mfma_f32_16x16x32_bf16 v[4:7], v[204:207], v[196:199], v[4:7]
	v_mfma_f32_16x16x32_bf16 v[0:3], v[212:215], v[196:199], v[0:3]
	v_mfma_f32_16x16x32_bf16 v[24:27], v[204:207], v[154:157], v[68:71]
	v_mfma_f32_16x16x32_bf16 v[28:31], v[212:215], v[154:157], v[64:67]
	v_mfma_f32_16x16x32_bf16 v[32:35], v[204:207], v[180:183], v[52:55]
	v_mfma_f32_16x16x32_bf16 v[36:39], v[212:215], v[180:183], v[48:51]
	v_mfma_f32_16x16x32_bf16 v[20:23], v[208:211], v[192:195], v[20:23]
	v_mfma_f32_16x16x32_bf16 v[16:19], v[216:219], v[192:195], v[16:19]
	v_mfma_f32_16x16x32_bf16 v[4:7], v[208:211], v[200:203], v[4:7]
	v_mfma_f32_16x16x32_bf16 v[0:3], v[216:219], v[200:203], v[0:3]
	v_mfma_f32_16x16x32_bf16 v[24:27], v[208:211], v[158:161], v[24:27]
	v_mfma_f32_16x16x32_bf16 v[28:31], v[216:219], v[158:161], v[28:31]
	v_mfma_f32_16x16x32_bf16 v[32:35], v[208:211], v[184:187], v[32:35]
	v_mfma_f32_16x16x32_bf16 v[36:39], v[216:219], v[184:187], v[36:39]
	s_add_i32 s53, 0, 0x18000
	v_add_u32_e32 v68, s53, v164
	s_barrier
	ds_read_b128 v[48:51], v68
	ds_read_b128 v[52:55], v68 offset:1024
	ds_read_b128 v[64:67], v68 offset:2048
	ds_read_b128 v[68:71], v68 offset:3072
	s_add_u32 s22, s22, 0x40000
	s_addc_u32 s23, s23, 0
	s_mov_b32 m0, s39
	ds_read_b128 v[154:157], v165 offset:32768
	ds_read_b128 v[158:161], v165 offset:33792
	ds_read_b128 v[180:183], v165 offset:34816
	ds_read_b128 v[184:187], v165 offset:35840
	ds_read_b128 v[188:191], v165 offset:36864
	ds_read_b128 v[192:195], v165 offset:37888
	ds_read_b128 v[196:199], v165 offset:38912
	global_load_lds_dwordx4 v144, s[22:23]
	s_mov_b32 m0, s40
	ds_read_b128 v[200:203], v165 offset:39936
	global_load_lds_dwordx4 v146, s[22:23]
	s_waitcnt lgkmcnt(8)
	s_barrier
	s_waitcnt lgkmcnt(0)
	v_mfma_f32_16x16x32_bf16 v[140:143], v[48:51], v[154:157], v[140:143]
	v_mfma_f32_16x16x32_bf16 v[136:139], v[64:67], v[154:157], v[136:139]
	v_mfma_f32_16x16x32_bf16 v[124:127], v[48:51], v[180:183], v[124:127]
	v_mfma_f32_16x16x32_bf16 v[120:123], v[64:67], v[180:183], v[120:123]
	v_mfma_f32_16x16x32_bf16 v[108:111], v[48:51], v[188:191], v[108:111]
	v_mfma_f32_16x16x32_bf16 v[104:107], v[64:67], v[188:191], v[104:107]
	v_mfma_f32_16x16x32_bf16 v[92:95], v[48:51], v[196:199], v[92:95]
	v_mfma_f32_16x16x32_bf16 v[88:91], v[64:67], v[196:199], v[88:91]
	v_mfma_f32_16x16x32_bf16 v[140:143], v[52:55], v[158:161], v[140:143]
	v_mfma_f32_16x16x32_bf16 v[136:139], v[68:71], v[158:161], v[136:139]
	v_mfma_f32_16x16x32_bf16 v[124:127], v[52:55], v[184:187], v[124:127]
	v_mfma_f32_16x16x32_bf16 v[120:123], v[68:71], v[184:187], v[120:123]
	v_mfma_f32_16x16x32_bf16 v[108:111], v[52:55], v[192:195], v[108:111]
	v_mfma_f32_16x16x32_bf16 v[104:107], v[68:71], v[192:195], v[104:107]
	v_mfma_f32_16x16x32_bf16 v[92:95], v[52:55], v[200:203], v[92:95]
	v_mfma_f32_16x16x32_bf16 v[88:91], v[68:71], v[200:203], v[88:91]
	s_barrier
	s_add_i32 s22, 0, 0x1c000
	s_add_i32 s23, s53, s36
	v_add_u32_e32 v216, s22, v164
	s_mov_b32 m0, s23
	ds_read_b128 v[204:207], v216
	ds_read_b128 v[208:211], v216 offset:1024
	ds_read_b128 v[212:215], v216 offset:2048
	global_load_lds_dwordx4 v168, s[98:99]
	s_add_i32 m0, s23, 0x2000
	ds_read_b128 v[216:219], v216 offset:3072
	global_load_lds_dwordx4 v148, s[98:99]
	s_barrier
	s_waitcnt lgkmcnt(0)
	v_mfma_f32_16x16x32_bf16 v[132:135], v[204:207], v[154:157], v[132:135]
	v_mfma_f32_16x16x32_bf16 v[128:131], v[212:215], v[154:157], v[128:131]
	v_mfma_f32_16x16x32_bf16 v[116:119], v[204:207], v[180:183], v[116:119]
	v_mfma_f32_16x16x32_bf16 v[112:115], v[212:215], v[180:183], v[112:115]
	v_mfma_f32_16x16x32_bf16 v[100:103], v[204:207], v[188:191], v[100:103]
	v_mfma_f32_16x16x32_bf16 v[96:99], v[212:215], v[188:191], v[96:99]
	v_mfma_f32_16x16x32_bf16 v[84:87], v[204:207], v[196:199], v[84:87]
	v_mfma_f32_16x16x32_bf16 v[80:83], v[212:215], v[196:199], v[80:83]
	v_mfma_f32_16x16x32_bf16 v[132:135], v[208:211], v[158:161], v[132:135]
	v_mfma_f32_16x16x32_bf16 v[128:131], v[216:219], v[158:161], v[128:131]
	v_mfma_f32_16x16x32_bf16 v[116:119], v[208:211], v[184:187], v[116:119]
	v_mfma_f32_16x16x32_bf16 v[112:115], v[216:219], v[184:187], v[112:115]
	v_mfma_f32_16x16x32_bf16 v[100:103], v[208:211], v[192:195], v[100:103]
	v_mfma_f32_16x16x32_bf16 v[96:99], v[216:219], v[192:195], v[96:99]
	v_mfma_f32_16x16x32_bf16 v[84:87], v[208:211], v[200:203], v[84:87]
	v_mfma_f32_16x16x32_bf16 v[80:83], v[216:219], v[200:203], v[80:83]
	s_mov_b32 m0, s45
	s_barrier
	ds_read_b128 v[154:157], v165 offset:49152
	ds_read_b128 v[158:161], v165 offset:50176
	ds_read_b128 v[180:183], v165 offset:51200
	ds_read_b128 v[184:187], v165 offset:52224
	ds_read_b128 v[188:191], v165 offset:53248
	ds_read_b128 v[192:195], v165 offset:54272
	ds_read_b128 v[196:199], v165 offset:55296
	global_load_lds_dwordx4 v144, s[100:101]
	s_mov_b32 m0, s46
	ds_read_b128 v[200:203], v165 offset:56320
	global_load_lds_dwordx4 v146, s[100:101]
	s_barrier
	s_waitcnt lgkmcnt(0)
	v_mfma_f32_16x16x32_bf16 v[76:79], v[48:51], v[154:157], v[76:79]
	v_mfma_f32_16x16x32_bf16 v[72:75], v[64:67], v[154:157], v[72:75]
	v_mfma_f32_16x16x32_bf16 v[60:63], v[48:51], v[180:183], v[60:63]
	v_mfma_f32_16x16x32_bf16 v[56:59], v[64:67], v[180:183], v[56:59]
	v_mfma_f32_16x16x32_bf16 v[44:47], v[48:51], v[188:191], v[44:47]
	v_mfma_f32_16x16x32_bf16 v[40:43], v[64:67], v[188:191], v[40:43]
	v_mfma_f32_16x16x32_bf16 v[12:15], v[48:51], v[196:199], v[12:15]
	v_mfma_f32_16x16x32_bf16 v[8:11], v[64:67], v[196:199], v[8:11]
	v_mfma_f32_16x16x32_bf16 v[76:79], v[52:55], v[158:161], v[76:79]
	v_mfma_f32_16x16x32_bf16 v[72:75], v[68:71], v[158:161], v[72:75]
	v_mfma_f32_16x16x32_bf16 v[60:63], v[52:55], v[184:187], v[60:63]
	v_mfma_f32_16x16x32_bf16 v[56:59], v[68:71], v[184:187], v[56:59]
	v_mfma_f32_16x16x32_bf16 v[44:47], v[52:55], v[192:195], v[44:47]
	v_mfma_f32_16x16x32_bf16 v[40:43], v[68:71], v[192:195], v[40:43]
	v_mfma_f32_16x16x32_bf16 v[12:15], v[52:55], v[200:203], v[12:15]
	v_mfma_f32_16x16x32_bf16 v[8:11], v[68:71], v[200:203], v[8:11]
	s_barrier
	s_add_i32 s22, s22, s36
	s_mov_b32 m0, s22
	s_add_u32 s2, s2, 0x40080
	s_addc_u32 s3, s3, 0
	global_load_lds_dwordx4 v168, s[2:3]
	s_add_i32 m0, s22, 0x2000
	s_nop 0
	global_load_lds_dwordx4 v148, s[2:3]
	s_waitcnt vmcnt(6)
	s_barrier
	v_mfma_f32_16x16x32_bf16 v[24:27], v[204:207], v[154:157], v[24:27]
	v_mfma_f32_16x16x32_bf16 v[68:71], v[208:211], v[158:161], v[24:27]
	v_mfma_f32_16x16x32_bf16 v[24:27], v[212:215], v[154:157], v[28:31]
	v_mfma_f32_16x16x32_bf16 v[64:67], v[216:219], v[158:161], v[24:27]
	v_mfma_f32_16x16x32_bf16 v[24:27], v[204:207], v[180:183], v[32:35]
	v_mfma_f32_16x16x32_bf16 v[52:55], v[208:211], v[184:187], v[24:27]
	v_mfma_f32_16x16x32_bf16 v[24:27], v[212:215], v[180:183], v[36:39]
	v_mfma_f32_16x16x32_bf16 v[20:23], v[204:207], v[188:191], v[20:23]
	v_mfma_f32_16x16x32_bf16 v[16:19], v[212:215], v[188:191], v[16:19]
	v_mfma_f32_16x16x32_bf16 v[4:7], v[204:207], v[196:199], v[4:7]
	v_mfma_f32_16x16x32_bf16 v[0:3], v[212:215], v[196:199], v[0:3]
	v_mfma_f32_16x16x32_bf16 v[48:51], v[216:219], v[184:187], v[24:27]
	v_mfma_f32_16x16x32_bf16 v[20:23], v[208:211], v[192:195], v[20:23]
	v_mfma_f32_16x16x32_bf16 v[16:19], v[216:219], v[192:195], v[16:19]
	v_mfma_f32_16x16x32_bf16 v[4:7], v[208:211], v[200:203], v[4:7]
	v_mfma_f32_16x16x32_bf16 v[0:3], v[216:219], v[200:203], v[0:3]
	s_add_i32 s52, s52, 2
	s_add_u32 s20, s20, 0x100
	s_addc_u32 s21, s21, 0
	s_add_u32 s50, s50, 0x100
	s_addc_u32 s51, s51, 0
	s_cmp_gt_u32 s52, 13
	s_barrier
	s_cbranch_scc0 .LBB0_123
	s_lshl_b32 s2, s6, 8
	s_add_i32 s3, s2, s43
	s_lshl_b32 s2, s8, 8
	s_cmp_gt_i32 s8, 3
	s_cselect_b64 s[20:21], -1, 0
	s_and_b64 s[22:23], s[20:21], exec
	s_mov_b32 s7, 0x8982000
	s_cselect_b32 s7, s7, 0x7182000
	s_add_u32 s22, s26, s7
	s_addc_u32 s23, s25, 0
	s_add_i32 s7, s6, -16
	v_mov_b32_e32 v160, v163
	v_mov_b32_e32 v24, v162
	s_lshr_b32 s7, s7, 3
	s_add_i32 s96, s7, 1
	v_add_u32_e32 v154, s3, v24
	s_lshl_b64 s[50:51], s[96:97], 11
	v_ashrrev_i32_e32 v155, 31, v154
	s_cmp_gt_i32 s6, 15
	v_lshl_add_u64 v[156:157], v[154:155], 2, s[10:11]
	s_cselect_b32 s7, s51, 0
	s_cselect_b32 s6, s50, 0
	global_load_dword v166, v[156:157], off
	global_load_dword v191, v[156:157], off offset:64
	global_load_dword v192, v[156:157], off offset:128
	global_load_dword v193, v[156:157], off offset:192
	global_load_dword v194, v[156:157], off offset:512
	global_load_dword v195, v[156:157], off offset:576
	global_load_dword v196, v[156:157], off offset:640
	global_load_dword v197, v[156:157], off offset:704
	s_lshl_b64 s[6:7], s[6:7], 2
	s_add_u32 s9, s41, s6
	s_addc_u32 s13, s42, s7
	s_ashr_i32 s3, s2, 31
	s_lshl_b64 s[6:7], s[2:3], 2
	s_add_u32 s3, s9, s6
	s_addc_u32 s7, s13, s7
	v_lshlrev_b32_e32 v158, 3, v160
	s_add_u32 s6, s3, s49
	s_addc_u32 s7, s7, 0
	v_ashrrev_i32_e32 v159, 31, v158
	v_lshl_add_u64 v[24:25], v[158:159], 2, s[6:7]
	global_load_dwordx4 v[36:39], v[24:25], off
	global_load_dwordx4 v[32:35], v[24:25], off offset:16
	global_load_dwordx4 v[28:31], v[24:25], off offset:512
	s_nop 0
	global_load_dwordx4 v[24:27], v[24:25], off offset:528
	s_and_b32 s2, s2, 0x300
	s_or_b32 s2, s2, s44
	v_add_u32_e32 v158, s2, v158
	v_cmp_eq_u32_e64 s[6:7], 0, v160
	v_lshlrev_b64 v[160:161], 11, v[154:155]
	s_cmp_lt_i32 s8, 4
	s_waitcnt vmcnt(0)
	v_ashrrev_i32_e32 v159, 31, v158
	v_lshl_add_u64 v[158:159], v[158:159], 1, s[22:23]
	v_lshl_add_u64 v[160:161], v[158:159], 0, v[160:161]
	v_lshl_add_u64 v[156:157], v[154:155], 2, s[0:1]
	s_and_b64 s[6:7], s[6:7], s[20:21]
	s_mov_b64 s[2:3], 0x8000
	s_mov_b64 s[50:51], 0x28000
	v_mov_b32_e32 v180, 0xc0135761
	v_mov_b32_e32 v181, 0xc0135761
	v_mov_b32_e32 v182, 0xbdd2d3e7
	v_mov_b32_e32 v183, 0xbdd2d3e7
	v_fmamk_f32 v166, v166, 0x3a800000, v225
	v_fmamk_f32 v190, v191, 0x3a800000, v225
	v_fmamk_f32 v192, v192, 0x3a800000, v225
	v_fmamk_f32 v188, v193, 0x3a800000, v225
	v_fmamk_f32 v194, v194, 0x3a800000, v225
	v_fmamk_f32 v186, v195, 0x3a800000, v225
	v_fmamk_f32 v196, v196, 0x3a800000, v225
	v_fmamk_f32 v184, v197, 0x3a800000, v225
	v_rsq_f32_e32 v166, v166
	v_rsq_f32_e32 v190, v190
	v_rsq_f32_e32 v192, v192
	v_rsq_f32_e32 v188, v188
	v_rsq_f32_e32 v194, v194
	v_rsq_f32_e32 v186, v186
	v_rsq_f32_e32 v196, v196
	v_rsq_f32_e32 v184, v184
	v_pk_fma_f32 v[140:141], v[140:141], v[166:167], v[36:37] op_sel_hi:[1,0,1]
	v_pk_fma_f32 v[142:143], v[142:143], v[166:167], v[38:39] op_sel_hi:[1,0,1]
	v_pk_fma_f32 v[136:137], v[136:137], v[166:167], v[32:33] op_sel_hi:[1,0,1]
	v_pk_fma_f32 v[138:139], v[138:139], v[166:167], v[34:35] op_sel_hi:[1,0,1]
	v_pk_fma_f32 v[132:133], v[132:133], v[166:167], v[28:29] op_sel_hi:[1,0,1]
	v_pk_fma_f32 v[134:135], v[134:135], v[166:167], v[30:31] op_sel_hi:[1,0,1]
	v_pk_fma_f32 v[128:129], v[128:129], v[166:167], v[24:25] op_sel_hi:[1,0,1]
	v_pk_fma_f32 v[130:131], v[130:131], v[166:167], v[26:27] op_sel_hi:[1,0,1]
	v_pk_fma_f32 v[124:125], v[124:125], v[190:191], v[36:37] op_sel_hi:[1,0,1]
	v_pk_fma_f32 v[126:127], v[126:127], v[190:191], v[38:39] op_sel_hi:[1,0,1]
	v_pk_fma_f32 v[120:121], v[120:121], v[190:191], v[32:33] op_sel_hi:[1,0,1]
	v_pk_fma_f32 v[122:123], v[122:123], v[190:191], v[34:35] op_sel_hi:[1,0,1]
	v_pk_fma_f32 v[116:117], v[116:117], v[190:191], v[28:29] op_sel_hi:[1,0,1]
	v_pk_fma_f32 v[118:119], v[118:119], v[190:191], v[30:31] op_sel_hi:[1,0,1]
	v_pk_fma_f32 v[112:113], v[112:113], v[190:191], v[24:25] op_sel_hi:[1,0,1]
	v_pk_fma_f32 v[114:115], v[114:115], v[190:191], v[26:27] op_sel_hi:[1,0,1]
	v_pk_fma_f32 v[108:109], v[108:109], v[192:193], v[36:37] op_sel_hi:[1,0,1]
	v_pk_fma_f32 v[110:111], v[110:111], v[192:193], v[38:39] op_sel_hi:[1,0,1]
	v_pk_fma_f32 v[104:105], v[104:105], v[192:193], v[32:33] op_sel_hi:[1,0,1]
	v_pk_fma_f32 v[106:107], v[106:107], v[192:193], v[34:35] op_sel_hi:[1,0,1]
	v_pk_fma_f32 v[100:101], v[100:101], v[192:193], v[28:29] op_sel_hi:[1,0,1]
	v_pk_fma_f32 v[102:103], v[102:103], v[192:193], v[30:31] op_sel_hi:[1,0,1]
	v_pk_fma_f32 v[96:97], v[96:97], v[192:193], v[24:25] op_sel_hi:[1,0,1]
	v_pk_fma_f32 v[98:99], v[98:99], v[192:193], v[26:27] op_sel_hi:[1,0,1]
	v_pk_fma_f32 v[92:93], v[92:93], v[188:189], v[36:37] op_sel_hi:[1,0,1]
	v_pk_fma_f32 v[94:95], v[94:95], v[188:189], v[38:39] op_sel_hi:[1,0,1]
	v_pk_fma_f32 v[88:89], v[88:89], v[188:189], v[32:33] op_sel_hi:[1,0,1]
	v_pk_fma_f32 v[90:91], v[90:91], v[188:189], v[34:35] op_sel_hi:[1,0,1]
	v_pk_fma_f32 v[84:85], v[84:85], v[188:189], v[28:29] op_sel_hi:[1,0,1]
	v_pk_fma_f32 v[86:87], v[86:87], v[188:189], v[30:31] op_sel_hi:[1,0,1]
	v_pk_fma_f32 v[80:81], v[80:81], v[188:189], v[24:25] op_sel_hi:[1,0,1]
	v_pk_fma_f32 v[82:83], v[82:83], v[188:189], v[26:27] op_sel_hi:[1,0,1]
	v_pk_fma_f32 v[76:77], v[76:77], v[194:195], v[36:37] op_sel_hi:[1,0,1]
	v_pk_fma_f32 v[78:79], v[78:79], v[194:195], v[38:39] op_sel_hi:[1,0,1]
	v_pk_fma_f32 v[72:73], v[72:73], v[194:195], v[32:33] op_sel_hi:[1,0,1]
	v_pk_fma_f32 v[74:75], v[74:75], v[194:195], v[34:35] op_sel_hi:[1,0,1]
	v_pk_fma_f32 v[68:69], v[68:69], v[194:195], v[28:29] op_sel_hi:[1,0,1]
	v_pk_fma_f32 v[70:71], v[70:71], v[194:195], v[30:31] op_sel_hi:[1,0,1]
	v_pk_fma_f32 v[64:65], v[64:65], v[194:195], v[24:25] op_sel_hi:[1,0,1]
	v_pk_fma_f32 v[66:67], v[66:67], v[194:195], v[26:27] op_sel_hi:[1,0,1]
	v_pk_fma_f32 v[60:61], v[60:61], v[186:187], v[36:37] op_sel_hi:[1,0,1]
	v_pk_fma_f32 v[62:63], v[62:63], v[186:187], v[38:39] op_sel_hi:[1,0,1]
	v_pk_fma_f32 v[56:57], v[56:57], v[186:187], v[32:33] op_sel_hi:[1,0,1]
	v_pk_fma_f32 v[58:59], v[58:59], v[186:187], v[34:35] op_sel_hi:[1,0,1]
	v_pk_fma_f32 v[52:53], v[52:53], v[186:187], v[28:29] op_sel_hi:[1,0,1]
	v_pk_fma_f32 v[54:55], v[54:55], v[186:187], v[30:31] op_sel_hi:[1,0,1]
	v_pk_fma_f32 v[48:49], v[48:49], v[186:187], v[24:25] op_sel_hi:[1,0,1]
	v_pk_fma_f32 v[50:51], v[50:51], v[186:187], v[26:27] op_sel_hi:[1,0,1]
	v_pk_fma_f32 v[44:45], v[44:45], v[196:197], v[36:37] op_sel_hi:[1,0,1]
	v_pk_fma_f32 v[46:47], v[46:47], v[196:197], v[38:39] op_sel_hi:[1,0,1]
	v_pk_fma_f32 v[40:41], v[40:41], v[196:197], v[32:33] op_sel_hi:[1,0,1]
	v_pk_fma_f32 v[42:43], v[42:43], v[196:197], v[34:35] op_sel_hi:[1,0,1]
	v_pk_fma_f32 v[20:21], v[20:21], v[196:197], v[28:29] op_sel_hi:[1,0,1]
	v_pk_fma_f32 v[22:23], v[22:23], v[196:197], v[30:31] op_sel_hi:[1,0,1]
	v_pk_fma_f32 v[16:17], v[16:17], v[196:197], v[24:25] op_sel_hi:[1,0,1]
	v_pk_fma_f32 v[18:19], v[18:19], v[196:197], v[26:27] op_sel_hi:[1,0,1]
	v_pk_fma_f32 v[12:13], v[12:13], v[184:185], v[36:37] op_sel_hi:[1,0,1]
	v_pk_fma_f32 v[14:15], v[14:15], v[184:185], v[38:39] op_sel_hi:[1,0,1]
	v_pk_fma_f32 v[8:9], v[8:9], v[184:185], v[32:33] op_sel_hi:[1,0,1]
	v_pk_fma_f32 v[10:11], v[10:11], v[184:185], v[34:35] op_sel_hi:[1,0,1]
	v_pk_fma_f32 v[4:5], v[4:5], v[184:185], v[28:29] op_sel_hi:[1,0,1]
	v_pk_fma_f32 v[6:7], v[6:7], v[184:185], v[30:31] op_sel_hi:[1,0,1]
	v_pk_fma_f32 v[0:1], v[0:1], v[184:185], v[24:25] op_sel_hi:[1,0,1]
	v_pk_fma_f32 v[2:3], v[2:3], v[184:185], v[26:27] op_sel_hi:[1,0,1]
	v_pk_mul_f32 v[24:25], v[140:141], v[140:141]
	v_pk_mul_f32 v[26:27], v[142:143], v[142:143]
	v_pk_mul_f32 v[28:29], v[136:137], v[136:137]
	v_pk_mul_f32 v[30:31], v[138:139], v[138:139]
	v_pk_mul_f32 v[32:33], v[132:133], v[132:133]
	v_pk_mul_f32 v[34:35], v[134:135], v[134:135]
	v_pk_mul_f32 v[36:37], v[128:129], v[128:129]
	v_pk_mul_f32 v[38:39], v[130:131], v[130:131]
	v_pk_fma_f32 v[24:25], v[24:25], v[182:183], v[180:181]
	v_pk_fma_f32 v[26:27], v[26:27], v[182:183], v[180:181]
	v_pk_fma_f32 v[28:29], v[28:29], v[182:183], v[180:181]
	v_pk_fma_f32 v[30:31], v[30:31], v[182:183], v[180:181]
	v_pk_fma_f32 v[32:33], v[32:33], v[182:183], v[180:181]
	v_pk_fma_f32 v[34:35], v[34:35], v[182:183], v[180:181]
	v_pk_fma_f32 v[36:37], v[36:37], v[182:183], v[180:181]
	v_pk_fma_f32 v[38:39], v[38:39], v[182:183], v[180:181]
	v_pk_mul_f32 v[24:25], v[24:25], v[140:141]
	v_pk_mul_f32 v[26:27], v[26:27], v[142:143]
	v_pk_mul_f32 v[28:29], v[28:29], v[136:137]
	v_pk_mul_f32 v[30:31], v[30:31], v[138:139]
	v_pk_mul_f32 v[32:33], v[32:33], v[132:133]
	v_pk_mul_f32 v[34:35], v[34:35], v[134:135]
	v_pk_mul_f32 v[36:37], v[36:37], v[128:129]
	v_pk_mul_f32 v[38:39], v[38:39], v[130:131]
	v_exp_f32_e32 v24, v24
	v_exp_f32_e32 v25, v25
	v_exp_f32_e32 v26, v26
	v_exp_f32_e32 v27, v27
	v_exp_f32_e32 v28, v28
	v_exp_f32_e32 v29, v29
	v_exp_f32_e32 v30, v30
	v_exp_f32_e32 v31, v31
	v_exp_f32_e32 v32, v32
	v_exp_f32_e32 v33, v33
	v_exp_f32_e32 v34, v34
	v_exp_f32_e32 v35, v35
	v_exp_f32_e32 v36, v36
	v_exp_f32_e32 v37, v37
	v_exp_f32_e32 v38, v38
	v_exp_f32_e32 v39, v39
	v_pk_add_f32 v[24:25], v[24:25], 1.0 op_sel_hi:[1,0]
	v_pk_add_f32 v[26:27], v[26:27], 1.0 op_sel_hi:[1,0]
	v_pk_add_f32 v[28:29], v[28:29], 1.0 op_sel_hi:[1,0]
	v_pk_add_f32 v[30:31], v[30:31], 1.0 op_sel_hi:[1,0]
	v_pk_add_f32 v[32:33], v[32:33], 1.0 op_sel_hi:[1,0]
	v_pk_add_f32 v[34:35], v[34:35], 1.0 op_sel_hi:[1,0]
	v_pk_add_f32 v[36:37], v[36:37], 1.0 op_sel_hi:[1,0]
	v_pk_add_f32 v[38:39], v[38:39], 1.0 op_sel_hi:[1,0]
	v_rcp_f32_e32 v24, v24
	v_rcp_f32_e32 v25, v25
	v_rcp_f32_e32 v26, v26
	v_rcp_f32_e32 v27, v27
	v_rcp_f32_e32 v28, v28
	v_rcp_f32_e32 v29, v29
	v_rcp_f32_e32 v30, v30
	v_rcp_f32_e32 v31, v31
	v_rcp_f32_e32 v32, v32
	v_rcp_f32_e32 v33, v33
	v_rcp_f32_e32 v34, v34
	v_rcp_f32_e32 v35, v35
	v_rcp_f32_e32 v36, v36
	v_rcp_f32_e32 v37, v37
	v_rcp_f32_e32 v38, v38
	v_rcp_f32_e32 v39, v39
	v_pk_mul_f32 v[140:141], v[140:141], v[24:25]
	v_pk_mul_f32 v[142:143], v[142:143], v[26:27]
	v_pk_mul_f32 v[136:137], v[136:137], v[28:29]
	v_pk_mul_f32 v[138:139], v[138:139], v[30:31]
	v_pk_mul_f32 v[132:133], v[132:133], v[32:33]
	v_pk_mul_f32 v[134:135], v[134:135], v[34:35]
	v_pk_mul_f32 v[128:129], v[128:129], v[36:37]
	v_pk_mul_f32 v[130:131], v[130:131], v[38:39]
	v_cvt_pk_bf16_f32 v24, v140, v141
	v_cvt_pk_bf16_f32 v25, v142, v143
	v_cvt_pk_bf16_f32 v26, v136, v137
	v_cvt_pk_bf16_f32 v27, v138, v139
	v_cvt_pk_bf16_f32 v28, v132, v133
	v_cvt_pk_bf16_f32 v29, v134, v135
	v_cvt_pk_bf16_f32 v30, v128, v129
	v_cvt_pk_bf16_f32 v31, v130, v131
	global_store_dwordx4 v[160:161], v[24:27], off
	global_store_dwordx4 v[160:161], v[28:31], off offset:256
	s_and_b64 vcc, exec, s[20:21]
	s_cbranch_vccz .Lio_skip_0
	v_pk_mul_f32 v[32:33], v[140:141], v[140:141]
	v_pk_fma_f32 v[32:33], v[142:143], v[142:143], v[32:33]
	v_pk_fma_f32 v[32:33], v[136:137], v[136:137], v[32:33]
	v_pk_fma_f32 v[32:33], v[138:139], v[138:139], v[32:33]
	v_pk_fma_f32 v[32:33], v[132:133], v[132:133], v[32:33]
	v_pk_fma_f32 v[32:33], v[134:135], v[134:135], v[32:33]
	v_pk_fma_f32 v[32:33], v[128:129], v[128:129], v[32:33]
	v_pk_fma_f32 v[32:33], v[130:131], v[130:131], v[32:33]
	s_nop 0
	v_add_f32_e32 v32, v32, v33
	v_mov_b32_e32 v33, v32
	s_nop 1
	v_permlane16_swap_b32_e32 v32, v33
	v_add_f32_e32 v32, v32, v33
	v_mov_b32_e32 v33, v32
	s_nop 1
	v_permlane32_swap_b32_e32 v32, v33
	s_and_saveexec_b64 vcc, s[6:7]
	v_add_f32_e32 v32, v32, v33
	global_atomic_add_f32 v[156:157], v32, off
	s_mov_b64 exec, vcc

.Lie_done_b:
.LBB0_354:
	s_ashr_i32 s31, s30, 31
	v_cmp_lt_i64_e32 vcc, s[8:9], v[170:171]
	s_lshl_b64 s[8:9], s[30:31], 19
	s_add_u32 s34, s52, s8
	s_addc_u32 s35, s53, s9
	s_and_b64 s[8:9], vcc, exec
	s_cselect_b32 s1, s35, s7
	s_cselect_b32 s31, s34, s6
	s_ashr_i32 s29, s28, 31
	s_lshl_b64 s[8:9], s[28:29], 19
	s_add_u32 s36, s43, s8
	s_addc_u32 s37, s42, s9
	s_and_b64 s[8:9], vcc, exec
	s_cselect_b32 s29, s37, s3
	s_cselect_b32 s38, s36, s2
	s_add_u32 s6, s6, 0x40080
	s_addc_u32 s7, s7, 0
	s_add_u32 s39, s2, 0x100
	s_addc_u32 s40, s3, 0
	s_mov_b32 s41, -2
	s_add_u32 s2, s6, 0xfffc0080
	s_addc_u32 s3, s7, -1
	s_add_i32 s64, 0, 0x10000
	v_add_u32_e32 v140, s64, v208
	ds_read_b128 v[128:131], v140
	ds_read_b128 v[132:135], v140 offset:1024
	ds_read_b128 v[136:139], v140 offset:2048
	ds_read_b128 v[140:143], v140 offset:3072
	s_cmp_eq_u32 s41, 12
	s_cselect_b32 s9, s1, s3
	s_cselect_b32 s8, s31, s2
	s_cselect_b32 s3, s29, s40
	s_cselect_b32 s2, s38, s39
	s_add_i32 m0, s21, 0xc000
	ds_read_b128 v[144:147], v209
	ds_read_b128 v[148:151], v209 offset:1024
	ds_read_b128 v[152:155], v209 offset:2048
	ds_read_b128 v[156:159], v209 offset:3072
	ds_read_b128 v[180:183], v209 offset:4096
	ds_read_b128 v[184:187], v209 offset:5120
	ds_read_b128 v[188:191], v209 offset:6144
	global_load_lds_dwordx4 v164, s[6:7]
	s_add_i32 m0, s21, 0xe000
	ds_read_b128 v[192:195], v209 offset:7168
	global_load_lds_dwordx4 v166, s[6:7]
	s_waitcnt lgkmcnt(8)
	s_barrier
	s_waitcnt lgkmcnt(0)
	v_mfma_f32_16x16x32_bf16 v[124:127], v[128:131], v[144:147], 0
	v_mfma_f32_16x16x32_bf16 v[120:123], v[136:139], v[144:147], 0
	v_mfma_f32_16x16x32_bf16 v[116:119], v[128:131], v[152:155], 0
	v_mfma_f32_16x16x32_bf16 v[112:115], v[136:139], v[152:155], 0
	v_mfma_f32_16x16x32_bf16 v[100:103], v[128:131], v[180:183], 0
	v_mfma_f32_16x16x32_bf16 v[96:99], v[136:139], v[180:183], 0
	v_mfma_f32_16x16x32_bf16 v[84:87], v[128:131], v[188:191], 0
	v_mfma_f32_16x16x32_bf16 v[80:83], v[136:139], v[188:191], 0
	v_mfma_f32_16x16x32_bf16 v[124:127], v[132:135], v[148:151], v[124:127]
	v_mfma_f32_16x16x32_bf16 v[120:123], v[140:143], v[148:151], v[120:123]
	v_mfma_f32_16x16x32_bf16 v[116:119], v[132:135], v[156:159], v[116:119]
	v_mfma_f32_16x16x32_bf16 v[112:115], v[140:143], v[156:159], v[112:115]
	v_mfma_f32_16x16x32_bf16 v[100:103], v[132:135], v[184:187], v[100:103]
	v_mfma_f32_16x16x32_bf16 v[96:99], v[140:143], v[184:187], v[96:99]
	v_mfma_f32_16x16x32_bf16 v[84:87], v[132:135], v[192:195], v[84:87]
	v_mfma_f32_16x16x32_bf16 v[80:83], v[140:143], v[192:195], v[80:83]
	s_barrier
	s_add_i32 s66, 0, 0x14000
	s_add_i32 s64, s64, s54
	v_add_u32_e32 v168, s66, v208
	s_add_u32 s98, s2, 0x80
	s_addc_u32 s99, s3, 0
	s_mov_b32 m0, s64
	ds_read_b128 v[196:199], v168
	ds_read_b128 v[200:203], v168 offset:1024
	ds_read_b128 v[210:213], v168 offset:2048
	global_load_lds_dwordx4 v160, s[2:3]
	s_add_i32 m0, s64, 0x2000
	ds_read_b128 v[214:217], v168 offset:3072
	global_load_lds_dwordx4 v162, s[2:3]
	s_barrier
	s_waitcnt lgkmcnt(0)
	v_mfma_f32_16x16x32_bf16 v[108:111], v[196:199], v[144:147], 0
	v_mfma_f32_16x16x32_bf16 v[104:107], v[210:213], v[144:147], 0
	v_mfma_f32_16x16x32_bf16 v[92:95], v[196:199], v[152:155], 0
	v_mfma_f32_16x16x32_bf16 v[88:91], v[210:213], v[152:155], 0
	v_mfma_f32_16x16x32_bf16 v[76:79], v[196:199], v[180:183], 0
	v_mfma_f32_16x16x32_bf16 v[72:75], v[210:213], v[180:183], 0
	v_mfma_f32_16x16x32_bf16 v[68:71], v[196:199], v[188:191], 0
	v_mfma_f32_16x16x32_bf16 v[64:67], v[210:213], v[188:191], 0
	v_mfma_f32_16x16x32_bf16 v[108:111], v[200:203], v[148:151], v[108:111]
	v_mfma_f32_16x16x32_bf16 v[104:107], v[214:217], v[148:151], v[104:107]
	v_mfma_f32_16x16x32_bf16 v[92:95], v[200:203], v[156:159], v[92:95]
	v_mfma_f32_16x16x32_bf16 v[88:91], v[214:217], v[156:159], v[88:91]
	v_mfma_f32_16x16x32_bf16 v[76:79], v[200:203], v[184:187], v[76:79]
	v_mfma_f32_16x16x32_bf16 v[72:75], v[214:217], v[184:187], v[72:75]
	v_mfma_f32_16x16x32_bf16 v[68:71], v[200:203], v[192:195], v[68:71]
	v_mfma_f32_16x16x32_bf16 v[64:67], v[214:217], v[192:195], v[64:67]
	s_mov_b32 m0, s21
	s_add_u32 s100, s8, 0x80
	s_addc_u32 s101, s9, 0
	s_barrier
	ds_read_b128 v[144:147], v209 offset:16384
	ds_read_b128 v[148:151], v209 offset:17408
	ds_read_b128 v[152:155], v209 offset:18432
	ds_read_b128 v[156:159], v209 offset:19456
	ds_read_b128 v[180:183], v209 offset:20480
	ds_read_b128 v[184:187], v209 offset:21504
	ds_read_b128 v[188:191], v209 offset:22528
	global_load_lds_dwordx4 v160, s[8:9]
	s_mov_b32 m0, s55
	ds_read_b128 v[192:195], v209 offset:23552
	global_load_lds_dwordx4 v162, s[8:9]
	s_barrier
	s_waitcnt lgkmcnt(0)
	v_mfma_f32_16x16x32_bf16 v[60:63], v[128:131], v[144:147], 0
	v_mfma_f32_16x16x32_bf16 v[56:59], v[136:139], v[144:147], 0
	v_mfma_f32_16x16x32_bf16 v[52:55], v[128:131], v[152:155], 0
	v_mfma_f32_16x16x32_bf16 v[48:51], v[136:139], v[152:155], 0
	v_mfma_f32_16x16x32_bf16 v[36:39], v[128:131], v[180:183], 0
	v_mfma_f32_16x16x32_bf16 v[32:35], v[136:139], v[180:183], 0
	v_mfma_f32_16x16x32_bf16 v[20:23], v[128:131], v[188:191], 0
	v_mfma_f32_16x16x32_bf16 v[16:19], v[136:139], v[188:191], 0
	v_mfma_f32_16x16x32_bf16 v[60:63], v[132:135], v[148:151], v[60:63]
	v_mfma_f32_16x16x32_bf16 v[56:59], v[140:143], v[148:151], v[56:59]
	v_mfma_f32_16x16x32_bf16 v[52:55], v[132:135], v[156:159], v[52:55]
	v_mfma_f32_16x16x32_bf16 v[48:51], v[140:143], v[156:159], v[48:51]
	v_mfma_f32_16x16x32_bf16 v[36:39], v[132:135], v[184:187], v[36:39]
	v_mfma_f32_16x16x32_bf16 v[32:35], v[140:143], v[184:187], v[32:35]
	v_mfma_f32_16x16x32_bf16 v[20:23], v[132:135], v[192:195], v[20:23]
	v_mfma_f32_16x16x32_bf16 v[16:19], v[140:143], v[192:195], v[16:19]
	s_barrier
	s_add_i32 s66, s66, s54
	s_mov_b32 m0, s66
	s_add_u32 s64, s2, 0x40000
	s_addc_u32 s65, s3, 0
	global_load_lds_dwordx4 v160, s[64:65]
	s_add_i32 m0, s66, 0x2000
	s_nop 0
	global_load_lds_dwordx4 v162, s[64:65]
	s_waitcnt vmcnt(6)
	s_barrier
	v_mfma_f32_16x16x32_bf16 v[44:47], v[196:199], v[144:147], 0
	v_mfma_f32_16x16x32_bf16 v[40:43], v[210:213], v[144:147], 0
	v_mfma_f32_16x16x32_bf16 v[28:31], v[196:199], v[152:155], 0
	v_mfma_f32_16x16x32_bf16 v[24:27], v[210:213], v[152:155], 0
	v_mfma_f32_16x16x32_bf16 v[12:15], v[196:199], v[180:183], 0
	v_mfma_f32_16x16x32_bf16 v[8:11], v[210:213], v[180:183], 0
	v_mfma_f32_16x16x32_bf16 v[4:7], v[196:199], v[188:191], 0
	v_mfma_f32_16x16x32_bf16 v[0:3], v[210:213], v[188:191], 0
	v_mfma_f32_16x16x32_bf16 v[44:47], v[200:203], v[148:151], v[44:47]
	v_mfma_f32_16x16x32_bf16 v[40:43], v[214:217], v[148:151], v[40:43]
	v_mfma_f32_16x16x32_bf16 v[28:31], v[200:203], v[156:159], v[28:31]
	v_mfma_f32_16x16x32_bf16 v[24:27], v[214:217], v[156:159], v[24:27]
	v_mfma_f32_16x16x32_bf16 v[12:15], v[200:203], v[184:187], v[12:15]
	v_mfma_f32_16x16x32_bf16 v[8:11], v[214:217], v[184:187], v[8:11]
	v_mfma_f32_16x16x32_bf16 v[4:7], v[200:203], v[192:195], v[4:7]
	v_mfma_f32_16x16x32_bf16 v[0:3], v[214:217], v[192:195], v[0:3]
	s_add_i32 s64, 0, 0x18000
	v_add_u32_e32 v140, s64, v208
	s_barrier
	ds_read_b128 v[128:131], v140
	ds_read_b128 v[132:135], v140 offset:1024
	ds_read_b128 v[136:139], v140 offset:2048
	ds_read_b128 v[140:143], v140 offset:3072
	s_add_u32 s8, s8, 0x40000
	s_addc_u32 s9, s9, 0
	s_mov_b32 m0, s56
	ds_read_b128 v[144:147], v209 offset:32768
	ds_read_b128 v[148:151], v209 offset:33792
	ds_read_b128 v[152:155], v209 offset:34816
	ds_read_b128 v[156:159], v209 offset:35840
	ds_read_b128 v[180:183], v209 offset:36864
	ds_read_b128 v[184:187], v209 offset:37888
	ds_read_b128 v[188:191], v209 offset:38912
	global_load_lds_dwordx4 v160, s[8:9]
	s_mov_b32 m0, s57
	ds_read_b128 v[192:195], v209 offset:39936
	global_load_lds_dwordx4 v162, s[8:9]
	s_waitcnt lgkmcnt(8)
	s_barrier
	s_waitcnt lgkmcnt(0)
	v_mfma_f32_16x16x32_bf16 v[124:127], v[128:131], v[144:147], v[124:127]
	v_mfma_f32_16x16x32_bf16 v[120:123], v[136:139], v[144:147], v[120:123]
	v_mfma_f32_16x16x32_bf16 v[116:119], v[128:131], v[152:155], v[116:119]
	v_mfma_f32_16x16x32_bf16 v[112:115], v[136:139], v[152:155], v[112:115]
	v_mfma_f32_16x16x32_bf16 v[100:103], v[128:131], v[180:183], v[100:103]
	v_mfma_f32_16x16x32_bf16 v[96:99], v[136:139], v[180:183], v[96:99]
	v_mfma_f32_16x16x32_bf16 v[84:87], v[128:131], v[188:191], v[84:87]
	v_mfma_f32_16x16x32_bf16 v[80:83], v[136:139], v[188:191], v[80:83]
	v_mfma_f32_16x16x32_bf16 v[124:127], v[132:135], v[148:151], v[124:127]
	v_mfma_f32_16x16x32_bf16 v[120:123], v[140:143], v[148:151], v[120:123]
	v_mfma_f32_16x16x32_bf16 v[116:119], v[132:135], v[156:159], v[116:119]
	v_mfma_f32_16x16x32_bf16 v[112:115], v[140:143], v[156:159], v[112:115]
	v_mfma_f32_16x16x32_bf16 v[100:103], v[132:135], v[184:187], v[100:103]
	v_mfma_f32_16x16x32_bf16 v[96:99], v[140:143], v[184:187], v[96:99]
	v_mfma_f32_16x16x32_bf16 v[84:87], v[132:135], v[192:195], v[84:87]
	v_mfma_f32_16x16x32_bf16 v[80:83], v[140:143], v[192:195], v[80:83]
	s_barrier
	s_add_i32 s8, 0, 0x1c000
	s_add_i32 s9, s64, s54
	v_add_u32_e32 v168, s8, v208
	s_mov_b32 m0, s9
	ds_read_b128 v[196:199], v168
	ds_read_b128 v[200:203], v168 offset:1024
	ds_read_b128 v[210:213], v168 offset:2048
	global_load_lds_dwordx4 v160, s[98:99]
	s_add_i32 m0, s9, 0x2000
	ds_read_b128 v[214:217], v168 offset:3072
	global_load_lds_dwordx4 v162, s[98:99]
	s_barrier
	s_waitcnt lgkmcnt(0)
	v_mfma_f32_16x16x32_bf16 v[108:111], v[196:199], v[144:147], v[108:111]
	v_mfma_f32_16x16x32_bf16 v[104:107], v[210:213], v[144:147], v[104:107]
	v_mfma_f32_16x16x32_bf16 v[92:95], v[196:199], v[152:155], v[92:95]
	v_mfma_f32_16x16x32_bf16 v[88:91], v[210:213], v[152:155], v[88:91]
	v_mfma_f32_16x16x32_bf16 v[76:79], v[196:199], v[180:183], v[76:79]
	v_mfma_f32_16x16x32_bf16 v[72:75], v[210:213], v[180:183], v[72:75]
	v_mfma_f32_16x16x32_bf16 v[68:71], v[196:199], v[188:191], v[68:71]
	v_mfma_f32_16x16x32_bf16 v[64:67], v[210:213], v[188:191], v[64:67]
	v_mfma_f32_16x16x32_bf16 v[108:111], v[200:203], v[148:151], v[108:111]
	v_mfma_f32_16x16x32_bf16 v[104:107], v[214:217], v[148:151], v[104:107]
	v_mfma_f32_16x16x32_bf16 v[92:95], v[200:203], v[156:159], v[92:95]
	v_mfma_f32_16x16x32_bf16 v[88:91], v[214:217], v[156:159], v[88:91]
	v_mfma_f32_16x16x32_bf16 v[76:79], v[200:203], v[184:187], v[76:79]
	v_mfma_f32_16x16x32_bf16 v[72:75], v[214:217], v[184:187], v[72:75]
	v_mfma_f32_16x16x32_bf16 v[68:71], v[200:203], v[192:195], v[68:71]
	v_mfma_f32_16x16x32_bf16 v[64:67], v[214:217], v[192:195], v[64:67]
	s_mov_b32 m0, s60
	s_barrier
	ds_read_b128 v[144:147], v209 offset:49152
	ds_read_b128 v[148:151], v209 offset:50176
	ds_read_b128 v[152:155], v209 offset:51200
	ds_read_b128 v[156:159], v209 offset:52224
	ds_read_b128 v[180:183], v209 offset:53248
	ds_read_b128 v[184:187], v209 offset:54272
	ds_read_b128 v[188:191], v209 offset:55296
	global_load_lds_dwordx4 v160, s[100:101]
	s_mov_b32 m0, s61
	ds_read_b128 v[192:195], v209 offset:56320
	global_load_lds_dwordx4 v162, s[100:101]
	s_barrier
	s_waitcnt lgkmcnt(0)
	v_mfma_f32_16x16x32_bf16 v[60:63], v[128:131], v[144:147], v[60:63]
	v_mfma_f32_16x16x32_bf16 v[56:59], v[136:139], v[144:147], v[56:59]
	v_mfma_f32_16x16x32_bf16 v[52:55], v[128:131], v[152:155], v[52:55]
	v_mfma_f32_16x16x32_bf16 v[48:51], v[136:139], v[152:155], v[48:51]
	v_mfma_f32_16x16x32_bf16 v[36:39], v[128:131], v[180:183], v[36:39]
	v_mfma_f32_16x16x32_bf16 v[32:35], v[136:139], v[180:183], v[32:35]
	v_mfma_f32_16x16x32_bf16 v[20:23], v[128:131], v[188:191], v[20:23]
	v_mfma_f32_16x16x32_bf16 v[16:19], v[136:139], v[188:191], v[16:19]
	v_mfma_f32_16x16x32_bf16 v[60:63], v[132:135], v[148:151], v[60:63]
	v_mfma_f32_16x16x32_bf16 v[56:59], v[140:143], v[148:151], v[56:59]
	v_mfma_f32_16x16x32_bf16 v[52:55], v[132:135], v[156:159], v[52:55]
	v_mfma_f32_16x16x32_bf16 v[48:51], v[140:143], v[156:159], v[48:51]
	v_mfma_f32_16x16x32_bf16 v[36:39], v[132:135], v[184:187], v[36:39]
	v_mfma_f32_16x16x32_bf16 v[32:35], v[140:143], v[184:187], v[32:35]
	v_mfma_f32_16x16x32_bf16 v[20:23], v[132:135], v[192:195], v[20:23]
	v_mfma_f32_16x16x32_bf16 v[16:19], v[140:143], v[192:195], v[16:19]
	s_barrier
	s_add_i32 s8, s8, s54
	s_mov_b32 m0, s8
	s_add_u32 s2, s2, 0x40080
	s_addc_u32 s3, s3, 0
	global_load_lds_dwordx4 v160, s[2:3]
	s_add_i32 m0, s8, 0x2000
	s_nop 0
	global_load_lds_dwordx4 v162, s[2:3]
	s_waitcnt vmcnt(6)
	s_barrier
	v_mfma_f32_16x16x32_bf16 v[44:47], v[196:199], v[144:147], v[44:47]
	v_mfma_f32_16x16x32_bf16 v[40:43], v[210:213], v[144:147], v[40:43]
	v_mfma_f32_16x16x32_bf16 v[28:31], v[196:199], v[152:155], v[28:31]
	v_mfma_f32_16x16x32_bf16 v[24:27], v[210:213], v[152:155], v[24:27]
	v_mfma_f32_16x16x32_bf16 v[12:15], v[196:199], v[180:183], v[12:15]
	v_mfma_f32_16x16x32_bf16 v[8:11], v[210:213], v[180:183], v[8:11]
	v_mfma_f32_16x16x32_bf16 v[4:7], v[196:199], v[188:191], v[4:7]
	v_mfma_f32_16x16x32_bf16 v[0:3], v[210:213], v[188:191], v[0:3]
	v_mfma_f32_16x16x32_bf16 v[44:47], v[200:203], v[148:151], v[44:47]
	v_mfma_f32_16x16x32_bf16 v[40:43], v[214:217], v[148:151], v[40:43]
	v_mfma_f32_16x16x32_bf16 v[28:31], v[200:203], v[156:159], v[28:31]
	v_mfma_f32_16x16x32_bf16 v[24:27], v[214:217], v[156:159], v[24:27]
	v_mfma_f32_16x16x32_bf16 v[12:15], v[200:203], v[184:187], v[12:15]
	v_mfma_f32_16x16x32_bf16 v[8:11], v[214:217], v[184:187], v[8:11]
	v_mfma_f32_16x16x32_bf16 v[4:7], v[200:203], v[192:195], v[4:7]
	v_mfma_f32_16x16x32_bf16 v[0:3], v[214:217], v[192:195], v[0:3]
	s_add_i32 s41, s41, 2
	s_add_u32 s6, s6, 0x100
	s_addc_u32 s7, s7, 0
	s_add_u32 s39, s39, 0x100
	s_addc_u32 s40, s40, 0
	s_cmp_gt_u32 s41, 13
	s_barrier
.LBB0_355:
	s_add_u32 s2, s6, 0xfffc0080
	s_addc_u32 s3, s7, -1
	s_add_i32 s64, 0, 0x10000
	v_add_u32_e32 v140, s64, v208
	ds_read_b128 v[128:131], v140
	ds_read_b128 v[132:135], v140 offset:1024
	ds_read_b128 v[136:139], v140 offset:2048
	ds_read_b128 v[140:143], v140 offset:3072
	s_cmp_eq_u32 s41, 12
	s_cselect_b32 s9, s1, s3
	s_cselect_b32 s8, s31, s2
	s_cselect_b32 s3, s29, s40
	s_cselect_b32 s2, s38, s39
	s_add_i32 m0, s21, 0xc000
	ds_read_b128 v[144:147], v209
	ds_read_b128 v[148:151], v209 offset:1024
	ds_read_b128 v[152:155], v209 offset:2048
	ds_read_b128 v[156:159], v209 offset:3072
	ds_read_b128 v[180:183], v209 offset:4096
	ds_read_b128 v[184:187], v209 offset:5120
	ds_read_b128 v[188:191], v209 offset:6144
	global_load_lds_dwordx4 v164, s[6:7]
	s_add_i32 m0, s21, 0xe000
	ds_read_b128 v[192:195], v209 offset:7168
	global_load_lds_dwordx4 v166, s[6:7]
	s_waitcnt lgkmcnt(8)
	s_barrier
	s_waitcnt lgkmcnt(0)
	v_mfma_f32_16x16x32_bf16 v[124:127], v[128:131], v[144:147], v[124:127]
	v_mfma_f32_16x16x32_bf16 v[120:123], v[136:139], v[144:147], v[120:123]
	v_mfma_f32_16x16x32_bf16 v[116:119], v[128:131], v[152:155], v[116:119]
	v_mfma_f32_16x16x32_bf16 v[112:115], v[136:139], v[152:155], v[112:115]
	v_mfma_f32_16x16x32_bf16 v[100:103], v[128:131], v[180:183], v[100:103]
	v_mfma_f32_16x16x32_bf16 v[96:99], v[136:139], v[180:183], v[96:99]
	v_mfma_f32_16x16x32_bf16 v[84:87], v[128:131], v[188:191], v[84:87]
	v_mfma_f32_16x16x32_bf16 v[80:83], v[136:139], v[188:191], v[80:83]
	v_mfma_f32_16x16x32_bf16 v[124:127], v[132:135], v[148:151], v[124:127]
	v_mfma_f32_16x16x32_bf16 v[120:123], v[140:143], v[148:151], v[120:123]
	v_mfma_f32_16x16x32_bf16 v[116:119], v[132:135], v[156:159], v[116:119]
	v_mfma_f32_16x16x32_bf16 v[112:115], v[140:143], v[156:159], v[112:115]
	v_mfma_f32_16x16x32_bf16 v[100:103], v[132:135], v[184:187], v[100:103]
	v_mfma_f32_16x16x32_bf16 v[96:99], v[140:143], v[184:187], v[96:99]
	v_mfma_f32_16x16x32_bf16 v[84:87], v[132:135], v[192:195], v[84:87]
	v_mfma_f32_16x16x32_bf16 v[80:83], v[140:143], v[192:195], v[80:83]
	s_barrier
	s_add_i32 s66, 0, 0x14000
	s_add_i32 s64, s64, s54
	v_add_u32_e32 v168, s66, v208
	s_add_u32 s98, s2, 0x80
	s_addc_u32 s99, s3, 0
	s_mov_b32 m0, s64
	ds_read_b128 v[196:199], v168
	ds_read_b128 v[200:203], v168 offset:1024
	ds_read_b128 v[210:213], v168 offset:2048
	global_load_lds_dwordx4 v160, s[2:3]
	s_add_i32 m0, s64, 0x2000
	ds_read_b128 v[214:217], v168 offset:3072
	global_load_lds_dwordx4 v162, s[2:3]
	s_barrier
	s_waitcnt lgkmcnt(0)
	v_mfma_f32_16x16x32_bf16 v[108:111], v[196:199], v[144:147], v[108:111]
	v_mfma_f32_16x16x32_bf16 v[104:107], v[210:213], v[144:147], v[104:107]
	v_mfma_f32_16x16x32_bf16 v[92:95], v[196:199], v[152:155], v[92:95]
	v_mfma_f32_16x16x32_bf16 v[88:91], v[210:213], v[152:155], v[88:91]
	v_mfma_f32_16x16x32_bf16 v[76:79], v[196:199], v[180:183], v[76:79]
	v_mfma_f32_16x16x32_bf16 v[72:75], v[210:213], v[180:183], v[72:75]
	v_mfma_f32_16x16x32_bf16 v[68:71], v[196:199], v[188:191], v[68:71]
	v_mfma_f32_16x16x32_bf16 v[64:67], v[210:213], v[188:191], v[64:67]
	v_mfma_f32_16x16x32_bf16 v[108:111], v[200:203], v[148:151], v[108:111]
	v_mfma_f32_16x16x32_bf16 v[104:107], v[214:217], v[148:151], v[104:107]
	v_mfma_f32_16x16x32_bf16 v[92:95], v[200:203], v[156:159], v[92:95]
	v_mfma_f32_16x16x32_bf16 v[88:91], v[214:217], v[156:159], v[88:91]
	v_mfma_f32_16x16x32_bf16 v[76:79], v[200:203], v[184:187], v[76:79]
	v_mfma_f32_16x16x32_bf16 v[72:75], v[214:217], v[184:187], v[72:75]
	v_mfma_f32_16x16x32_bf16 v[68:71], v[200:203], v[192:195], v[68:71]
	v_mfma_f32_16x16x32_bf16 v[64:67], v[214:217], v[192:195], v[64:67]
	s_mov_b32 m0, s21
	s_add_u32 s100, s8, 0x80
	s_addc_u32 s101, s9, 0
	s_barrier
	ds_read_b128 v[144:147], v209 offset:16384
	ds_read_b128 v[148:151], v209 offset:17408
	ds_read_b128 v[152:155], v209 offset:18432
	ds_read_b128 v[156:159], v209 offset:19456
	ds_read_b128 v[180:183], v209 offset:20480
	ds_read_b128 v[184:187], v209 offset:21504
	ds_read_b128 v[188:191], v209 offset:22528
	global_load_lds_dwordx4 v160, s[8:9]
	s_mov_b32 m0, s55
	ds_read_b128 v[192:195], v209 offset:23552
	global_load_lds_dwordx4 v162, s[8:9]
	s_barrier
	s_waitcnt lgkmcnt(0)
	v_mfma_f32_16x16x32_bf16 v[60:63], v[128:131], v[144:147], v[60:63]
	v_mfma_f32_16x16x32_bf16 v[56:59], v[136:139], v[144:147], v[56:59]
	v_mfma_f32_16x16x32_bf16 v[52:55], v[128:131], v[152:155], v[52:55]
	v_mfma_f32_16x16x32_bf16 v[48:51], v[136:139], v[152:155], v[48:51]
	v_mfma_f32_16x16x32_bf16 v[36:39], v[128:131], v[180:183], v[36:39]
	v_mfma_f32_16x16x32_bf16 v[32:35], v[136:139], v[180:183], v[32:35]
	v_mfma_f32_16x16x32_bf16 v[20:23], v[128:131], v[188:191], v[20:23]
	v_mfma_f32_16x16x32_bf16 v[16:19], v[136:139], v[188:191], v[16:19]
	v_mfma_f32_16x16x32_bf16 v[60:63], v[132:135], v[148:151], v[60:63]
	v_mfma_f32_16x16x32_bf16 v[56:59], v[140:143], v[148:151], v[56:59]
	v_mfma_f32_16x16x32_bf16 v[52:55], v[132:135], v[156:159], v[52:55]
	v_mfma_f32_16x16x32_bf16 v[48:51], v[140:143], v[156:159], v[48:51]
	v_mfma_f32_16x16x32_bf16 v[36:39], v[132:135], v[184:187], v[36:39]
	v_mfma_f32_16x16x32_bf16 v[32:35], v[140:143], v[184:187], v[32:35]
	v_mfma_f32_16x16x32_bf16 v[20:23], v[132:135], v[192:195], v[20:23]
	v_mfma_f32_16x16x32_bf16 v[16:19], v[140:143], v[192:195], v[16:19]
	s_barrier
	s_add_i32 s66, s66, s54
	s_mov_b32 m0, s66
	s_add_u32 s64, s2, 0x40000
	s_addc_u32 s65, s3, 0
	global_load_lds_dwordx4 v160, s[64:65]
	s_add_i32 m0, s66, 0x2000
	s_nop 0
	global_load_lds_dwordx4 v162, s[64:65]
	s_waitcnt vmcnt(6)
	s_barrier
	v_mfma_f32_16x16x32_bf16 v[44:47], v[196:199], v[144:147], v[44:47]
	v_mfma_f32_16x16x32_bf16 v[40:43], v[210:213], v[144:147], v[40:43]
	v_mfma_f32_16x16x32_bf16 v[28:31], v[196:199], v[152:155], v[28:31]
	v_mfma_f32_16x16x32_bf16 v[24:27], v[210:213], v[152:155], v[24:27]
	v_mfma_f32_16x16x32_bf16 v[12:15], v[196:199], v[180:183], v[12:15]
	v_mfma_f32_16x16x32_bf16 v[8:11], v[210:213], v[180:183], v[8:11]
	v_mfma_f32_16x16x32_bf16 v[4:7], v[196:199], v[188:191], v[4:7]
	v_mfma_f32_16x16x32_bf16 v[0:3], v[210:213], v[188:191], v[0:3]
	v_mfma_f32_16x16x32_bf16 v[44:47], v[200:203], v[148:151], v[44:47]
	v_mfma_f32_16x16x32_bf16 v[40:43], v[214:217], v[148:151], v[40:43]
	v_mfma_f32_16x16x32_bf16 v[28:31], v[200:203], v[156:159], v[28:31]
	v_mfma_f32_16x16x32_bf16 v[24:27], v[214:217], v[156:159], v[24:27]
	v_mfma_f32_16x16x32_bf16 v[12:15], v[200:203], v[184:187], v[12:15]
	v_mfma_f32_16x16x32_bf16 v[8:11], v[214:217], v[184:187], v[8:11]
	v_mfma_f32_16x16x32_bf16 v[4:7], v[200:203], v[192:195], v[4:7]
	v_mfma_f32_16x16x32_bf16 v[0:3], v[214:217], v[192:195], v[0:3]
	s_add_i32 s64, 0, 0x18000
	v_add_u32_e32 v140, s64, v208
	s_barrier
	ds_read_b128 v[128:131], v140
	ds_read_b128 v[132:135], v140 offset:1024
	ds_read_b128 v[136:139], v140 offset:2048
	ds_read_b128 v[140:143], v140 offset:3072
	s_add_u32 s8, s8, 0x40000
	s_addc_u32 s9, s9, 0
	s_mov_b32 m0, s56
	ds_read_b128 v[144:147], v209 offset:32768
	ds_read_b128 v[148:151], v209 offset:33792
	ds_read_b128 v[152:155], v209 offset:34816
	ds_read_b128 v[156:159], v209 offset:35840
	ds_read_b128 v[180:183], v209 offset:36864
	ds_read_b128 v[184:187], v209 offset:37888
	ds_read_b128 v[188:191], v209 offset:38912
	global_load_lds_dwordx4 v160, s[8:9]
	s_mov_b32 m0, s57
	ds_read_b128 v[192:195], v209 offset:39936
	global_load_lds_dwordx4 v162, s[8:9]
	s_waitcnt lgkmcnt(8)
	s_barrier
	s_waitcnt lgkmcnt(0)
	v_mfma_f32_16x16x32_bf16 v[124:127], v[128:131], v[144:147], v[124:127]
	v_mfma_f32_16x16x32_bf16 v[120:123], v[136:139], v[144:147], v[120:123]
	v_mfma_f32_16x16x32_bf16 v[116:119], v[128:131], v[152:155], v[116:119]
	v_mfma_f32_16x16x32_bf16 v[112:115], v[136:139], v[152:155], v[112:115]
	v_mfma_f32_16x16x32_bf16 v[100:103], v[128:131], v[180:183], v[100:103]
	v_mfma_f32_16x16x32_bf16 v[96:99], v[136:139], v[180:183], v[96:99]
	v_mfma_f32_16x16x32_bf16 v[84:87], v[128:131], v[188:191], v[84:87]
	v_mfma_f32_16x16x32_bf16 v[80:83], v[136:139], v[188:191], v[80:83]
	v_mfma_f32_16x16x32_bf16 v[124:127], v[132:135], v[148:151], v[124:127]
	v_mfma_f32_16x16x32_bf16 v[120:123], v[140:143], v[148:151], v[120:123]
	v_mfma_f32_16x16x32_bf16 v[116:119], v[132:135], v[156:159], v[116:119]
	v_mfma_f32_16x16x32_bf16 v[112:115], v[140:143], v[156:159], v[112:115]
	v_mfma_f32_16x16x32_bf16 v[100:103], v[132:135], v[184:187], v[100:103]
	v_mfma_f32_16x16x32_bf16 v[96:99], v[140:143], v[184:187], v[96:99]
	v_mfma_f32_16x16x32_bf16 v[84:87], v[132:135], v[192:195], v[84:87]
	v_mfma_f32_16x16x32_bf16 v[80:83], v[140:143], v[192:195], v[80:83]
	s_barrier
	s_add_i32 s8, 0, 0x1c000
	s_add_i32 s9, s64, s54
	v_add_u32_e32 v168, s8, v208
	s_mov_b32 m0, s9
	ds_read_b128 v[196:199], v168
	ds_read_b128 v[200:203], v168 offset:1024
	ds_read_b128 v[210:213], v168 offset:2048
	global_load_lds_dwordx4 v160, s[98:99]
	s_add_i32 m0, s9, 0x2000
	ds_read_b128 v[214:217], v168 offset:3072
	global_load_lds_dwordx4 v162, s[98:99]
	s_barrier
	s_waitcnt lgkmcnt(0)
	v_mfma_f32_16x16x32_bf16 v[108:111], v[196:199], v[144:147], v[108:111]
	v_mfma_f32_16x16x32_bf16 v[104:107], v[210:213], v[144:147], v[104:107]
	v_mfma_f32_16x16x32_bf16 v[92:95], v[196:199], v[152:155], v[92:95]
	v_mfma_f32_16x16x32_bf16 v[88:91], v[210:213], v[152:155], v[88:91]
	v_mfma_f32_16x16x32_bf16 v[76:79], v[196:199], v[180:183], v[76:79]
	v_mfma_f32_16x16x32_bf16 v[72:75], v[210:213], v[180:183], v[72:75]
	v_mfma_f32_16x16x32_bf16 v[68:71], v[196:199], v[188:191], v[68:71]
	v_mfma_f32_16x16x32_bf16 v[64:67], v[210:213], v[188:191], v[64:67]
	v_mfma_f32_16x16x32_bf16 v[108:111], v[200:203], v[148:151], v[108:111]
	v_mfma_f32_16x16x32_bf16 v[104:107], v[214:217], v[148:151], v[104:107]
	v_mfma_f32_16x16x32_bf16 v[92:95], v[200:203], v[156:159], v[92:95]
	v_mfma_f32_16x16x32_bf16 v[88:91], v[214:217], v[156:159], v[88:91]
	v_mfma_f32_16x16x32_bf16 v[76:79], v[200:203], v[184:187], v[76:79]
	v_mfma_f32_16x16x32_bf16 v[72:75], v[214:217], v[184:187], v[72:75]
	v_mfma_f32_16x16x32_bf16 v[68:71], v[200:203], v[192:195], v[68:71]
	v_mfma_f32_16x16x32_bf16 v[64:67], v[214:217], v[192:195], v[64:67]
	s_mov_b32 m0, s60
	s_barrier
	ds_read_b128 v[144:147], v209 offset:49152
	ds_read_b128 v[148:151], v209 offset:50176
	ds_read_b128 v[152:155], v209 offset:51200
	ds_read_b128 v[156:159], v209 offset:52224
	ds_read_b128 v[180:183], v209 offset:53248
	ds_read_b128 v[184:187], v209 offset:54272
	ds_read_b128 v[188:191], v209 offset:55296
	global_load_lds_dwordx4 v160, s[100:101]
	s_mov_b32 m0, s61
	ds_read_b128 v[192:195], v209 offset:56320
	global_load_lds_dwordx4 v162, s[100:101]
	s_barrier
	s_waitcnt lgkmcnt(0)
	v_mfma_f32_16x16x32_bf16 v[60:63], v[128:131], v[144:147], v[60:63]
	v_mfma_f32_16x16x32_bf16 v[56:59], v[136:139], v[144:147], v[56:59]
	v_mfma_f32_16x16x32_bf16 v[52:55], v[128:131], v[152:155], v[52:55]
	v_mfma_f32_16x16x32_bf16 v[48:51], v[136:139], v[152:155], v[48:51]
	v_mfma_f32_16x16x32_bf16 v[36:39], v[128:131], v[180:183], v[36:39]
	v_mfma_f32_16x16x32_bf16 v[32:35], v[136:139], v[180:183], v[32:35]
	v_mfma_f32_16x16x32_bf16 v[20:23], v[128:131], v[188:191], v[20:23]
	v_mfma_f32_16x16x32_bf16 v[16:19], v[136:139], v[188:191], v[16:19]
	v_mfma_f32_16x16x32_bf16 v[60:63], v[132:135], v[148:151], v[60:63]
	v_mfma_f32_16x16x32_bf16 v[56:59], v[140:143], v[148:151], v[56:59]
	v_mfma_f32_16x16x32_bf16 v[52:55], v[132:135], v[156:159], v[52:55]
	v_mfma_f32_16x16x32_bf16 v[48:51], v[140:143], v[156:159], v[48:51]
	v_mfma_f32_16x16x32_bf16 v[36:39], v[132:135], v[184:187], v[36:39]
	v_mfma_f32_16x16x32_bf16 v[32:35], v[140:143], v[184:187], v[32:35]
	v_mfma_f32_16x16x32_bf16 v[20:23], v[132:135], v[192:195], v[20:23]
	v_mfma_f32_16x16x32_bf16 v[16:19], v[140:143], v[192:195], v[16:19]
	s_barrier
	s_add_i32 s8, s8, s54
	s_mov_b32 m0, s8
	s_add_u32 s2, s2, 0x40080
	s_addc_u32 s3, s3, 0
	global_load_lds_dwordx4 v160, s[2:3]
	s_add_i32 m0, s8, 0x2000
	s_nop 0
	global_load_lds_dwordx4 v162, s[2:3]
	s_waitcnt vmcnt(6)
	s_barrier
	v_mfma_f32_16x16x32_bf16 v[44:47], v[196:199], v[144:147], v[44:47]
	v_mfma_f32_16x16x32_bf16 v[40:43], v[210:213], v[144:147], v[40:43]
	v_mfma_f32_16x16x32_bf16 v[28:31], v[196:199], v[152:155], v[28:31]
	v_mfma_f32_16x16x32_bf16 v[24:27], v[210:213], v[152:155], v[24:27]
	v_mfma_f32_16x16x32_bf16 v[12:15], v[196:199], v[180:183], v[12:15]
	v_mfma_f32_16x16x32_bf16 v[8:11], v[210:213], v[180:183], v[8:11]
	v_mfma_f32_16x16x32_bf16 v[4:7], v[196:199], v[188:191], v[4:7]
	v_mfma_f32_16x16x32_bf16 v[0:3], v[210:213], v[188:191], v[0:3]
	v_mfma_f32_16x16x32_bf16 v[44:47], v[200:203], v[148:151], v[44:47]
	v_mfma_f32_16x16x32_bf16 v[40:43], v[214:217], v[148:151], v[40:43]
	v_mfma_f32_16x16x32_bf16 v[28:31], v[200:203], v[156:159], v[28:31]
	v_mfma_f32_16x16x32_bf16 v[24:27], v[214:217], v[156:159], v[24:27]
	v_mfma_f32_16x16x32_bf16 v[12:15], v[200:203], v[184:187], v[12:15]
	v_mfma_f32_16x16x32_bf16 v[8:11], v[214:217], v[184:187], v[8:11]
	v_mfma_f32_16x16x32_bf16 v[4:7], v[200:203], v[192:195], v[4:7]
	v_mfma_f32_16x16x32_bf16 v[0:3], v[214:217], v[192:195], v[0:3]
	s_add_i32 s41, s41, 2
	s_add_u32 s6, s6, 0x100
	s_addc_u32 s7, s7, 0
	s_add_u32 s39, s39, 0x100
	s_addc_u32 s40, s40, 0
	s_cmp_gt_u32 s41, 13
	s_barrier
	s_cbranch_scc0 .LBB0_355
	s_lshl_b32 s1, s0, 8
	v_mov_b32_e32 v211, v206
	v_mov_b32_e32 v210, v207
	s_add_i32 s1, s1, s59
	s_cmp_lt_i32 s20, 3
	v_add_u32_e32 v180, s1, v211
	s_mov_b64 s[2:3], -1
	s_cbranch_scc0 .LBB0_490
	s_cmp_gt_i32 s0, 15
	s_cselect_b64 s[2:3], -1, 0
	s_cmp_lt_i32 s0, 16
	s_cselect_b64 s[38:39], -1, 0
	s_cmp_eq_u32 s20, 2
	s_cselect_b64 s[8:9], -1, 0
	s_cmp_lg_u32 s20, 2
	s_cselect_b64 s[0:1], -1, 0
	s_and_b64 s[40:41], s[8:9], s[22:23]
	v_lshlrev_b32_e32 v182, 2, v210
	s_mov_b64 s[6:7], -1
	s_and_b64 vcc, exec, s[40:41]
	v_ashrrev_i32_e32 v183, 31, v182
	s_cbranch_vccnz .LBB0_447
	s_and_b64 s[6:7], s[8:9], exec
	s_cselect_b32 s6, s46, s44
	s_cselect_b32 s7, s47, s45
	v_mov_b32_e32 v128, s7
	v_mov_b32_e32 v129, s6
	v_lshl_add_u64 v[128:129], v[182:183], 2, v[128:129]
	global_load_dwordx4 v[140:143], v[128:129], off
	global_load_dwordx4 v[136:139], v[128:129], off offset:64
	global_load_dwordx4 v[132:135], v[128:129], off offset:128
	s_nop 0
	global_load_dwordx4 v[128:131], v[128:129], off offset:192
	v_mul_f32_e32 v144, v125, v125
	v_mul_f32_e32 v145, v127, v127
	v_fmac_f32_e32 v144, v124, v124
	v_fmac_f32_e32 v145, v126, v126
	v_add_f32_e32 v144, v144, v145
	v_mul_f32_e32 v145, v121, v121
	v_mul_f32_e32 v146, v123, v123
	v_fmac_f32_e32 v145, v120, v120
	v_fmac_f32_e32 v146, v122, v122
	v_add_f32_e32 v145, v145, v146
	v_add_f32_e32 v144, v144, v145
	v_mul_f32_e32 v145, v109, v109
	v_mul_f32_e32 v146, v111, v111
	v_fmac_f32_e32 v145, v108, v108
	v_fmac_f32_e32 v146, v110, v110
	v_add_f32_e32 v145, v145, v146
	v_add_f32_e32 v144, v144, v145
	v_mul_f32_e32 v145, v105, v105
	v_mul_f32_e32 v146, v107, v107
	v_fmac_f32_e32 v145, v104, v104
	v_fmac_f32_e32 v146, v106, v106
	v_add_f32_e32 v145, v145, v146
	v_add_f32_e32 v144, v144, v145
	v_mov_b32_e32 v145, v144
	s_nop 1
	v_permlane16_swap_b32_e32 v144, v145
	v_add_f32_e32 v144, v144, v145
	v_mov_b32_e32 v145, v144
	s_nop 1
	v_permlane32_swap_b32_e32 v144, v145
	v_add_f32_e32 v144, v144, v145
	v_fmamk_f32 v144, v144, 0x3c800000, v225
	v_cmp_gt_f32_e32 vcc, s93, v144
	v_mul_f32_e32 v145, 0x4b800000, v144
	v_and_b32_e32 v202, 63, v211
	v_cndmask_b32_e32 v144, v144, v145, vcc
	v_rsq_f32_e32 v144, v144
	v_cndmask_b32_e64 v168, 0, 1, s[2:3]
	v_cmp_ne_u32_e64 s[6:7], 1, v168
	v_lshlrev_b32_e32 v186, 7, v202
	v_mul_f32_e32 v145, 0x45800000, v144
	v_cndmask_b32_e32 v152, v144, v145, vcc
	v_pk_mul_f32 v[144:145], v[124:125], v[152:153] op_sel_hi:[1,0]
	v_pk_mul_f32 v[146:147], v[126:127], v[152:153] op_sel_hi:[1,0]
	v_pk_mul_f32 v[148:149], v[108:109], v[152:153] op_sel_hi:[1,0]
	v_pk_mul_f32 v[150:151], v[110:111], v[152:153] op_sel_hi:[1,0]
	v_pk_mul_f32 v[184:185], v[104:105], v[152:153] op_sel_hi:[1,0]
	s_andn2_b64 vcc, exec, s[2:3]
	s_waitcnt vmcnt(0)
	v_pk_mul_f32 v[158:159], v[142:143], v[146:147]
	v_pk_mul_f32 v[156:157], v[140:141], v[144:145]
	v_pk_mul_f32 v[144:145], v[120:121], v[152:153] op_sel_hi:[1,0]
	v_pk_mul_f32 v[146:147], v[122:123], v[152:153] op_sel_hi:[1,0]
	v_pk_mul_f32 v[152:153], v[106:107], v[152:153] op_sel_hi:[1,0]
	v_pk_mul_f32 v[146:147], v[138:139], v[146:147]
	v_pk_mul_f32 v[144:145], v[136:137], v[144:145]
	v_pk_mul_f32 v[150:151], v[134:135], v[150:151]
	v_pk_mul_f32 v[148:149], v[132:133], v[148:149]
	v_pk_mul_f32 v[154:155], v[130:131], v[152:153]
	v_pk_mul_f32 v[152:153], v[128:129], v[184:185]
	v_lshl_add_u64 v[184:185], v[182:183], 3, s[18:19]
	s_cbranch_vccnz .LBB0_360
	v_lshlrev_b32_e32 v168, 1, v180
	v_and_b32_e32 v168, 0xf80, v168
	v_lshl_add_u64 v[188:189], v[184:185], 0, v[168:169]
	global_load_dwordx4 v[190:193], v[188:189], off offset:16
	global_load_dwordx4 v[194:197], v[188:189], off
	v_mov_b32_e32 v187, v169
	s_waitcnt vmcnt(0)
	v_mul_f32_e32 v198, v158, v190
	v_mov_b32_e32 v188, v194
	v_mov_b32_e32 v189, v196
	v_mov_b32_e32 v196, v195
	v_mul_f32_e32 v200, v146, v191
	v_mul_f32_e32 v204, v146, v190
	v_mul_f32_e32 v212, v158, v191
	v_mov_b32_e32 v146, v159
	v_mov_b32_e32 v158, v147
	v_pk_mul_f32 v[194:195], v[144:145], v[196:197]
	v_pk_mul_f32 v[144:145], v[144:145], v[188:189]
	v_pk_mul_f32 v[190:191], v[146:147], v[192:193]
	v_pk_mul_f32 v[146:147], v[158:159], v[192:193]
	v_lshl_add_u64 v[192:193], v[184:185], 0, v[186:187]
	v_mov_b32_e32 v199, v190
	v_mov_b32_e32 v201, v191
	v_pk_fma_f32 v[190:191], v[156:157], v[188:189], v[194:195] neg_lo:[0,0,1] neg_hi:[0,0,1]
	v_pk_fma_f32 v[144:145], v[156:157], v[196:197], v[144:145]
	global_load_dwordx4 v[156:159], v[192:193], off offset:16
	s_nop 0
	global_load_dwordx4 v[192:195], v[192:193], off
	v_pk_add_f32 v[188:189], v[198:199], v[200:201] neg_lo:[0,1] neg_hi:[0,1]
	v_mov_b32_e32 v213, v147
	v_mov_b32_e32 v205, v146
	v_pk_add_f32 v[146:147], v[212:213], v[204:205]
	s_waitcnt vmcnt(0)
	v_mul_f32_e32 v198, v150, v156
	v_mul_f32_e32 v200, v154, v157
	v_mul_f32_e32 v156, v154, v156
	v_mov_b32_e32 v154, v151
	v_mov_b32_e32 v197, v194
	v_mov_b32_e32 v194, v193
	v_mul_f32_e32 v204, v150, v157
	v_pk_mul_f32 v[212:213], v[154:155], v[158:159]
	v_mov_b32_e32 v150, v155
	v_mov_b32_e32 v196, v192
	v_pk_mul_f32 v[192:193], v[152:153], v[194:195]
	v_mov_b32_e32 v199, v212
	v_mov_b32_e32 v201, v213
	v_pk_mul_f32 v[150:151], v[150:151], v[158:159]
	v_pk_mul_f32 v[152:153], v[152:153], v[196:197]
	v_pk_fma_f32 v[192:193], v[148:149], v[196:197], v[192:193] neg_lo:[0,0,1] neg_hi:[0,0,1]
	v_pk_add_f32 v[196:197], v[198:199], v[200:201] neg_lo:[0,1] neg_hi:[0,1]
	v_mov_b32_e32 v205, v151
	v_mov_b32_e32 v157, v150
	v_pk_fma_f32 v[152:153], v[148:149], v[194:195], v[152:153]
	v_pk_add_f32 v[154:155], v[204:205], v[156:157]
	v_mov_b32_e32 v148, v192
	v_mov_b32_e32 v149, v193
	v_mov_b32_e32 v150, v196
	v_mov_b32_e32 v151, v197
	v_mov_b32_e32 v156, v190
	v_mov_b32_e32 v157, v191
	v_mov_b32_e32 v158, v188
	v_mov_b32_e32 v159, v189

.LBB0_677:
	s_ashr_i32 s23, s22, 31
	v_cmp_lt_i64_e32 vcc, s[24:25], v[174:175]
	s_lshl_b64 s[24:25], s[22:23], 19
	s_add_u32 s24, s36, s24
	s_addc_u32 s25, s37, s25
	s_and_b64 s[26:27], vcc, exec
	s_cselect_b32 s1, s25, s9
	s_cselect_b32 s7, s24, s8
	s_ashr_i32 s21, s20, 31
	s_lshl_b64 s[26:27], s[20:21], 19
	s_add_u32 s26, s38, s26
	s_addc_u32 s27, s39, s27
	s_and_b64 s[28:29], vcc, exec
	s_cselect_b32 s21, s27, s3
	s_cselect_b32 s23, s26, s2
	s_add_u32 s8, s8, 0x40080
	s_addc_u32 s9, s9, 0
	s_add_u32 s56, s2, 0x100
	s_addc_u32 s57, s3, 0
	s_mov_b32 s58, -2
	s_add_u32 s2, s8, 0xfffc0080
	s_addc_u32 s3, s9, -1
	s_add_i32 s59, 0, 0x10000
	v_add_u32_e32 v68, s59, v206
	ds_read_b128 v[48:51], v68
	ds_read_b128 v[52:55], v68 offset:1024
	ds_read_b128 v[60:63], v68 offset:2048
	ds_read_b128 v[68:71], v68 offset:3072
	s_cmp_eq_u32 s58, 12
	s_cselect_b32 s29, s1, s3
	s_cselect_b32 s28, s7, s2
	s_cselect_b32 s3, s21, s57
	s_cselect_b32 s2, s23, s56
	s_add_i32 m0, s41, 0xc000
	ds_read_b128 v[72:75], v207
	ds_read_b128 v[76:79], v207 offset:1024
	ds_read_b128 v[80:83], v207 offset:2048
	ds_read_b128 v[84:87], v207 offset:3072
	ds_read_b128 v[160:163], v207 offset:4096
	ds_read_b128 v[164:167], v207 offset:5120
	ds_read_b128 v[192:195], v207 offset:6144
	global_load_lds_dwordx4 v188, s[8:9]
	s_add_i32 m0, s41, 0xe000
	ds_read_b128 v[196:199], v207 offset:7168
	global_load_lds_dwordx4 v190, s[8:9]
	s_waitcnt lgkmcnt(8)
	s_barrier
	s_waitcnt lgkmcnt(0)
	v_mfma_f32_16x16x32_bf16 v[156:159], v[48:51], v[72:75], 0
	v_mfma_f32_16x16x32_bf16 v[152:155], v[60:63], v[72:75], 0
	v_mfma_f32_16x16x32_bf16 v[140:143], v[48:51], v[80:83], 0
	v_mfma_f32_16x16x32_bf16 v[136:139], v[60:63], v[80:83], 0
	v_mfma_f32_16x16x32_bf16 v[124:127], v[48:51], v[160:163], 0
	v_mfma_f32_16x16x32_bf16 v[120:123], v[60:63], v[160:163], 0
	v_mfma_f32_16x16x32_bf16 v[108:111], v[48:51], v[192:195], 0
	v_mfma_f32_16x16x32_bf16 v[104:107], v[60:63], v[192:195], 0
	v_mfma_f32_16x16x32_bf16 v[156:159], v[52:55], v[76:79], v[156:159]
	v_mfma_f32_16x16x32_bf16 v[152:155], v[68:71], v[76:79], v[152:155]
	v_mfma_f32_16x16x32_bf16 v[140:143], v[52:55], v[84:87], v[140:143]
	v_mfma_f32_16x16x32_bf16 v[136:139], v[68:71], v[84:87], v[136:139]
	v_mfma_f32_16x16x32_bf16 v[124:127], v[52:55], v[164:167], v[124:127]
	v_mfma_f32_16x16x32_bf16 v[120:123], v[68:71], v[164:167], v[120:123]
	v_mfma_f32_16x16x32_bf16 v[108:111], v[52:55], v[196:199], v[108:111]
	v_mfma_f32_16x16x32_bf16 v[104:107], v[68:71], v[196:199], v[104:107]
	s_barrier
	s_add_i32 s62, 0, 0x14000
	s_add_i32 s59, s59, s40
	v_add_u32_e32 v168, s62, v206
	s_add_u32 s98, s2, 0x80
	s_addc_u32 s99, s3, 0
	s_mov_b32 m0, s59
	ds_read_b128 v[200:203], v168
	ds_read_b128 v[208:211], v168 offset:1024
	ds_read_b128 v[212:215], v168 offset:2048
	global_load_lds_dwordx4 v182, s[2:3]
	s_add_i32 m0, s59, 0x2000
	ds_read_b128 v[216:219], v168 offset:3072
	global_load_lds_dwordx4 v186, s[2:3]
	s_barrier
	s_waitcnt lgkmcnt(0)
	v_mfma_f32_16x16x32_bf16 v[148:151], v[200:203], v[72:75], 0
	v_mfma_f32_16x16x32_bf16 v[72:75], v[212:215], v[72:75], 0
	v_mfma_f32_16x16x32_bf16 v[148:151], v[208:211], v[76:79], v[148:151]
	v_mfma_f32_16x16x32_bf16 v[72:75], v[216:219], v[76:79], v[72:75]
	v_mfma_f32_16x16x32_bf16 v[76:79], v[200:203], v[80:83], 0
	v_mfma_f32_16x16x32_bf16 v[80:83], v[212:215], v[80:83], 0
	v_mfma_f32_16x16x32_bf16 v[112:115], v[212:215], v[160:163], 0
	v_mfma_f32_16x16x32_bf16 v[100:103], v[200:203], v[192:195], 0
	v_mfma_f32_16x16x32_bf16 v[96:99], v[212:215], v[192:195], 0
	v_mfma_f32_16x16x32_bf16 v[76:79], v[208:211], v[84:87], v[76:79]
	v_mfma_f32_16x16x32_bf16 v[80:83], v[216:219], v[84:87], v[80:83]
	v_mfma_f32_16x16x32_bf16 v[84:87], v[200:203], v[160:163], 0
	v_mfma_f32_16x16x32_bf16 v[112:115], v[216:219], v[164:167], v[112:115]
	v_mfma_f32_16x16x32_bf16 v[100:103], v[208:211], v[196:199], v[100:103]
	v_mfma_f32_16x16x32_bf16 v[96:99], v[216:219], v[196:199], v[96:99]
	v_mfma_f32_16x16x32_bf16 v[84:87], v[208:211], v[164:167], v[84:87]
	s_mov_b32 m0, s41
	s_add_u32 s100, s28, 0x80
	s_addc_u32 s101, s29, 0
	s_barrier
	ds_read_b128 v[116:119], v207 offset:16384
	ds_read_b128 v[128:131], v207 offset:17408
	ds_read_b128 v[132:135], v207 offset:18432
	ds_read_b128 v[144:147], v207 offset:19456
	ds_read_b128 v[160:163], v207 offset:20480
	ds_read_b128 v[164:167], v207 offset:21504
	ds_read_b128 v[192:195], v207 offset:22528
	global_load_lds_dwordx4 v180, s[28:29]
	s_mov_b32 m0, s42
	ds_read_b128 v[196:199], v207 offset:23552
	global_load_lds_dwordx4 v184, s[28:29]
	s_barrier
	s_waitcnt lgkmcnt(0)
	v_mfma_f32_16x16x32_bf16 v[92:95], v[48:51], v[116:119], 0
	v_mfma_f32_16x16x32_bf16 v[88:91], v[60:63], v[116:119], 0
	v_mfma_f32_16x16x32_bf16 v[44:47], v[48:51], v[132:135], 0
	v_mfma_f32_16x16x32_bf16 v[40:43], v[60:63], v[132:135], 0
	v_mfma_f32_16x16x32_bf16 v[28:31], v[48:51], v[160:163], 0
	v_mfma_f32_16x16x32_bf16 v[24:27], v[60:63], v[160:163], 0
	v_mfma_f32_16x16x32_bf16 v[12:15], v[48:51], v[192:195], 0
	v_mfma_f32_16x16x32_bf16 v[8:11], v[60:63], v[192:195], 0
	v_mfma_f32_16x16x32_bf16 v[92:95], v[52:55], v[128:131], v[92:95]
	v_mfma_f32_16x16x32_bf16 v[88:91], v[68:71], v[128:131], v[88:91]
	v_mfma_f32_16x16x32_bf16 v[44:47], v[52:55], v[144:147], v[44:47]
	v_mfma_f32_16x16x32_bf16 v[40:43], v[68:71], v[144:147], v[40:43]
	v_mfma_f32_16x16x32_bf16 v[28:31], v[52:55], v[164:167], v[28:31]
	v_mfma_f32_16x16x32_bf16 v[24:27], v[68:71], v[164:167], v[24:27]
	v_mfma_f32_16x16x32_bf16 v[12:15], v[52:55], v[196:199], v[12:15]
	v_mfma_f32_16x16x32_bf16 v[8:11], v[68:71], v[196:199], v[8:11]
	s_barrier
	s_add_i32 s59, s62, s40
	s_mov_b32 m0, s59
	s_add_u32 s60, s2, 0x40000
	s_addc_u32 s61, s3, 0
	global_load_lds_dwordx4 v182, s[60:61]
	s_add_i32 m0, s59, 0x2000
	s_nop 0
	global_load_lds_dwordx4 v186, s[60:61]
	s_waitcnt vmcnt(6)
	s_barrier
	v_mfma_f32_16x16x32_bf16 v[36:39], v[200:203], v[132:135], 0
	v_mfma_f32_16x16x32_bf16 v[32:35], v[212:215], v[132:135], 0
	v_mfma_f32_16x16x32_bf16 v[20:23], v[200:203], v[160:163], 0
	v_mfma_f32_16x16x32_bf16 v[16:19], v[212:215], v[160:163], 0
	v_mfma_f32_16x16x32_bf16 v[4:7], v[200:203], v[192:195], 0
	v_mfma_f32_16x16x32_bf16 v[0:3], v[212:215], v[192:195], 0
	v_mfma_f32_16x16x32_bf16 v[48:51], v[200:203], v[116:119], 0
	v_mfma_f32_16x16x32_bf16 v[52:55], v[212:215], v[116:119], 0
	v_mfma_f32_16x16x32_bf16 v[36:39], v[208:211], v[144:147], v[36:39]
	v_mfma_f32_16x16x32_bf16 v[32:35], v[216:219], v[144:147], v[32:35]
	v_mfma_f32_16x16x32_bf16 v[20:23], v[208:211], v[164:167], v[20:23]
	v_mfma_f32_16x16x32_bf16 v[16:19], v[216:219], v[164:167], v[16:19]
	v_mfma_f32_16x16x32_bf16 v[4:7], v[208:211], v[196:199], v[4:7]
	v_mfma_f32_16x16x32_bf16 v[0:3], v[216:219], v[196:199], v[0:3]
	v_mfma_f32_16x16x32_bf16 v[48:51], v[208:211], v[128:131], v[48:51]
	v_mfma_f32_16x16x32_bf16 v[52:55], v[216:219], v[128:131], v[52:55]
	s_add_i32 s59, 0, 0x18000
	v_add_u32_e32 v68, s59, v206
	s_barrier
	ds_read_b128 v[56:59], v68
	ds_read_b128 v[60:63], v68 offset:1024
	ds_read_b128 v[64:67], v68 offset:2048
	ds_read_b128 v[68:71], v68 offset:3072
	s_add_u32 s28, s28, 0x40000
	s_addc_u32 s29, s29, 0
	s_mov_b32 m0, s43
	ds_read_b128 v[116:119], v207 offset:32768
	ds_read_b128 v[128:131], v207 offset:33792
	ds_read_b128 v[160:163], v207 offset:34816
	ds_read_b128 v[164:167], v207 offset:35840
	ds_read_b128 v[192:195], v207 offset:36864
	ds_read_b128 v[196:199], v207 offset:37888
	ds_read_b128 v[200:203], v207 offset:38912
	global_load_lds_dwordx4 v180, s[28:29]
	s_mov_b32 m0, s44
	ds_read_b128 v[208:211], v207 offset:39936
	global_load_lds_dwordx4 v184, s[28:29]
	s_waitcnt lgkmcnt(8)
	s_barrier
	s_waitcnt lgkmcnt(0)
	v_mfma_f32_16x16x32_bf16 v[132:135], v[56:59], v[116:119], v[156:159]
	v_mfma_f32_16x16x32_bf16 v[156:159], v[60:63], v[128:131], v[132:135]
	v_mfma_f32_16x16x32_bf16 v[132:135], v[64:67], v[116:119], v[152:155]
	v_mfma_f32_16x16x32_bf16 v[152:155], v[68:71], v[128:131], v[132:135]
	v_mfma_f32_16x16x32_bf16 v[132:135], v[56:59], v[160:163], v[140:143]
	v_mfma_f32_16x16x32_bf16 v[140:143], v[60:63], v[164:167], v[132:135]
	v_mfma_f32_16x16x32_bf16 v[132:135], v[64:67], v[160:163], v[136:139]
	v_mfma_f32_16x16x32_bf16 v[124:127], v[56:59], v[192:195], v[124:127]
	v_mfma_f32_16x16x32_bf16 v[120:123], v[64:67], v[192:195], v[120:123]
	v_mfma_f32_16x16x32_bf16 v[108:111], v[56:59], v[200:203], v[108:111]
	v_mfma_f32_16x16x32_bf16 v[104:107], v[64:67], v[200:203], v[104:107]
	v_mfma_f32_16x16x32_bf16 v[136:139], v[68:71], v[164:167], v[132:135]
	v_mfma_f32_16x16x32_bf16 v[124:127], v[60:63], v[196:199], v[124:127]
	v_mfma_f32_16x16x32_bf16 v[120:123], v[68:71], v[196:199], v[120:123]
	v_mfma_f32_16x16x32_bf16 v[108:111], v[60:63], v[208:211], v[108:111]
	v_mfma_f32_16x16x32_bf16 v[104:107], v[68:71], v[208:211], v[104:107]
	s_barrier
	s_add_i32 s28, 0, 0x1c000
	v_add_u32_e32 v132, s28, v206
	s_add_i32 s29, s59, s40
	ds_read_b128 v[212:215], v132
	ds_read_b128 v[216:219], v132 offset:1024
	ds_read_b128 v[220:223], v132 offset:2048
	s_mov_b32 m0, s29
	ds_read_b128 v[236:239], v132 offset:3072
	global_load_lds_dwordx4 v182, s[98:99]
	s_add_i32 m0, s29, 0x2000
	s_nop 0
	global_load_lds_dwordx4 v186, s[98:99]
	s_barrier
	s_waitcnt lgkmcnt(0)
	v_mfma_f32_16x16x32_bf16 v[72:75], v[220:223], v[116:119], v[72:75]
	v_mfma_f32_16x16x32_bf16 v[132:135], v[212:215], v[116:119], v[148:151]
	v_mfma_f32_16x16x32_bf16 v[144:147], v[236:239], v[128:131], v[72:75]
	v_mfma_f32_16x16x32_bf16 v[72:75], v[212:215], v[160:163], v[76:79]
	v_mfma_f32_16x16x32_bf16 v[148:151], v[216:219], v[128:131], v[132:135]
	v_mfma_f32_16x16x32_bf16 v[132:135], v[216:219], v[164:167], v[72:75]
	v_mfma_f32_16x16x32_bf16 v[72:75], v[220:223], v[160:163], v[80:83]
	v_mfma_f32_16x16x32_bf16 v[128:131], v[236:239], v[164:167], v[72:75]
	v_mfma_f32_16x16x32_bf16 v[72:75], v[212:215], v[192:195], v[84:87]
	v_mfma_f32_16x16x32_bf16 v[116:119], v[216:219], v[196:199], v[72:75]
	v_mfma_f32_16x16x32_bf16 v[72:75], v[220:223], v[192:195], v[112:115]
	v_mfma_f32_16x16x32_bf16 v[112:115], v[236:239], v[196:199], v[72:75]
	v_mfma_f32_16x16x32_bf16 v[72:75], v[212:215], v[200:203], v[100:103]
	v_mfma_f32_16x16x32_bf16 v[100:103], v[216:219], v[208:211], v[72:75]
	v_mfma_f32_16x16x32_bf16 v[72:75], v[220:223], v[200:203], v[96:99]
	v_mfma_f32_16x16x32_bf16 v[96:99], v[236:239], v[208:211], v[72:75]
	s_mov_b32 m0, s53
	s_barrier
	s_nop 2
	ds_read_b128 v[72:75], v207 offset:49152
	ds_read_b128 v[76:79], v207 offset:50176
	ds_read_b128 v[80:83], v207 offset:51200
	ds_read_b128 v[84:87], v207 offset:52224
	ds_read_b128 v[160:163], v207 offset:53248
	ds_read_b128 v[164:167], v207 offset:54272
	ds_read_b128 v[192:195], v207 offset:55296
	global_load_lds_dwordx4 v180, s[100:101]
	s_mov_b32 m0, s54
	ds_read_b128 v[196:199], v207 offset:56320
	global_load_lds_dwordx4 v184, s[100:101]
	s_barrier
	s_waitcnt lgkmcnt(0)
	v_mfma_f32_16x16x32_bf16 v[92:95], v[56:59], v[72:75], v[92:95]
	v_mfma_f32_16x16x32_bf16 v[88:91], v[64:67], v[72:75], v[88:91]
	v_mfma_f32_16x16x32_bf16 v[44:47], v[56:59], v[80:83], v[44:47]
	v_mfma_f32_16x16x32_bf16 v[40:43], v[64:67], v[80:83], v[40:43]
	v_mfma_f32_16x16x32_bf16 v[28:31], v[56:59], v[160:163], v[28:31]
	v_mfma_f32_16x16x32_bf16 v[24:27], v[64:67], v[160:163], v[24:27]
	v_mfma_f32_16x16x32_bf16 v[12:15], v[56:59], v[192:195], v[12:15]
	v_mfma_f32_16x16x32_bf16 v[8:11], v[64:67], v[192:195], v[8:11]
	v_mfma_f32_16x16x32_bf16 v[92:95], v[60:63], v[76:79], v[92:95]
	v_mfma_f32_16x16x32_bf16 v[88:91], v[68:71], v[76:79], v[88:91]
	v_mfma_f32_16x16x32_bf16 v[44:47], v[60:63], v[84:87], v[44:47]
	v_mfma_f32_16x16x32_bf16 v[40:43], v[68:71], v[84:87], v[40:43]
	v_mfma_f32_16x16x32_bf16 v[28:31], v[60:63], v[164:167], v[28:31]
	v_mfma_f32_16x16x32_bf16 v[24:27], v[68:71], v[164:167], v[24:27]
	v_mfma_f32_16x16x32_bf16 v[12:15], v[60:63], v[196:199], v[12:15]
	v_mfma_f32_16x16x32_bf16 v[8:11], v[68:71], v[196:199], v[8:11]
	s_barrier
	s_add_i32 s28, s28, s40
	s_mov_b32 m0, s28
	s_add_u32 s2, s2, 0x40080
	s_addc_u32 s3, s3, 0
	global_load_lds_dwordx4 v182, s[2:3]
	s_add_i32 m0, s28, 0x2000
	s_nop 0
	global_load_lds_dwordx4 v186, s[2:3]
	s_waitcnt vmcnt(6)
	s_barrier
	v_mfma_f32_16x16x32_bf16 v[48:51], v[212:215], v[72:75], v[48:51]
	v_mfma_f32_16x16x32_bf16 v[64:67], v[216:219], v[76:79], v[48:51]
	v_mfma_f32_16x16x32_bf16 v[48:51], v[220:223], v[72:75], v[52:55]
	v_mfma_f32_16x16x32_bf16 v[36:39], v[212:215], v[80:83], v[36:39]
	v_mfma_f32_16x16x32_bf16 v[32:35], v[220:223], v[80:83], v[32:35]
	v_mfma_f32_16x16x32_bf16 v[20:23], v[212:215], v[160:163], v[20:23]
	v_mfma_f32_16x16x32_bf16 v[16:19], v[220:223], v[160:163], v[16:19]
	v_mfma_f32_16x16x32_bf16 v[4:7], v[212:215], v[192:195], v[4:7]
	v_mfma_f32_16x16x32_bf16 v[0:3], v[220:223], v[192:195], v[0:3]
	v_mfma_f32_16x16x32_bf16 v[56:59], v[236:239], v[76:79], v[48:51]
	v_mfma_f32_16x16x32_bf16 v[36:39], v[216:219], v[84:87], v[36:39]
	v_mfma_f32_16x16x32_bf16 v[32:35], v[236:239], v[84:87], v[32:35]
	v_mfma_f32_16x16x32_bf16 v[20:23], v[216:219], v[164:167], v[20:23]
	v_mfma_f32_16x16x32_bf16 v[16:19], v[236:239], v[164:167], v[16:19]
	v_mfma_f32_16x16x32_bf16 v[4:7], v[216:219], v[196:199], v[4:7]
	v_mfma_f32_16x16x32_bf16 v[0:3], v[236:239], v[196:199], v[0:3]
	s_add_i32 s58, s58, 2
	s_add_u32 s8, s8, 0x100
	s_addc_u32 s9, s9, 0
	s_add_u32 s56, s56, 0x100
	s_addc_u32 s57, s57, 0
	s_cmp_gt_u32 s58, 13
	s_barrier
.LBB0_678:
	s_add_u32 s2, s8, 0xfffc0080
	s_addc_u32 s3, s9, -1
	s_add_i32 s59, 0, 0x10000
	v_add_u32_e32 v68, s59, v206
	ds_read_b128 v[48:51], v68
	ds_read_b128 v[52:55], v68 offset:1024
	ds_read_b128 v[60:63], v68 offset:2048
	ds_read_b128 v[68:71], v68 offset:3072
	s_cmp_eq_u32 s58, 12
	s_cselect_b32 s29, s1, s3
	s_cselect_b32 s28, s7, s2
	s_cselect_b32 s3, s21, s57
	s_cselect_b32 s2, s23, s56
	s_add_i32 m0, s41, 0xc000
	ds_read_b128 v[72:75], v207
	ds_read_b128 v[76:79], v207 offset:1024
	ds_read_b128 v[80:83], v207 offset:2048
	ds_read_b128 v[84:87], v207 offset:3072
	ds_read_b128 v[160:163], v207 offset:4096
	ds_read_b128 v[164:167], v207 offset:5120
	ds_read_b128 v[192:195], v207 offset:6144
	global_load_lds_dwordx4 v188, s[8:9]
	s_add_i32 m0, s41, 0xe000
	ds_read_b128 v[196:199], v207 offset:7168
	global_load_lds_dwordx4 v190, s[8:9]
	s_waitcnt lgkmcnt(8)
	s_barrier
	s_waitcnt lgkmcnt(0)
	v_mfma_f32_16x16x32_bf16 v[156:159], v[48:51], v[72:75], v[156:159]
	v_mfma_f32_16x16x32_bf16 v[152:155], v[60:63], v[72:75], v[152:155]
	v_mfma_f32_16x16x32_bf16 v[140:143], v[48:51], v[80:83], v[140:143]
	v_mfma_f32_16x16x32_bf16 v[136:139], v[60:63], v[80:83], v[136:139]
	v_mfma_f32_16x16x32_bf16 v[124:127], v[48:51], v[160:163], v[124:127]
	v_mfma_f32_16x16x32_bf16 v[120:123], v[60:63], v[160:163], v[120:123]
	v_mfma_f32_16x16x32_bf16 v[108:111], v[48:51], v[192:195], v[108:111]
	v_mfma_f32_16x16x32_bf16 v[104:107], v[60:63], v[192:195], v[104:107]
	v_mfma_f32_16x16x32_bf16 v[156:159], v[52:55], v[76:79], v[156:159]
	v_mfma_f32_16x16x32_bf16 v[152:155], v[68:71], v[76:79], v[152:155]
	v_mfma_f32_16x16x32_bf16 v[140:143], v[52:55], v[84:87], v[140:143]
	v_mfma_f32_16x16x32_bf16 v[136:139], v[68:71], v[84:87], v[136:139]
	v_mfma_f32_16x16x32_bf16 v[124:127], v[52:55], v[164:167], v[124:127]
	v_mfma_f32_16x16x32_bf16 v[120:123], v[68:71], v[164:167], v[120:123]
	v_mfma_f32_16x16x32_bf16 v[108:111], v[52:55], v[196:199], v[108:111]
	v_mfma_f32_16x16x32_bf16 v[104:107], v[68:71], v[196:199], v[104:107]
	s_barrier
	s_add_i32 s62, 0, 0x14000
	s_add_i32 s59, s59, s40
	v_add_u32_e32 v168, s62, v206
	s_add_u32 s98, s2, 0x80
	s_addc_u32 s99, s3, 0
	s_mov_b32 m0, s59
	ds_read_b128 v[200:203], v168
	ds_read_b128 v[208:211], v168 offset:1024
	ds_read_b128 v[212:215], v168 offset:2048
	global_load_lds_dwordx4 v182, s[2:3]
	s_add_i32 m0, s59, 0x2000
	ds_read_b128 v[216:219], v168 offset:3072
	global_load_lds_dwordx4 v186, s[2:3]
	s_barrier
	s_waitcnt lgkmcnt(0)
	v_mfma_f32_16x16x32_bf16 v[148:151], v[200:203], v[72:75], v[148:151]
	v_mfma_f32_16x16x32_bf16 v[72:75], v[212:215], v[72:75], v[144:147]
	v_mfma_f32_16x16x32_bf16 v[148:151], v[208:211], v[76:79], v[148:151]
	v_mfma_f32_16x16x32_bf16 v[72:75], v[216:219], v[76:79], v[72:75]
	v_mfma_f32_16x16x32_bf16 v[76:79], v[200:203], v[80:83], v[132:135]
	v_mfma_f32_16x16x32_bf16 v[80:83], v[212:215], v[80:83], v[128:131]
	v_mfma_f32_16x16x32_bf16 v[112:115], v[212:215], v[160:163], v[112:115]
	v_mfma_f32_16x16x32_bf16 v[100:103], v[200:203], v[192:195], v[100:103]
	v_mfma_f32_16x16x32_bf16 v[96:99], v[212:215], v[192:195], v[96:99]
	v_mfma_f32_16x16x32_bf16 v[76:79], v[208:211], v[84:87], v[76:79]
	v_mfma_f32_16x16x32_bf16 v[80:83], v[216:219], v[84:87], v[80:83]
	v_mfma_f32_16x16x32_bf16 v[84:87], v[200:203], v[160:163], v[116:119]
	v_mfma_f32_16x16x32_bf16 v[112:115], v[216:219], v[164:167], v[112:115]
	v_mfma_f32_16x16x32_bf16 v[100:103], v[208:211], v[196:199], v[100:103]
	v_mfma_f32_16x16x32_bf16 v[96:99], v[216:219], v[196:199], v[96:99]
	v_mfma_f32_16x16x32_bf16 v[84:87], v[208:211], v[164:167], v[84:87]
	s_mov_b32 m0, s41
	s_add_u32 s100, s28, 0x80
	s_addc_u32 s101, s29, 0
	s_barrier
	ds_read_b128 v[116:119], v207 offset:16384
	ds_read_b128 v[128:131], v207 offset:17408
	ds_read_b128 v[132:135], v207 offset:18432
	ds_read_b128 v[144:147], v207 offset:19456
	ds_read_b128 v[160:163], v207 offset:20480
	ds_read_b128 v[164:167], v207 offset:21504
	ds_read_b128 v[192:195], v207 offset:22528
	global_load_lds_dwordx4 v180, s[28:29]
	s_mov_b32 m0, s42
	ds_read_b128 v[196:199], v207 offset:23552
	global_load_lds_dwordx4 v184, s[28:29]
	s_barrier
	s_waitcnt lgkmcnt(0)
	v_mfma_f32_16x16x32_bf16 v[92:95], v[48:51], v[116:119], v[92:95]
	v_mfma_f32_16x16x32_bf16 v[88:91], v[60:63], v[116:119], v[88:91]
	v_mfma_f32_16x16x32_bf16 v[44:47], v[48:51], v[132:135], v[44:47]
	v_mfma_f32_16x16x32_bf16 v[40:43], v[60:63], v[132:135], v[40:43]
	v_mfma_f32_16x16x32_bf16 v[28:31], v[48:51], v[160:163], v[28:31]
	v_mfma_f32_16x16x32_bf16 v[24:27], v[60:63], v[160:163], v[24:27]
	v_mfma_f32_16x16x32_bf16 v[12:15], v[48:51], v[192:195], v[12:15]
	v_mfma_f32_16x16x32_bf16 v[8:11], v[60:63], v[192:195], v[8:11]
	v_mfma_f32_16x16x32_bf16 v[92:95], v[52:55], v[128:131], v[92:95]
	v_mfma_f32_16x16x32_bf16 v[88:91], v[68:71], v[128:131], v[88:91]
	v_mfma_f32_16x16x32_bf16 v[44:47], v[52:55], v[144:147], v[44:47]
	v_mfma_f32_16x16x32_bf16 v[40:43], v[68:71], v[144:147], v[40:43]
	v_mfma_f32_16x16x32_bf16 v[28:31], v[52:55], v[164:167], v[28:31]
	v_mfma_f32_16x16x32_bf16 v[24:27], v[68:71], v[164:167], v[24:27]
	v_mfma_f32_16x16x32_bf16 v[12:15], v[52:55], v[196:199], v[12:15]
	v_mfma_f32_16x16x32_bf16 v[8:11], v[68:71], v[196:199], v[8:11]
	s_barrier
	s_add_i32 s59, s62, s40
	s_mov_b32 m0, s59
	s_add_u32 s60, s2, 0x40000
	s_addc_u32 s61, s3, 0
	global_load_lds_dwordx4 v182, s[60:61]
	s_add_i32 m0, s59, 0x2000
	s_nop 0
	global_load_lds_dwordx4 v186, s[60:61]
	s_waitcnt vmcnt(6)
	s_barrier
	v_mfma_f32_16x16x32_bf16 v[36:39], v[200:203], v[132:135], v[36:39]
	v_mfma_f32_16x16x32_bf16 v[32:35], v[212:215], v[132:135], v[32:35]
	v_mfma_f32_16x16x32_bf16 v[20:23], v[200:203], v[160:163], v[20:23]
	v_mfma_f32_16x16x32_bf16 v[16:19], v[212:215], v[160:163], v[16:19]
	v_mfma_f32_16x16x32_bf16 v[4:7], v[200:203], v[192:195], v[4:7]
	v_mfma_f32_16x16x32_bf16 v[0:3], v[212:215], v[192:195], v[0:3]
	v_mfma_f32_16x16x32_bf16 v[48:51], v[200:203], v[116:119], v[64:67]
	v_mfma_f32_16x16x32_bf16 v[52:55], v[212:215], v[116:119], v[56:59]
	v_mfma_f32_16x16x32_bf16 v[36:39], v[208:211], v[144:147], v[36:39]
	v_mfma_f32_16x16x32_bf16 v[32:35], v[216:219], v[144:147], v[32:35]
	v_mfma_f32_16x16x32_bf16 v[20:23], v[208:211], v[164:167], v[20:23]
	v_mfma_f32_16x16x32_bf16 v[16:19], v[216:219], v[164:167], v[16:19]
	v_mfma_f32_16x16x32_bf16 v[4:7], v[208:211], v[196:199], v[4:7]
	v_mfma_f32_16x16x32_bf16 v[0:3], v[216:219], v[196:199], v[0:3]
	v_mfma_f32_16x16x32_bf16 v[48:51], v[208:211], v[128:131], v[48:51]
	v_mfma_f32_16x16x32_bf16 v[52:55], v[216:219], v[128:131], v[52:55]
	s_add_i32 s59, 0, 0x18000
	v_add_u32_e32 v68, s59, v206
	s_barrier
	ds_read_b128 v[56:59], v68
	ds_read_b128 v[60:63], v68 offset:1024
	ds_read_b128 v[64:67], v68 offset:2048
	ds_read_b128 v[68:71], v68 offset:3072
	s_add_u32 s28, s28, 0x40000
	s_addc_u32 s29, s29, 0
	s_mov_b32 m0, s43
	ds_read_b128 v[116:119], v207 offset:32768
	ds_read_b128 v[128:131], v207 offset:33792
	ds_read_b128 v[160:163], v207 offset:34816
	ds_read_b128 v[164:167], v207 offset:35840
	ds_read_b128 v[192:195], v207 offset:36864
	ds_read_b128 v[196:199], v207 offset:37888
	ds_read_b128 v[200:203], v207 offset:38912
	global_load_lds_dwordx4 v180, s[28:29]
	s_mov_b32 m0, s44
	ds_read_b128 v[208:211], v207 offset:39936
	global_load_lds_dwordx4 v184, s[28:29]
	s_waitcnt lgkmcnt(8)
	s_barrier
	s_waitcnt lgkmcnt(0)
	v_mfma_f32_16x16x32_bf16 v[132:135], v[56:59], v[116:119], v[156:159]
	v_mfma_f32_16x16x32_bf16 v[156:159], v[60:63], v[128:131], v[132:135]
	v_mfma_f32_16x16x32_bf16 v[132:135], v[64:67], v[116:119], v[152:155]
	v_mfma_f32_16x16x32_bf16 v[152:155], v[68:71], v[128:131], v[132:135]
	v_mfma_f32_16x16x32_bf16 v[132:135], v[56:59], v[160:163], v[140:143]
	v_mfma_f32_16x16x32_bf16 v[140:143], v[60:63], v[164:167], v[132:135]
	v_mfma_f32_16x16x32_bf16 v[132:135], v[64:67], v[160:163], v[136:139]
	v_mfma_f32_16x16x32_bf16 v[124:127], v[56:59], v[192:195], v[124:127]
	v_mfma_f32_16x16x32_bf16 v[120:123], v[64:67], v[192:195], v[120:123]
	v_mfma_f32_16x16x32_bf16 v[108:111], v[56:59], v[200:203], v[108:111]
	v_mfma_f32_16x16x32_bf16 v[104:107], v[64:67], v[200:203], v[104:107]
	v_mfma_f32_16x16x32_bf16 v[136:139], v[68:71], v[164:167], v[132:135]
	v_mfma_f32_16x16x32_bf16 v[124:127], v[60:63], v[196:199], v[124:127]
	v_mfma_f32_16x16x32_bf16 v[120:123], v[68:71], v[196:199], v[120:123]
	v_mfma_f32_16x16x32_bf16 v[108:111], v[60:63], v[208:211], v[108:111]
	v_mfma_f32_16x16x32_bf16 v[104:107], v[68:71], v[208:211], v[104:107]
	s_barrier
	s_add_i32 s28, 0, 0x1c000
	v_add_u32_e32 v132, s28, v206
	s_add_i32 s29, s59, s40
	ds_read_b128 v[212:215], v132
	ds_read_b128 v[216:219], v132 offset:1024
	ds_read_b128 v[220:223], v132 offset:2048
	s_mov_b32 m0, s29
	ds_read_b128 v[236:239], v132 offset:3072
	global_load_lds_dwordx4 v182, s[98:99]
	s_add_i32 m0, s29, 0x2000
	s_nop 0
	global_load_lds_dwordx4 v186, s[98:99]
	s_barrier
	s_waitcnt lgkmcnt(0)
	v_mfma_f32_16x16x32_bf16 v[72:75], v[220:223], v[116:119], v[72:75]
	v_mfma_f32_16x16x32_bf16 v[132:135], v[212:215], v[116:119], v[148:151]
	v_mfma_f32_16x16x32_bf16 v[144:147], v[236:239], v[128:131], v[72:75]
	v_mfma_f32_16x16x32_bf16 v[72:75], v[212:215], v[160:163], v[76:79]
	v_mfma_f32_16x16x32_bf16 v[148:151], v[216:219], v[128:131], v[132:135]
	v_mfma_f32_16x16x32_bf16 v[132:135], v[216:219], v[164:167], v[72:75]
	v_mfma_f32_16x16x32_bf16 v[72:75], v[220:223], v[160:163], v[80:83]
	v_mfma_f32_16x16x32_bf16 v[128:131], v[236:239], v[164:167], v[72:75]
	v_mfma_f32_16x16x32_bf16 v[72:75], v[212:215], v[192:195], v[84:87]
	v_mfma_f32_16x16x32_bf16 v[116:119], v[216:219], v[196:199], v[72:75]
	v_mfma_f32_16x16x32_bf16 v[72:75], v[220:223], v[192:195], v[112:115]
	v_mfma_f32_16x16x32_bf16 v[112:115], v[236:239], v[196:199], v[72:75]
	v_mfma_f32_16x16x32_bf16 v[72:75], v[212:215], v[200:203], v[100:103]
	v_mfma_f32_16x16x32_bf16 v[100:103], v[216:219], v[208:211], v[72:75]
	v_mfma_f32_16x16x32_bf16 v[72:75], v[220:223], v[200:203], v[96:99]
	v_mfma_f32_16x16x32_bf16 v[96:99], v[236:239], v[208:211], v[72:75]
	s_mov_b32 m0, s53
	s_barrier
	s_nop 2
	ds_read_b128 v[72:75], v207 offset:49152
	ds_read_b128 v[76:79], v207 offset:50176
	ds_read_b128 v[80:83], v207 offset:51200
	ds_read_b128 v[84:87], v207 offset:52224
	ds_read_b128 v[160:163], v207 offset:53248
	ds_read_b128 v[164:167], v207 offset:54272
	ds_read_b128 v[192:195], v207 offset:55296
	global_load_lds_dwordx4 v180, s[100:101]
	s_mov_b32 m0, s54
	ds_read_b128 v[196:199], v207 offset:56320
	global_load_lds_dwordx4 v184, s[100:101]
	s_barrier
	s_waitcnt lgkmcnt(0)
	v_mfma_f32_16x16x32_bf16 v[92:95], v[56:59], v[72:75], v[92:95]
	v_mfma_f32_16x16x32_bf16 v[88:91], v[64:67], v[72:75], v[88:91]
	v_mfma_f32_16x16x32_bf16 v[44:47], v[56:59], v[80:83], v[44:47]
	v_mfma_f32_16x16x32_bf16 v[40:43], v[64:67], v[80:83], v[40:43]
	v_mfma_f32_16x16x32_bf16 v[28:31], v[56:59], v[160:163], v[28:31]
	v_mfma_f32_16x16x32_bf16 v[24:27], v[64:67], v[160:163], v[24:27]
	v_mfma_f32_16x16x32_bf16 v[12:15], v[56:59], v[192:195], v[12:15]
	v_mfma_f32_16x16x32_bf16 v[8:11], v[64:67], v[192:195], v[8:11]
	v_mfma_f32_16x16x32_bf16 v[92:95], v[60:63], v[76:79], v[92:95]
	v_mfma_f32_16x16x32_bf16 v[88:91], v[68:71], v[76:79], v[88:91]
	v_mfma_f32_16x16x32_bf16 v[44:47], v[60:63], v[84:87], v[44:47]
	v_mfma_f32_16x16x32_bf16 v[40:43], v[68:71], v[84:87], v[40:43]
	v_mfma_f32_16x16x32_bf16 v[28:31], v[60:63], v[164:167], v[28:31]
	v_mfma_f32_16x16x32_bf16 v[24:27], v[68:71], v[164:167], v[24:27]
	v_mfma_f32_16x16x32_bf16 v[12:15], v[60:63], v[196:199], v[12:15]
	v_mfma_f32_16x16x32_bf16 v[8:11], v[68:71], v[196:199], v[8:11]
	s_barrier
	s_add_i32 s28, s28, s40
	s_mov_b32 m0, s28
	s_add_u32 s2, s2, 0x40080
	s_addc_u32 s3, s3, 0
	global_load_lds_dwordx4 v182, s[2:3]
	s_add_i32 m0, s28, 0x2000
	s_nop 0
	global_load_lds_dwordx4 v186, s[2:3]
	s_waitcnt vmcnt(6)
	s_barrier
	v_mfma_f32_16x16x32_bf16 v[48:51], v[212:215], v[72:75], v[48:51]
	v_mfma_f32_16x16x32_bf16 v[64:67], v[216:219], v[76:79], v[48:51]
	v_mfma_f32_16x16x32_bf16 v[48:51], v[220:223], v[72:75], v[52:55]
	v_mfma_f32_16x16x32_bf16 v[36:39], v[212:215], v[80:83], v[36:39]
	v_mfma_f32_16x16x32_bf16 v[32:35], v[220:223], v[80:83], v[32:35]
	v_mfma_f32_16x16x32_bf16 v[20:23], v[212:215], v[160:163], v[20:23]
	v_mfma_f32_16x16x32_bf16 v[16:19], v[220:223], v[160:163], v[16:19]
	v_mfma_f32_16x16x32_bf16 v[4:7], v[212:215], v[192:195], v[4:7]
	v_mfma_f32_16x16x32_bf16 v[0:3], v[220:223], v[192:195], v[0:3]
	v_mfma_f32_16x16x32_bf16 v[56:59], v[236:239], v[76:79], v[48:51]
	v_mfma_f32_16x16x32_bf16 v[36:39], v[216:219], v[84:87], v[36:39]
	v_mfma_f32_16x16x32_bf16 v[32:35], v[236:239], v[84:87], v[32:35]
	v_mfma_f32_16x16x32_bf16 v[20:23], v[216:219], v[164:167], v[20:23]
	v_mfma_f32_16x16x32_bf16 v[16:19], v[236:239], v[164:167], v[16:19]
	v_mfma_f32_16x16x32_bf16 v[4:7], v[216:219], v[196:199], v[4:7]
	v_mfma_f32_16x16x32_bf16 v[0:3], v[236:239], v[196:199], v[0:3]
	s_add_i32 s58, s58, 2
	s_add_u32 s8, s8, 0x100
	s_addc_u32 s9, s9, 0
	s_add_u32 s56, s56, 0x100
	s_addc_u32 s57, s57, 0
	s_cmp_gt_u32 s58, 13
	s_barrier
	s_cbranch_scc0 .LBB0_678
	s_lshl_b32 s1, s0, 8
	s_add_i32 s2, s1, s51
	s_lshl_b32 s1, s6, 8
	v_mov_b32_e32 v160, v205
	v_mov_b32_e32 v208, v204
	s_or_b32 s1, s1, s52
	s_nop 0
	v_lshl_add_u32 v192, v208, 3, s1
	s_add_i32 s1, s0, -16
	s_lshr_b32 s1, s1, 3
	s_add_i32 s1, s1, 1
	s_cmp_gt_i32 s0, 15
	s_cselect_b32 s3, s1, 0
	s_mul_i32 s96, s3, 0x1800
	s_lshl_b64 s[0:1], s[96:97], 2
	s_add_u32 s0, s45, s0
	v_ashrrev_i32_e32 v193, 31, v192
	s_addc_u32 s1, s46, s1
	v_lshlrev_b64 v[196:197], 2, v[192:193]
	s_lshl_b32 s96, s3, 10
	v_lshl_add_u64 v[48:49], s[0:1], 0, v[196:197]
	s_lshl_b64 s[0:1], s[96:97], 2
	s_add_u32 s0, s49, s0
	s_addc_u32 s1, s50, s1
	v_lshl_add_u64 v[52:53], s[0:1], 0, v[196:197]
	global_load_dwordx4 v[80:83], v[48:49], off offset:16
	global_load_dwordx4 v[84:87], v[48:49], off
	global_load_dwordx4 v[72:75], v[52:53], off offset:16
	global_load_dwordx4 v[76:79], v[52:53], off
	global_load_dwordx4 v[60:63], v[48:49], off offset:528
	global_load_dwordx4 v[68:71], v[48:49], off offset:512
	s_nop 0
	global_load_dwordx4 v[48:51], v[52:53], off offset:528
	s_nop 0
	global_load_dwordx4 v[52:55], v[52:53], off offset:512
	v_add_u32_e32 v194, s2, v160
	v_ashrrev_i32_e32 v195, 31, v194
	v_lshlrev_b64 v[160:161], 10, v[194:195]
	v_lshl_add_u64 v[198:199], v[160:161], 0, v[192:193]
	v_cndmask_b32_e64 v160, 0, 1, s[74:75]
	v_cmp_gt_i32_e64 s[0:1], s71, v194
	v_cmp_ne_u32_e64 s[6:7], 1, v160
	s_andn2_b64 vcc, exec, s[74:75]
	s_mov_b64 s[2:3], -1
	s_cbranch_vccnz .LBB0_681
	v_lshl_add_u64 v[160:161], v[198:199], 1, s[14:15]
	v_mov_b32_e32 v222, v160
	v_mov_b32_e32 v223, v161
	global_load_dwordx4 v[210:213], v[222:223], off
	global_load_dwordx4 v[214:217], v[222:223], off offset:256
	s_mov_b64 s[80:81], 0x8000
	v_lshl_add_u64 v[222:223], v[222:223], 0, s[80:81]
	global_load_dwordx4 v[218:221], v[222:223], off
	global_load_dwordx4 v[236:239], v[222:223], off offset:256
	s_mov_b64 s[2:3], 0
	s_waitcnt vmcnt(3)
	v_lshlrev_b32_e32 v164, 16, v210
	v_and_b32_e32 v165, 0xffff0000, v210
	v_lshlrev_b32_e32 v166, 16, v211
	v_and_b32_e32 v167, 0xffff0000, v211
	v_lshlrev_b32_e32 v160, 16, v212
	v_and_b32_e32 v161, 0xffff0000, v212
	v_lshlrev_b32_e32 v162, 16, v213
	v_and_b32_e32 v163, 0xffff0000, v213
	s_mov_b64 s[80:81], 0x8000
	v_lshl_add_u64 v[222:223], v[222:223], 0, s[80:81]
	global_load_dwordx4 v[210:213], v[222:223], off

.LBB0_879:
	s_ashr_i32 s39, s38, 31
	v_cmp_lt_i64_e32 vcc, s[12:13], v[178:179]
	s_lshl_b64 s[12:13], s[38:39], 19
	s_add_u32 s40, s49, s12
	s_addc_u32 s41, s50, s13
	s_lshl_b32 s84, s82, 18
	s_add_u32 s40, s40, s84
	s_addc_u32 s41, s41, 0
	s_and_b64 s[12:13], vcc, exec
	s_cselect_b32 s1, s41, s11
	s_cselect_b32 s9, s40, s10
	s_ashr_i32 s37, s36, 31
	s_lshl_b64 s[12:13], s[36:37], 19
	s_add_u32 s42, s51, s12
	s_addc_u32 s43, s52, s13
	s_and_b64 s[12:13], vcc, exec
	s_cselect_b32 s14, s43, s3
	s_cselect_b32 s15, s42, s2
	s_add_u32 s10, s10, 0x40080
	s_addc_u32 s11, s11, 0
	s_add_u32 s37, s2, 0x100
	s_addc_u32 s39, s3, 0
	s_mov_b32 s67, -2
	s_cmp_lg_u32 s83, 0
	s_cbranch_scc1 .Lup_half_peel
	s_add_u32 s2, s10, 0xfffc0080
	s_addc_u32 s3, s11, -1
	s_add_i32 s68, 0, 0x10000
	v_add_u32_e32 v108, s68, v237
	ds_read_b128 v[48:51], v108
	ds_read_b128 v[52:55], v108 offset:1024
	ds_read_b128 v[104:107], v108 offset:2048
	ds_read_b128 v[108:111], v108 offset:3072
	s_cmp_eq_u32 s67, 12
	s_cselect_b32 s13, s1, s3
	s_cselect_b32 s12, s9, s2
	s_cselect_b32 s3, s14, s39
	s_cselect_b32 s2, s15, s37
	s_add_i32 m0, s54, 0xc000
	ds_read_b128 v[112:115], v238
	ds_read_b128 v[116:119], v238 offset:1024
	ds_read_b128 v[120:123], v238 offset:2048
	ds_read_b128 v[156:159], v238 offset:3072
	ds_read_b128 v[160:163], v238 offset:4096
	ds_read_b128 v[164:167], v238 offset:5120
	ds_read_b128 v[190:193], v238 offset:6144
	global_load_lds_dwordx4 v186, s[10:11]
	s_add_i32 m0, s54, 0xe000
	ds_read_b128 v[194:197], v238 offset:7168
	global_load_lds_dwordx4 v188, s[10:11]
	s_waitcnt lgkmcnt(8)
	s_barrier
	s_waitcnt lgkmcnt(0)
	v_mfma_f32_16x16x32_bf16 v[152:155], v[48:51], v[112:115], 0
	v_mfma_f32_16x16x32_bf16 v[68:71], v[104:107], v[112:115], 0
	v_mfma_f32_16x16x32_bf16 v[148:151], v[48:51], v[120:123], 0
	v_mfma_f32_16x16x32_bf16 v[64:67], v[104:107], v[120:123], 0
	v_mfma_f32_16x16x32_bf16 v[136:139], v[48:51], v[160:163], 0
	v_mfma_f32_16x16x32_bf16 v[44:47], v[104:107], v[160:163], 0
	v_mfma_f32_16x16x32_bf16 v[128:131], v[48:51], v[190:193], 0
	v_mfma_f32_16x16x32_bf16 v[40:43], v[104:107], v[190:193], 0
	v_mfma_f32_16x16x32_bf16 v[152:155], v[52:55], v[116:119], v[152:155]
	v_mfma_f32_16x16x32_bf16 v[68:71], v[108:111], v[116:119], v[68:71]
	v_mfma_f32_16x16x32_bf16 v[148:151], v[52:55], v[156:159], v[148:151]
	v_mfma_f32_16x16x32_bf16 v[64:67], v[108:111], v[156:159], v[64:67]
	v_mfma_f32_16x16x32_bf16 v[136:139], v[52:55], v[164:167], v[136:139]
	v_mfma_f32_16x16x32_bf16 v[44:47], v[108:111], v[164:167], v[44:47]
	v_mfma_f32_16x16x32_bf16 v[128:131], v[52:55], v[194:197], v[128:131]
	v_mfma_f32_16x16x32_bf16 v[40:43], v[108:111], v[194:197], v[40:43]
	s_barrier
	s_add_i32 s70, 0, 0x14000
	s_add_i32 s68, s68, s53
	v_add_u32_e32 v210, s70, v237
	s_add_u32 s98, s2, 0x80
	s_addc_u32 s99, s3, 0
	s_mov_b32 m0, s68
	ds_read_b128 v[198:201], v210
	ds_read_b128 v[202:205], v210 offset:1024
	ds_read_b128 v[206:209], v210 offset:2048
	global_load_lds_dwordx4 v168, s[2:3]
	s_add_i32 m0, s68, 0x2000
	ds_read_b128 v[210:213], v210 offset:3072
	global_load_lds_dwordx4 v184, s[2:3]
	s_barrier
	s_waitcnt lgkmcnt(0)
	v_mfma_f32_16x16x32_bf16 v[144:147], v[198:201], v[112:115], 0
	v_mfma_f32_16x16x32_bf16 v[60:63], v[206:209], v[112:115], 0
	v_mfma_f32_16x16x32_bf16 v[56:59], v[206:209], v[120:123], 0
	v_mfma_f32_16x16x32_bf16 v[36:39], v[206:209], v[160:163], 0
	v_mfma_f32_16x16x32_bf16 v[32:35], v[206:209], v[190:193], 0
	v_mfma_f32_16x16x32_bf16 v[144:147], v[202:205], v[116:119], v[144:147]
	v_mfma_f32_16x16x32_bf16 v[60:63], v[210:213], v[116:119], v[60:63]
	v_mfma_f32_16x16x32_bf16 v[112:115], v[198:201], v[120:123], 0
	v_mfma_f32_16x16x32_bf16 v[56:59], v[210:213], v[156:159], v[56:59]
	v_mfma_f32_16x16x32_bf16 v[116:119], v[198:201], v[160:163], 0
	v_mfma_f32_16x16x32_bf16 v[36:39], v[210:213], v[164:167], v[36:39]
	v_mfma_f32_16x16x32_bf16 v[120:123], v[198:201], v[190:193], 0
	v_mfma_f32_16x16x32_bf16 v[32:35], v[210:213], v[194:197], v[32:35]
	v_mfma_f32_16x16x32_bf16 v[112:115], v[202:205], v[156:159], v[112:115]
	v_mfma_f32_16x16x32_bf16 v[116:119], v[202:205], v[164:167], v[116:119]
	v_mfma_f32_16x16x32_bf16 v[120:123], v[202:205], v[194:197], v[120:123]
	s_mov_b32 m0, s54
	s_add_u32 s100, s12, 0x80
	s_addc_u32 s101, s13, 0
	s_barrier
	ds_read_b128 v[124:127], v238 offset:16384
	ds_read_b128 v[132:135], v238 offset:17408
	ds_read_b128 v[140:143], v238 offset:18432
	ds_read_b128 v[156:159], v238 offset:19456
	ds_read_b128 v[160:163], v238 offset:20480
	ds_read_b128 v[164:167], v238 offset:21504
	ds_read_b128 v[190:193], v238 offset:22528
	global_load_lds_dwordx4 v180, s[12:13]
	s_mov_b32 m0, s55
	ds_read_b128 v[194:197], v238 offset:23552
	global_load_lds_dwordx4 v182, s[12:13]
	s_barrier
	s_waitcnt lgkmcnt(0)
	v_mfma_f32_16x16x32_bf16 v[100:103], v[48:51], v[124:127], 0
	v_mfma_f32_16x16x32_bf16 v[28:31], v[104:107], v[124:127], 0
	v_mfma_f32_16x16x32_bf16 v[96:99], v[48:51], v[140:143], 0
	v_mfma_f32_16x16x32_bf16 v[24:27], v[104:107], v[140:143], 0
	v_mfma_f32_16x16x32_bf16 v[84:87], v[48:51], v[160:163], 0
	v_mfma_f32_16x16x32_bf16 v[12:15], v[104:107], v[160:163], 0
	v_mfma_f32_16x16x32_bf16 v[8:11], v[104:107], v[190:193], 0
	v_mfma_f32_16x16x32_bf16 v[100:103], v[52:55], v[132:135], v[100:103]
	v_mfma_f32_16x16x32_bf16 v[28:31], v[108:111], v[132:135], v[28:31]
	v_mfma_f32_16x16x32_bf16 v[96:99], v[52:55], v[156:159], v[96:99]
	v_mfma_f32_16x16x32_bf16 v[24:27], v[108:111], v[156:159], v[24:27]
	v_mfma_f32_16x16x32_bf16 v[84:87], v[52:55], v[164:167], v[84:87]
	v_mfma_f32_16x16x32_bf16 v[12:15], v[108:111], v[164:167], v[12:15]
	v_mfma_f32_16x16x32_bf16 v[48:51], v[48:51], v[190:193], 0
	v_mfma_f32_16x16x32_bf16 v[8:11], v[108:111], v[194:197], v[8:11]
	v_mfma_f32_16x16x32_bf16 v[48:51], v[52:55], v[194:197], v[48:51]
	s_barrier
	s_add_i32 s70, s70, s53
	s_mov_b32 m0, s70
	s_add_u32 s68, s2, 0x40000
	s_addc_u32 s69, s3, 0
	global_load_lds_dwordx4 v168, s[68:69]
	s_add_i32 m0, s70, 0x2000
	s_nop 0
	global_load_lds_dwordx4 v184, s[68:69]
	s_waitcnt vmcnt(6)
	s_barrier
	v_mfma_f32_16x16x32_bf16 v[76:79], v[198:201], v[140:143], 0
	v_mfma_f32_16x16x32_bf16 v[20:23], v[206:209], v[124:127], 0
	v_mfma_f32_16x16x32_bf16 v[88:91], v[202:205], v[156:159], v[76:79]
	v_mfma_f32_16x16x32_bf16 v[16:19], v[206:209], v[140:143], 0
	v_mfma_f32_16x16x32_bf16 v[76:79], v[198:201], v[160:163], 0
	v_mfma_f32_16x16x32_bf16 v[4:7], v[206:209], v[160:163], 0
	v_mfma_f32_16x16x32_bf16 v[72:75], v[198:201], v[190:193], 0
	v_mfma_f32_16x16x32_bf16 v[0:3], v[206:209], v[190:193], 0
	v_mfma_f32_16x16x32_bf16 v[52:55], v[198:201], v[124:127], 0
	v_mfma_f32_16x16x32_bf16 v[20:23], v[210:213], v[132:135], v[20:23]
	v_mfma_f32_16x16x32_bf16 v[16:19], v[210:213], v[156:159], v[16:19]
	v_mfma_f32_16x16x32_bf16 v[80:83], v[202:205], v[164:167], v[76:79]
	v_mfma_f32_16x16x32_bf16 v[4:7], v[210:213], v[164:167], v[4:7]
	v_mfma_f32_16x16x32_bf16 v[72:75], v[202:205], v[194:197], v[72:75]
	v_mfma_f32_16x16x32_bf16 v[0:3], v[210:213], v[194:197], v[0:3]
	v_mfma_f32_16x16x32_bf16 v[52:55], v[202:205], v[132:135], v[52:55]
	s_add_i32 s68, 0, 0x18000
	v_add_u32_e32 v108, s68, v237
	s_barrier
	ds_read_b128 v[76:79], v108
	ds_read_b128 v[92:95], v108 offset:1024
	ds_read_b128 v[104:107], v108 offset:2048
	ds_read_b128 v[108:111], v108 offset:3072
	s_add_u32 s12, s12, 0x40000
	s_addc_u32 s13, s13, 0
	s_mov_b32 m0, s56
	ds_read_b128 v[124:127], v238 offset:32768
	ds_read_b128 v[132:135], v238 offset:33792
	ds_read_b128 v[156:159], v238 offset:34816
	ds_read_b128 v[160:163], v238 offset:35840
	ds_read_b128 v[164:167], v238 offset:36864
	ds_read_b128 v[190:193], v238 offset:37888
	ds_read_b128 v[194:197], v238 offset:38912
	global_load_lds_dwordx4 v180, s[12:13]
	s_mov_b32 m0, s57
	ds_read_b128 v[198:201], v238 offset:39936
	global_load_lds_dwordx4 v182, s[12:13]
	s_waitcnt lgkmcnt(8)
	s_barrier
	s_waitcnt lgkmcnt(0)
	v_mfma_f32_16x16x32_bf16 v[140:143], v[76:79], v[124:127], v[152:155]
	v_mfma_f32_16x16x32_bf16 v[152:155], v[92:95], v[132:135], v[140:143]
	v_mfma_f32_16x16x32_bf16 v[68:71], v[104:107], v[124:127], v[68:71]
	v_mfma_f32_16x16x32_bf16 v[140:143], v[76:79], v[156:159], v[148:151]
	v_mfma_f32_16x16x32_bf16 v[64:67], v[104:107], v[156:159], v[64:67]
	v_mfma_f32_16x16x32_bf16 v[136:139], v[76:79], v[164:167], v[136:139]
	v_mfma_f32_16x16x32_bf16 v[44:47], v[104:107], v[164:167], v[44:47]
	v_mfma_f32_16x16x32_bf16 v[128:131], v[76:79], v[194:197], v[128:131]
	v_mfma_f32_16x16x32_bf16 v[40:43], v[104:107], v[194:197], v[40:43]
	v_mfma_f32_16x16x32_bf16 v[68:71], v[108:111], v[132:135], v[68:71]
	v_mfma_f32_16x16x32_bf16 v[148:151], v[92:95], v[160:163], v[140:143]
	v_mfma_f32_16x16x32_bf16 v[64:67], v[108:111], v[160:163], v[64:67]
	v_mfma_f32_16x16x32_bf16 v[136:139], v[92:95], v[190:193], v[136:139]
	v_mfma_f32_16x16x32_bf16 v[44:47], v[108:111], v[190:193], v[44:47]
	v_mfma_f32_16x16x32_bf16 v[128:131], v[92:95], v[198:201], v[128:131]
	v_mfma_f32_16x16x32_bf16 v[40:43], v[108:111], v[198:201], v[40:43]
	s_barrier
	s_add_i32 s12, 0, 0x1c000
	v_add_u32_e32 v140, s12, v237
	s_add_i32 s13, s68, s53
	ds_read_b128 v[202:205], v140
	ds_read_b128 v[206:209], v140 offset:1024
	ds_read_b128 v[210:213], v140 offset:2048
	s_mov_b32 m0, s13
	ds_read_b128 v[214:217], v140 offset:3072
	global_load_lds_dwordx4 v168, s[98:99]
	s_add_i32 m0, s13, 0x2000
	s_nop 0
	global_load_lds_dwordx4 v184, s[98:99]
	s_barrier
	s_waitcnt lgkmcnt(0)
	v_mfma_f32_16x16x32_bf16 v[140:143], v[202:205], v[124:127], v[144:147]
	v_mfma_f32_16x16x32_bf16 v[112:115], v[202:205], v[156:159], v[112:115]
	v_mfma_f32_16x16x32_bf16 v[144:147], v[206:209], v[132:135], v[140:143]
	v_mfma_f32_16x16x32_bf16 v[60:63], v[210:213], v[124:127], v[60:63]
	v_mfma_f32_16x16x32_bf16 v[140:143], v[206:209], v[160:163], v[112:115]
	v_mfma_f32_16x16x32_bf16 v[112:115], v[202:205], v[164:167], v[116:119]
	v_mfma_f32_16x16x32_bf16 v[60:63], v[214:217], v[132:135], v[60:63]
	v_mfma_f32_16x16x32_bf16 v[56:59], v[210:213], v[156:159], v[56:59]
	v_mfma_f32_16x16x32_bf16 v[132:135], v[206:209], v[190:193], v[112:115]
	v_mfma_f32_16x16x32_bf16 v[36:39], v[210:213], v[164:167], v[36:39]
	v_mfma_f32_16x16x32_bf16 v[112:115], v[202:205], v[194:197], v[120:123]
	v_mfma_f32_16x16x32_bf16 v[32:35], v[210:213], v[194:197], v[32:35]
	v_mfma_f32_16x16x32_bf16 v[56:59], v[214:217], v[160:163], v[56:59]
	v_mfma_f32_16x16x32_bf16 v[36:39], v[214:217], v[190:193], v[36:39]
	v_mfma_f32_16x16x32_bf16 v[124:127], v[206:209], v[198:201], v[112:115]
	v_mfma_f32_16x16x32_bf16 v[32:35], v[214:217], v[198:201], v[32:35]
	s_mov_b32 m0, s62
	s_barrier
	ds_read_b128 v[112:115], v238 offset:49152
	ds_read_b128 v[116:119], v238 offset:50176
	ds_read_b128 v[120:123], v238 offset:51200
	ds_read_b128 v[156:159], v238 offset:52224
	ds_read_b128 v[160:163], v238 offset:53248
	ds_read_b128 v[164:167], v238 offset:54272
	ds_read_b128 v[190:193], v238 offset:55296
	global_load_lds_dwordx4 v180, s[100:101]
	s_mov_b32 m0, s63
	ds_read_b128 v[194:197], v238 offset:56320
	global_load_lds_dwordx4 v182, s[100:101]
	s_barrier
	s_waitcnt lgkmcnt(0)
	v_mfma_f32_16x16x32_bf16 v[100:103], v[76:79], v[112:115], v[100:103]
	v_mfma_f32_16x16x32_bf16 v[28:31], v[104:107], v[112:115], v[28:31]
	v_mfma_f32_16x16x32_bf16 v[96:99], v[76:79], v[120:123], v[96:99]
	v_mfma_f32_16x16x32_bf16 v[24:27], v[104:107], v[120:123], v[24:27]
	v_mfma_f32_16x16x32_bf16 v[84:87], v[76:79], v[160:163], v[84:87]
	v_mfma_f32_16x16x32_bf16 v[12:15], v[104:107], v[160:163], v[12:15]
	v_mfma_f32_16x16x32_bf16 v[48:51], v[76:79], v[190:193], v[48:51]
	v_mfma_f32_16x16x32_bf16 v[8:11], v[104:107], v[190:193], v[8:11]
	v_mfma_f32_16x16x32_bf16 v[100:103], v[92:95], v[116:119], v[100:103]
	v_mfma_f32_16x16x32_bf16 v[28:31], v[108:111], v[116:119], v[28:31]
	v_mfma_f32_16x16x32_bf16 v[96:99], v[92:95], v[156:159], v[96:99]
	v_mfma_f32_16x16x32_bf16 v[24:27], v[108:111], v[156:159], v[24:27]
	v_mfma_f32_16x16x32_bf16 v[84:87], v[92:95], v[164:167], v[84:87]
	v_mfma_f32_16x16x32_bf16 v[12:15], v[108:111], v[164:167], v[12:15]
	v_mfma_f32_16x16x32_bf16 v[76:79], v[92:95], v[194:197], v[48:51]
	v_mfma_f32_16x16x32_bf16 v[8:11], v[108:111], v[194:197], v[8:11]
	s_barrier
	s_add_i32 s12, s12, s53
	s_mov_b32 m0, s12
	s_add_u32 s2, s2, 0x40080
	s_addc_u32 s3, s3, 0
	global_load_lds_dwordx4 v168, s[2:3]
	s_add_i32 m0, s12, 0x2000
	s_nop 0
	global_load_lds_dwordx4 v184, s[2:3]
	s_waitcnt vmcnt(6)
	s_barrier
	v_mfma_f32_16x16x32_bf16 v[48:51], v[202:205], v[112:115], v[52:55]
	v_mfma_f32_16x16x32_bf16 v[92:95], v[206:209], v[116:119], v[48:51]
	v_mfma_f32_16x16x32_bf16 v[48:51], v[202:205], v[120:123], v[88:91]
	v_mfma_f32_16x16x32_bf16 v[88:91], v[206:209], v[156:159], v[48:51]
	v_mfma_f32_16x16x32_bf16 v[48:51], v[202:205], v[160:163], v[80:83]
	v_mfma_f32_16x16x32_bf16 v[20:23], v[210:213], v[112:115], v[20:23]
	v_mfma_f32_16x16x32_bf16 v[16:19], v[210:213], v[120:123], v[16:19]
	v_mfma_f32_16x16x32_bf16 v[80:83], v[206:209], v[164:167], v[48:51]
	v_mfma_f32_16x16x32_bf16 v[4:7], v[210:213], v[160:163], v[4:7]
	v_mfma_f32_16x16x32_bf16 v[48:51], v[202:205], v[190:193], v[72:75]
	v_mfma_f32_16x16x32_bf16 v[0:3], v[210:213], v[190:193], v[0:3]
	v_mfma_f32_16x16x32_bf16 v[20:23], v[214:217], v[116:119], v[20:23]
	v_mfma_f32_16x16x32_bf16 v[16:19], v[214:217], v[156:159], v[16:19]
	v_mfma_f32_16x16x32_bf16 v[4:7], v[214:217], v[164:167], v[4:7]
	v_mfma_f32_16x16x32_bf16 v[72:75], v[206:209], v[194:197], v[48:51]
	v_mfma_f32_16x16x32_bf16 v[0:3], v[214:217], v[194:197], v[0:3]
	s_add_i32 s67, s67, 2
	s_add_u32 s10, s10, 0x100
	s_addc_u32 s11, s11, 0
	s_add_u32 s37, s37, 0x100
	s_addc_u32 s39, s39, 0
	s_cmp_gt_u32 s67, 13
	s_barrier
.LBB0_880:
	s_add_u32 s2, s10, 0xfffc0080
	s_addc_u32 s3, s11, -1
	s_add_i32 s68, 0, 0x10000
	v_add_u32_e32 v108, s68, v237
	ds_read_b128 v[48:51], v108
	ds_read_b128 v[52:55], v108 offset:1024
	ds_read_b128 v[104:107], v108 offset:2048
	ds_read_b128 v[108:111], v108 offset:3072
	s_cmp_eq_u32 s67, 12
	s_cselect_b32 s13, s1, s3
	s_cselect_b32 s12, s9, s2
	s_cselect_b32 s3, s14, s39
	s_cselect_b32 s2, s15, s37
	s_add_i32 m0, s54, 0xc000
	ds_read_b128 v[112:115], v238
	ds_read_b128 v[116:119], v238 offset:1024
	ds_read_b128 v[120:123], v238 offset:2048
	ds_read_b128 v[156:159], v238 offset:3072
	ds_read_b128 v[160:163], v238 offset:4096
	ds_read_b128 v[164:167], v238 offset:5120
	ds_read_b128 v[190:193], v238 offset:6144
	global_load_lds_dwordx4 v186, s[10:11]
	s_add_i32 m0, s54, 0xe000
	ds_read_b128 v[194:197], v238 offset:7168
	global_load_lds_dwordx4 v188, s[10:11]
	s_waitcnt lgkmcnt(8)
	s_barrier
	s_waitcnt lgkmcnt(0)
	v_mfma_f32_16x16x32_bf16 v[152:155], v[48:51], v[112:115], v[152:155]
	v_mfma_f32_16x16x32_bf16 v[68:71], v[104:107], v[112:115], v[68:71]
	v_mfma_f32_16x16x32_bf16 v[148:151], v[48:51], v[120:123], v[148:151]
	v_mfma_f32_16x16x32_bf16 v[64:67], v[104:107], v[120:123], v[64:67]
	v_mfma_f32_16x16x32_bf16 v[136:139], v[48:51], v[160:163], v[136:139]
	v_mfma_f32_16x16x32_bf16 v[44:47], v[104:107], v[160:163], v[44:47]
	v_mfma_f32_16x16x32_bf16 v[128:131], v[48:51], v[190:193], v[128:131]
	v_mfma_f32_16x16x32_bf16 v[40:43], v[104:107], v[190:193], v[40:43]
	v_mfma_f32_16x16x32_bf16 v[152:155], v[52:55], v[116:119], v[152:155]
	v_mfma_f32_16x16x32_bf16 v[68:71], v[108:111], v[116:119], v[68:71]
	v_mfma_f32_16x16x32_bf16 v[148:151], v[52:55], v[156:159], v[148:151]
	v_mfma_f32_16x16x32_bf16 v[64:67], v[108:111], v[156:159], v[64:67]
	v_mfma_f32_16x16x32_bf16 v[136:139], v[52:55], v[164:167], v[136:139]
	v_mfma_f32_16x16x32_bf16 v[44:47], v[108:111], v[164:167], v[44:47]
	v_mfma_f32_16x16x32_bf16 v[128:131], v[52:55], v[194:197], v[128:131]
	v_mfma_f32_16x16x32_bf16 v[40:43], v[108:111], v[194:197], v[40:43]
	s_barrier
	s_add_i32 s70, 0, 0x14000
	s_add_i32 s68, s68, s53
	v_add_u32_e32 v210, s70, v237
	s_add_u32 s98, s2, 0x80
	s_addc_u32 s99, s3, 0
	s_mov_b32 m0, s68
	ds_read_b128 v[198:201], v210
	ds_read_b128 v[202:205], v210 offset:1024
	ds_read_b128 v[206:209], v210 offset:2048
	global_load_lds_dwordx4 v168, s[2:3]
	s_add_i32 m0, s68, 0x2000
	ds_read_b128 v[210:213], v210 offset:3072
	global_load_lds_dwordx4 v184, s[2:3]
	s_barrier
	s_waitcnt lgkmcnt(0)
	v_mfma_f32_16x16x32_bf16 v[144:147], v[198:201], v[112:115], v[144:147]
	v_mfma_f32_16x16x32_bf16 v[60:63], v[206:209], v[112:115], v[60:63]
	v_mfma_f32_16x16x32_bf16 v[56:59], v[206:209], v[120:123], v[56:59]
	v_mfma_f32_16x16x32_bf16 v[36:39], v[206:209], v[160:163], v[36:39]
	v_mfma_f32_16x16x32_bf16 v[32:35], v[206:209], v[190:193], v[32:35]
	v_mfma_f32_16x16x32_bf16 v[144:147], v[202:205], v[116:119], v[144:147]
	v_mfma_f32_16x16x32_bf16 v[60:63], v[210:213], v[116:119], v[60:63]
	v_mfma_f32_16x16x32_bf16 v[112:115], v[198:201], v[120:123], v[140:143]
	v_mfma_f32_16x16x32_bf16 v[56:59], v[210:213], v[156:159], v[56:59]
	v_mfma_f32_16x16x32_bf16 v[116:119], v[198:201], v[160:163], v[132:135]
	v_mfma_f32_16x16x32_bf16 v[36:39], v[210:213], v[164:167], v[36:39]
	v_mfma_f32_16x16x32_bf16 v[120:123], v[198:201], v[190:193], v[124:127]
	v_mfma_f32_16x16x32_bf16 v[32:35], v[210:213], v[194:197], v[32:35]
	v_mfma_f32_16x16x32_bf16 v[112:115], v[202:205], v[156:159], v[112:115]
	v_mfma_f32_16x16x32_bf16 v[116:119], v[202:205], v[164:167], v[116:119]
	v_mfma_f32_16x16x32_bf16 v[120:123], v[202:205], v[194:197], v[120:123]
	s_mov_b32 m0, s54
	s_add_u32 s100, s12, 0x80
	s_addc_u32 s101, s13, 0
	s_barrier
	ds_read_b128 v[124:127], v238 offset:16384
	ds_read_b128 v[132:135], v238 offset:17408
	ds_read_b128 v[140:143], v238 offset:18432
	ds_read_b128 v[156:159], v238 offset:19456
	ds_read_b128 v[160:163], v238 offset:20480
	ds_read_b128 v[164:167], v238 offset:21504
	ds_read_b128 v[190:193], v238 offset:22528
	global_load_lds_dwordx4 v180, s[12:13]
	s_mov_b32 m0, s55
	ds_read_b128 v[194:197], v238 offset:23552
	global_load_lds_dwordx4 v182, s[12:13]
	s_barrier
	s_waitcnt lgkmcnt(0)
	v_mfma_f32_16x16x32_bf16 v[100:103], v[48:51], v[124:127], v[100:103]
	v_mfma_f32_16x16x32_bf16 v[28:31], v[104:107], v[124:127], v[28:31]
	v_mfma_f32_16x16x32_bf16 v[96:99], v[48:51], v[140:143], v[96:99]
	v_mfma_f32_16x16x32_bf16 v[24:27], v[104:107], v[140:143], v[24:27]
	v_mfma_f32_16x16x32_bf16 v[84:87], v[48:51], v[160:163], v[84:87]
	v_mfma_f32_16x16x32_bf16 v[12:15], v[104:107], v[160:163], v[12:15]
	v_mfma_f32_16x16x32_bf16 v[8:11], v[104:107], v[190:193], v[8:11]
	v_mfma_f32_16x16x32_bf16 v[100:103], v[52:55], v[132:135], v[100:103]
	v_mfma_f32_16x16x32_bf16 v[28:31], v[108:111], v[132:135], v[28:31]
	v_mfma_f32_16x16x32_bf16 v[96:99], v[52:55], v[156:159], v[96:99]
	v_mfma_f32_16x16x32_bf16 v[24:27], v[108:111], v[156:159], v[24:27]
	v_mfma_f32_16x16x32_bf16 v[84:87], v[52:55], v[164:167], v[84:87]
	v_mfma_f32_16x16x32_bf16 v[12:15], v[108:111], v[164:167], v[12:15]
	v_mfma_f32_16x16x32_bf16 v[48:51], v[48:51], v[190:193], v[76:79]
	v_mfma_f32_16x16x32_bf16 v[8:11], v[108:111], v[194:197], v[8:11]
	v_mfma_f32_16x16x32_bf16 v[48:51], v[52:55], v[194:197], v[48:51]
	s_barrier
	s_add_i32 s70, s70, s53
	s_mov_b32 m0, s70
	s_add_u32 s68, s2, 0x40000
	s_addc_u32 s69, s3, 0
	global_load_lds_dwordx4 v168, s[68:69]
	s_add_i32 m0, s70, 0x2000
	s_nop 0
	global_load_lds_dwordx4 v184, s[68:69]
	s_waitcnt vmcnt(6)
	s_barrier
	v_mfma_f32_16x16x32_bf16 v[76:79], v[198:201], v[140:143], v[88:91]
	v_mfma_f32_16x16x32_bf16 v[20:23], v[206:209], v[124:127], v[20:23]
	v_mfma_f32_16x16x32_bf16 v[88:91], v[202:205], v[156:159], v[76:79]
	v_mfma_f32_16x16x32_bf16 v[16:19], v[206:209], v[140:143], v[16:19]
	v_mfma_f32_16x16x32_bf16 v[76:79], v[198:201], v[160:163], v[80:83]
	v_mfma_f32_16x16x32_bf16 v[4:7], v[206:209], v[160:163], v[4:7]
	v_mfma_f32_16x16x32_bf16 v[72:75], v[198:201], v[190:193], v[72:75]
	v_mfma_f32_16x16x32_bf16 v[0:3], v[206:209], v[190:193], v[0:3]
	v_mfma_f32_16x16x32_bf16 v[52:55], v[198:201], v[124:127], v[92:95]
	v_mfma_f32_16x16x32_bf16 v[20:23], v[210:213], v[132:135], v[20:23]
	v_mfma_f32_16x16x32_bf16 v[16:19], v[210:213], v[156:159], v[16:19]
	v_mfma_f32_16x16x32_bf16 v[80:83], v[202:205], v[164:167], v[76:79]
	v_mfma_f32_16x16x32_bf16 v[4:7], v[210:213], v[164:167], v[4:7]
	v_mfma_f32_16x16x32_bf16 v[72:75], v[202:205], v[194:197], v[72:75]
	v_mfma_f32_16x16x32_bf16 v[0:3], v[210:213], v[194:197], v[0:3]
	v_mfma_f32_16x16x32_bf16 v[52:55], v[202:205], v[132:135], v[52:55]
	s_add_i32 s68, 0, 0x18000
	v_add_u32_e32 v108, s68, v237
	s_barrier
	ds_read_b128 v[76:79], v108
	ds_read_b128 v[92:95], v108 offset:1024
	ds_read_b128 v[104:107], v108 offset:2048
	ds_read_b128 v[108:111], v108 offset:3072
	s_add_u32 s12, s12, 0x40000
	s_addc_u32 s13, s13, 0
	s_mov_b32 m0, s56
	ds_read_b128 v[124:127], v238 offset:32768
	ds_read_b128 v[132:135], v238 offset:33792
	ds_read_b128 v[156:159], v238 offset:34816
	ds_read_b128 v[160:163], v238 offset:35840
	ds_read_b128 v[164:167], v238 offset:36864
	ds_read_b128 v[190:193], v238 offset:37888
	ds_read_b128 v[194:197], v238 offset:38912
	global_load_lds_dwordx4 v180, s[12:13]
	s_mov_b32 m0, s57
	ds_read_b128 v[198:201], v238 offset:39936
	global_load_lds_dwordx4 v182, s[12:13]
	s_waitcnt lgkmcnt(8)
	s_barrier
	s_waitcnt lgkmcnt(0)
	v_mfma_f32_16x16x32_bf16 v[140:143], v[76:79], v[124:127], v[152:155]
	v_mfma_f32_16x16x32_bf16 v[152:155], v[92:95], v[132:135], v[140:143]
	v_mfma_f32_16x16x32_bf16 v[68:71], v[104:107], v[124:127], v[68:71]
	v_mfma_f32_16x16x32_bf16 v[140:143], v[76:79], v[156:159], v[148:151]
	v_mfma_f32_16x16x32_bf16 v[64:67], v[104:107], v[156:159], v[64:67]
	v_mfma_f32_16x16x32_bf16 v[136:139], v[76:79], v[164:167], v[136:139]
	v_mfma_f32_16x16x32_bf16 v[44:47], v[104:107], v[164:167], v[44:47]
	v_mfma_f32_16x16x32_bf16 v[128:131], v[76:79], v[194:197], v[128:131]
	v_mfma_f32_16x16x32_bf16 v[40:43], v[104:107], v[194:197], v[40:43]
	v_mfma_f32_16x16x32_bf16 v[68:71], v[108:111], v[132:135], v[68:71]
	v_mfma_f32_16x16x32_bf16 v[148:151], v[92:95], v[160:163], v[140:143]
	v_mfma_f32_16x16x32_bf16 v[64:67], v[108:111], v[160:163], v[64:67]
	v_mfma_f32_16x16x32_bf16 v[136:139], v[92:95], v[190:193], v[136:139]
	v_mfma_f32_16x16x32_bf16 v[44:47], v[108:111], v[190:193], v[44:47]
	v_mfma_f32_16x16x32_bf16 v[128:131], v[92:95], v[198:201], v[128:131]
	v_mfma_f32_16x16x32_bf16 v[40:43], v[108:111], v[198:201], v[40:43]
	s_barrier
	s_add_i32 s12, 0, 0x1c000
	v_add_u32_e32 v140, s12, v237
	s_add_i32 s13, s68, s53
	ds_read_b128 v[202:205], v140
	ds_read_b128 v[206:209], v140 offset:1024
	ds_read_b128 v[210:213], v140 offset:2048
	s_mov_b32 m0, s13
	ds_read_b128 v[214:217], v140 offset:3072
	global_load_lds_dwordx4 v168, s[98:99]
	s_add_i32 m0, s13, 0x2000
	s_nop 0
	global_load_lds_dwordx4 v184, s[98:99]
	s_barrier
	s_waitcnt lgkmcnt(0)
	v_mfma_f32_16x16x32_bf16 v[140:143], v[202:205], v[124:127], v[144:147]
	v_mfma_f32_16x16x32_bf16 v[112:115], v[202:205], v[156:159], v[112:115]
	v_mfma_f32_16x16x32_bf16 v[144:147], v[206:209], v[132:135], v[140:143]
	v_mfma_f32_16x16x32_bf16 v[60:63], v[210:213], v[124:127], v[60:63]
	v_mfma_f32_16x16x32_bf16 v[140:143], v[206:209], v[160:163], v[112:115]
	v_mfma_f32_16x16x32_bf16 v[112:115], v[202:205], v[164:167], v[116:119]
	v_mfma_f32_16x16x32_bf16 v[60:63], v[214:217], v[132:135], v[60:63]
	v_mfma_f32_16x16x32_bf16 v[56:59], v[210:213], v[156:159], v[56:59]
	v_mfma_f32_16x16x32_bf16 v[132:135], v[206:209], v[190:193], v[112:115]
	v_mfma_f32_16x16x32_bf16 v[36:39], v[210:213], v[164:167], v[36:39]
	v_mfma_f32_16x16x32_bf16 v[112:115], v[202:205], v[194:197], v[120:123]
	v_mfma_f32_16x16x32_bf16 v[32:35], v[210:213], v[194:197], v[32:35]
	v_mfma_f32_16x16x32_bf16 v[56:59], v[214:217], v[160:163], v[56:59]
	v_mfma_f32_16x16x32_bf16 v[36:39], v[214:217], v[190:193], v[36:39]
	v_mfma_f32_16x16x32_bf16 v[124:127], v[206:209], v[198:201], v[112:115]
	v_mfma_f32_16x16x32_bf16 v[32:35], v[214:217], v[198:201], v[32:35]
	s_mov_b32 m0, s62
	s_barrier
	ds_read_b128 v[112:115], v238 offset:49152
	ds_read_b128 v[116:119], v238 offset:50176
	ds_read_b128 v[120:123], v238 offset:51200
	ds_read_b128 v[156:159], v238 offset:52224
	ds_read_b128 v[160:163], v238 offset:53248
	ds_read_b128 v[164:167], v238 offset:54272
	ds_read_b128 v[190:193], v238 offset:55296
	global_load_lds_dwordx4 v180, s[100:101]
	s_mov_b32 m0, s63
	ds_read_b128 v[194:197], v238 offset:56320
	global_load_lds_dwordx4 v182, s[100:101]
	s_barrier
	s_waitcnt lgkmcnt(0)
	v_mfma_f32_16x16x32_bf16 v[100:103], v[76:79], v[112:115], v[100:103]
	v_mfma_f32_16x16x32_bf16 v[28:31], v[104:107], v[112:115], v[28:31]
	v_mfma_f32_16x16x32_bf16 v[96:99], v[76:79], v[120:123], v[96:99]
	v_mfma_f32_16x16x32_bf16 v[24:27], v[104:107], v[120:123], v[24:27]
	v_mfma_f32_16x16x32_bf16 v[84:87], v[76:79], v[160:163], v[84:87]
	v_mfma_f32_16x16x32_bf16 v[12:15], v[104:107], v[160:163], v[12:15]
	v_mfma_f32_16x16x32_bf16 v[48:51], v[76:79], v[190:193], v[48:51]
	v_mfma_f32_16x16x32_bf16 v[8:11], v[104:107], v[190:193], v[8:11]
	v_mfma_f32_16x16x32_bf16 v[100:103], v[92:95], v[116:119], v[100:103]
	v_mfma_f32_16x16x32_bf16 v[28:31], v[108:111], v[116:119], v[28:31]
	v_mfma_f32_16x16x32_bf16 v[96:99], v[92:95], v[156:159], v[96:99]
	v_mfma_f32_16x16x32_bf16 v[24:27], v[108:111], v[156:159], v[24:27]
	v_mfma_f32_16x16x32_bf16 v[84:87], v[92:95], v[164:167], v[84:87]
	v_mfma_f32_16x16x32_bf16 v[12:15], v[108:111], v[164:167], v[12:15]
	v_mfma_f32_16x16x32_bf16 v[76:79], v[92:95], v[194:197], v[48:51]
	v_mfma_f32_16x16x32_bf16 v[8:11], v[108:111], v[194:197], v[8:11]
	s_barrier
	s_add_i32 s12, s12, s53
	s_mov_b32 m0, s12
	s_add_u32 s2, s2, 0x40080
	s_addc_u32 s3, s3, 0
	global_load_lds_dwordx4 v168, s[2:3]
	s_add_i32 m0, s12, 0x2000
	s_nop 0
	global_load_lds_dwordx4 v184, s[2:3]
	s_waitcnt vmcnt(6)
	s_barrier
	v_mfma_f32_16x16x32_bf16 v[48:51], v[202:205], v[112:115], v[52:55]
	v_mfma_f32_16x16x32_bf16 v[92:95], v[206:209], v[116:119], v[48:51]
	v_mfma_f32_16x16x32_bf16 v[48:51], v[202:205], v[120:123], v[88:91]
	v_mfma_f32_16x16x32_bf16 v[88:91], v[206:209], v[156:159], v[48:51]
	v_mfma_f32_16x16x32_bf16 v[48:51], v[202:205], v[160:163], v[80:83]
	v_mfma_f32_16x16x32_bf16 v[20:23], v[210:213], v[112:115], v[20:23]
	v_mfma_f32_16x16x32_bf16 v[16:19], v[210:213], v[120:123], v[16:19]
	v_mfma_f32_16x16x32_bf16 v[80:83], v[206:209], v[164:167], v[48:51]
	v_mfma_f32_16x16x32_bf16 v[4:7], v[210:213], v[160:163], v[4:7]
	v_mfma_f32_16x16x32_bf16 v[48:51], v[202:205], v[190:193], v[72:75]
	v_mfma_f32_16x16x32_bf16 v[0:3], v[210:213], v[190:193], v[0:3]
	v_mfma_f32_16x16x32_bf16 v[20:23], v[214:217], v[116:119], v[20:23]
	v_mfma_f32_16x16x32_bf16 v[16:19], v[214:217], v[156:159], v[16:19]
	v_mfma_f32_16x16x32_bf16 v[4:7], v[214:217], v[164:167], v[4:7]
	v_mfma_f32_16x16x32_bf16 v[72:75], v[206:209], v[194:197], v[48:51]
	v_mfma_f32_16x16x32_bf16 v[0:3], v[214:217], v[194:197], v[0:3]
	s_add_i32 s67, s67, 2
	s_add_u32 s10, s10, 0x100
	s_addc_u32 s11, s11, 0
	s_add_u32 s37, s37, 0x100
	s_addc_u32 s39, s39, 0
	s_cmp_gt_u32 s67, 13
	s_barrier
	s_cbranch_scc0 .LBB0_880

.Lup_half_peel:
	s_add_u32 s2, s10, 0xfffc0080
	s_addc_u32 s3, s11, -1
	s_add_i32 s68, 0, 0x10000
	v_add_u32_e32 v108, s68, v237
	ds_read_b128 v[48:51], v108
	ds_read_b128 v[52:55], v108 offset:1024
	ds_read_b128 v[104:107], v108 offset:2048
	ds_read_b128 v[108:111], v108 offset:3072
	s_cmp_eq_u32 s67, 12
	s_cselect_b32 s13, s1, s3
	s_cselect_b32 s12, s9, s2
	s_cselect_b32 s3, s14, s39
	s_cselect_b32 s2, s15, s37
	s_add_i32 m0, s54, 0xc000
	ds_read_b128 v[112:115], v238
	ds_read_b128 v[116:119], v238 offset:1024
	ds_read_b128 v[120:123], v238 offset:2048
	ds_read_b128 v[156:159], v238 offset:3072
	ds_read_b128 v[160:163], v238 offset:4096
	ds_read_b128 v[164:167], v238 offset:5120
	ds_read_b128 v[190:193], v238 offset:6144
	global_load_lds_dwordx4 v186, s[10:11]
	s_add_i32 m0, s54, 0xe000
	ds_read_b128 v[194:197], v238 offset:7168
	global_load_lds_dwordx4 v188, s[10:11]
	s_waitcnt lgkmcnt(8)
	s_barrier
	s_waitcnt lgkmcnt(0)
	v_mfma_f32_16x16x32_bf16 v[152:155], v[48:51], v[112:115], 0
	v_mfma_f32_16x16x32_bf16 v[68:71], v[104:107], v[112:115], 0
	v_mfma_f32_16x16x32_bf16 v[148:151], v[48:51], v[120:123], 0
	v_mfma_f32_16x16x32_bf16 v[64:67], v[104:107], v[120:123], 0
	v_mfma_f32_16x16x32_bf16 v[136:139], v[48:51], v[160:163], 0
	v_mfma_f32_16x16x32_bf16 v[44:47], v[104:107], v[160:163], 0
	v_mfma_f32_16x16x32_bf16 v[128:131], v[48:51], v[190:193], 0
	v_mfma_f32_16x16x32_bf16 v[40:43], v[104:107], v[190:193], 0
	v_mfma_f32_16x16x32_bf16 v[152:155], v[52:55], v[116:119], v[152:155]
	v_mfma_f32_16x16x32_bf16 v[68:71], v[108:111], v[116:119], v[68:71]
	v_mfma_f32_16x16x32_bf16 v[148:151], v[52:55], v[156:159], v[148:151]
	v_mfma_f32_16x16x32_bf16 v[64:67], v[108:111], v[156:159], v[64:67]
	v_mfma_f32_16x16x32_bf16 v[136:139], v[52:55], v[164:167], v[136:139]
	v_mfma_f32_16x16x32_bf16 v[44:47], v[108:111], v[164:167], v[44:47]
	v_mfma_f32_16x16x32_bf16 v[128:131], v[52:55], v[194:197], v[128:131]
	v_mfma_f32_16x16x32_bf16 v[40:43], v[108:111], v[194:197], v[40:43]
	s_barrier
	s_add_i32 s70, 0, 0x14000
	s_add_i32 s68, s68, s53
	v_add_u32_e32 v210, s70, v237
	s_add_u32 s98, s2, 0x80
	s_addc_u32 s99, s3, 0
	s_mov_b32 m0, s68
	ds_read_b128 v[198:201], v210
	ds_read_b128 v[202:205], v210 offset:1024
	ds_read_b128 v[206:209], v210 offset:2048
	global_load_lds_dwordx4 v168, s[2:3]
	s_add_i32 m0, s68, 0x2000
	ds_read_b128 v[210:213], v210 offset:3072
	global_load_lds_dwordx4 v184, s[2:3]
	s_barrier
	s_waitcnt lgkmcnt(0)
	v_mfma_f32_16x16x32_bf16 v[144:147], v[198:201], v[112:115], 0
	v_mfma_f32_16x16x32_bf16 v[60:63], v[206:209], v[112:115], 0
	v_mfma_f32_16x16x32_bf16 v[56:59], v[206:209], v[120:123], 0
	v_mfma_f32_16x16x32_bf16 v[36:39], v[206:209], v[160:163], 0
	v_mfma_f32_16x16x32_bf16 v[32:35], v[206:209], v[190:193], 0
	v_mfma_f32_16x16x32_bf16 v[144:147], v[202:205], v[116:119], v[144:147]
	v_mfma_f32_16x16x32_bf16 v[60:63], v[210:213], v[116:119], v[60:63]
	v_mfma_f32_16x16x32_bf16 v[112:115], v[198:201], v[120:123], 0
	v_mfma_f32_16x16x32_bf16 v[56:59], v[210:213], v[156:159], v[56:59]
	v_mfma_f32_16x16x32_bf16 v[116:119], v[198:201], v[160:163], 0
	v_mfma_f32_16x16x32_bf16 v[36:39], v[210:213], v[164:167], v[36:39]
	v_mfma_f32_16x16x32_bf16 v[120:123], v[198:201], v[190:193], 0
	v_mfma_f32_16x16x32_bf16 v[32:35], v[210:213], v[194:197], v[32:35]
	v_mfma_f32_16x16x32_bf16 v[112:115], v[202:205], v[156:159], v[112:115]
	v_mfma_f32_16x16x32_bf16 v[116:119], v[202:205], v[164:167], v[116:119]
	v_mfma_f32_16x16x32_bf16 v[120:123], v[202:205], v[194:197], v[120:123]
	s_mov_b32 m0, s54
	s_add_u32 s100, s12, 0x80
	s_addc_u32 s101, s13, 0
	s_barrier
	ds_read_b128 v[124:127], v238 offset:16384
	ds_read_b128 v[132:135], v238 offset:17408
	ds_read_b128 v[140:143], v238 offset:18432
	ds_read_b128 v[156:159], v238 offset:19456
	ds_read_b128 v[160:163], v238 offset:20480
	ds_read_b128 v[164:167], v238 offset:21504
	ds_read_b128 v[190:193], v238 offset:22528
	global_load_lds_dwordx4 v180, s[12:13]
	s_mov_b32 m0, s55
	ds_read_b128 v[194:197], v238 offset:23552
	global_load_lds_dwordx4 v182, s[12:13]
	s_barrier
	s_waitcnt lgkmcnt(0)
	s_barrier
	s_add_i32 s70, s70, s53
	s_mov_b32 m0, s70
	s_add_u32 s68, s2, 0x40000
	s_addc_u32 s69, s3, 0
	global_load_lds_dwordx4 v168, s[68:69]
	s_add_i32 m0, s70, 0x2000
	s_nop 0
	global_load_lds_dwordx4 v184, s[68:69]
	s_waitcnt vmcnt(6)
	s_barrier
	s_add_i32 s68, 0, 0x18000
	v_add_u32_e32 v108, s68, v237
	s_barrier
	ds_read_b128 v[76:79], v108
	ds_read_b128 v[92:95], v108 offset:1024
	ds_read_b128 v[104:107], v108 offset:2048
	ds_read_b128 v[108:111], v108 offset:3072
	s_add_u32 s12, s12, 0x40000
	s_addc_u32 s13, s13, 0
	s_mov_b32 m0, s56
	ds_read_b128 v[124:127], v238 offset:32768
	ds_read_b128 v[132:135], v238 offset:33792
	ds_read_b128 v[156:159], v238 offset:34816
	ds_read_b128 v[160:163], v238 offset:35840
	ds_read_b128 v[164:167], v238 offset:36864
	ds_read_b128 v[190:193], v238 offset:37888
	ds_read_b128 v[194:197], v238 offset:38912
	global_load_lds_dwordx4 v180, s[12:13]
	s_mov_b32 m0, s57
	ds_read_b128 v[198:201], v238 offset:39936
	global_load_lds_dwordx4 v182, s[12:13]
	s_waitcnt lgkmcnt(8)
	s_barrier
	s_waitcnt lgkmcnt(0)
	v_mfma_f32_16x16x32_bf16 v[140:143], v[76:79], v[124:127], v[152:155]
	v_mfma_f32_16x16x32_bf16 v[152:155], v[92:95], v[132:135], v[140:143]
	v_mfma_f32_16x16x32_bf16 v[68:71], v[104:107], v[124:127], v[68:71]
	v_mfma_f32_16x16x32_bf16 v[140:143], v[76:79], v[156:159], v[148:151]
	v_mfma_f32_16x16x32_bf16 v[64:67], v[104:107], v[156:159], v[64:67]
	v_mfma_f32_16x16x32_bf16 v[136:139], v[76:79], v[164:167], v[136:139]
	v_mfma_f32_16x16x32_bf16 v[44:47], v[104:107], v[164:167], v[44:47]
	v_mfma_f32_16x16x32_bf16 v[128:131], v[76:79], v[194:197], v[128:131]
	v_mfma_f32_16x16x32_bf16 v[40:43], v[104:107], v[194:197], v[40:43]
	v_mfma_f32_16x16x32_bf16 v[68:71], v[108:111], v[132:135], v[68:71]
	v_mfma_f32_16x16x32_bf16 v[148:151], v[92:95], v[160:163], v[140:143]
	v_mfma_f32_16x16x32_bf16 v[64:67], v[108:111], v[160:163], v[64:67]
	v_mfma_f32_16x16x32_bf16 v[136:139], v[92:95], v[190:193], v[136:139]
	v_mfma_f32_16x16x32_bf16 v[44:47], v[108:111], v[190:193], v[44:47]
	v_mfma_f32_16x16x32_bf16 v[128:131], v[92:95], v[198:201], v[128:131]
	v_mfma_f32_16x16x32_bf16 v[40:43], v[108:111], v[198:201], v[40:43]
	s_barrier
	s_add_i32 s12, 0, 0x1c000
	v_add_u32_e32 v140, s12, v237
	s_add_i32 s13, s68, s53
	ds_read_b128 v[202:205], v140
	ds_read_b128 v[206:209], v140 offset:1024
	ds_read_b128 v[210:213], v140 offset:2048
	s_mov_b32 m0, s13
	ds_read_b128 v[214:217], v140 offset:3072
	global_load_lds_dwordx4 v168, s[98:99]
	s_add_i32 m0, s13, 0x2000
	s_nop 0
	global_load_lds_dwordx4 v184, s[98:99]
	s_barrier
	s_waitcnt lgkmcnt(0)
	v_mfma_f32_16x16x32_bf16 v[140:143], v[202:205], v[124:127], v[144:147]
	v_mfma_f32_16x16x32_bf16 v[112:115], v[202:205], v[156:159], v[112:115]
	v_mfma_f32_16x16x32_bf16 v[144:147], v[206:209], v[132:135], v[140:143]
	v_mfma_f32_16x16x32_bf16 v[60:63], v[210:213], v[124:127], v[60:63]
	v_mfma_f32_16x16x32_bf16 v[140:143], v[206:209], v[160:163], v[112:115]
	v_mfma_f32_16x16x32_bf16 v[112:115], v[202:205], v[164:167], v[116:119]
	v_mfma_f32_16x16x32_bf16 v[60:63], v[214:217], v[132:135], v[60:63]
	v_mfma_f32_16x16x32_bf16 v[56:59], v[210:213], v[156:159], v[56:59]
	v_mfma_f32_16x16x32_bf16 v[132:135], v[206:209], v[190:193], v[112:115]
	v_mfma_f32_16x16x32_bf16 v[36:39], v[210:213], v[164:167], v[36:39]
	v_mfma_f32_16x16x32_bf16 v[112:115], v[202:205], v[194:197], v[120:123]
	v_mfma_f32_16x16x32_bf16 v[32:35], v[210:213], v[194:197], v[32:35]
	v_mfma_f32_16x16x32_bf16 v[56:59], v[214:217], v[160:163], v[56:59]
	v_mfma_f32_16x16x32_bf16 v[36:39], v[214:217], v[190:193], v[36:39]
	v_mfma_f32_16x16x32_bf16 v[124:127], v[206:209], v[198:201], v[112:115]
	v_mfma_f32_16x16x32_bf16 v[32:35], v[214:217], v[198:201], v[32:35]
	s_mov_b32 m0, s62
	s_barrier
	ds_read_b128 v[112:115], v238 offset:49152
	ds_read_b128 v[116:119], v238 offset:50176
	ds_read_b128 v[120:123], v238 offset:51200
	ds_read_b128 v[156:159], v238 offset:52224
	ds_read_b128 v[160:163], v238 offset:53248
	ds_read_b128 v[164:167], v238 offset:54272
	ds_read_b128 v[190:193], v238 offset:55296
	global_load_lds_dwordx4 v180, s[100:101]
	s_mov_b32 m0, s63
	ds_read_b128 v[194:197], v238 offset:56320
	global_load_lds_dwordx4 v182, s[100:101]
	s_barrier
	s_waitcnt lgkmcnt(0)
	s_barrier
	s_add_i32 s12, s12, s53
	s_mov_b32 m0, s12
	s_add_u32 s2, s2, 0x40080
	s_addc_u32 s3, s3, 0
	global_load_lds_dwordx4 v168, s[2:3]
	s_add_i32 m0, s12, 0x2000
	s_nop 0
	global_load_lds_dwordx4 v184, s[2:3]
	s_waitcnt vmcnt(6)
	s_barrier
	s_add_i32 s67, s67, 2
	s_add_u32 s10, s10, 0x100
	s_addc_u32 s11, s11, 0
	s_add_u32 s37, s37, 0x100
	s_addc_u32 s39, s39, 0
	s_cmp_gt_u32 s67, 13
	s_barrier
.Lup_half_loop:
	s_add_u32 s2, s10, 0xfffc0080
	s_addc_u32 s3, s11, -1
	s_add_i32 s68, 0, 0x10000
	v_add_u32_e32 v108, s68, v237
	ds_read_b128 v[48:51], v108
	ds_read_b128 v[52:55], v108 offset:1024
	ds_read_b128 v[104:107], v108 offset:2048
	ds_read_b128 v[108:111], v108 offset:3072
	s_cmp_eq_u32 s67, 12
	s_cselect_b32 s13, s1, s3
	s_cselect_b32 s12, s9, s2
	s_cselect_b32 s3, s14, s39
	s_cselect_b32 s2, s15, s37
	s_add_i32 m0, s54, 0xc000
	ds_read_b128 v[112:115], v238
	ds_read_b128 v[116:119], v238 offset:1024
	ds_read_b128 v[120:123], v238 offset:2048
	ds_read_b128 v[156:159], v238 offset:3072
	ds_read_b128 v[160:163], v238 offset:4096
	ds_read_b128 v[164:167], v238 offset:5120
	ds_read_b128 v[190:193], v238 offset:6144
	global_load_lds_dwordx4 v186, s[10:11]
	s_add_i32 m0, s54, 0xe000
	ds_read_b128 v[194:197], v238 offset:7168
	global_load_lds_dwordx4 v188, s[10:11]
	s_waitcnt lgkmcnt(8)
	s_barrier
	s_waitcnt lgkmcnt(0)
	v_mfma_f32_16x16x32_bf16 v[152:155], v[48:51], v[112:115], v[152:155]
	v_mfma_f32_16x16x32_bf16 v[68:71], v[104:107], v[112:115], v[68:71]
	v_mfma_f32_16x16x32_bf16 v[148:151], v[48:51], v[120:123], v[148:151]
	v_mfma_f32_16x16x32_bf16 v[64:67], v[104:107], v[120:123], v[64:67]
	v_mfma_f32_16x16x32_bf16 v[136:139], v[48:51], v[160:163], v[136:139]
	v_mfma_f32_16x16x32_bf16 v[44:47], v[104:107], v[160:163], v[44:47]
	v_mfma_f32_16x16x32_bf16 v[128:131], v[48:51], v[190:193], v[128:131]
	v_mfma_f32_16x16x32_bf16 v[40:43], v[104:107], v[190:193], v[40:43]
	v_mfma_f32_16x16x32_bf16 v[152:155], v[52:55], v[116:119], v[152:155]
	v_mfma_f32_16x16x32_bf16 v[68:71], v[108:111], v[116:119], v[68:71]
	v_mfma_f32_16x16x32_bf16 v[148:151], v[52:55], v[156:159], v[148:151]
	v_mfma_f32_16x16x32_bf16 v[64:67], v[108:111], v[156:159], v[64:67]
	v_mfma_f32_16x16x32_bf16 v[136:139], v[52:55], v[164:167], v[136:139]
	v_mfma_f32_16x16x32_bf16 v[44:47], v[108:111], v[164:167], v[44:47]
	v_mfma_f32_16x16x32_bf16 v[128:131], v[52:55], v[194:197], v[128:131]
	v_mfma_f32_16x16x32_bf16 v[40:43], v[108:111], v[194:197], v[40:43]
	s_barrier
	s_add_i32 s70, 0, 0x14000
	s_add_i32 s68, s68, s53
	v_add_u32_e32 v210, s70, v237
	s_add_u32 s98, s2, 0x80
	s_addc_u32 s99, s3, 0
	s_mov_b32 m0, s68
	ds_read_b128 v[198:201], v210
	ds_read_b128 v[202:205], v210 offset:1024
	ds_read_b128 v[206:209], v210 offset:2048
	global_load_lds_dwordx4 v168, s[2:3]
	s_add_i32 m0, s68, 0x2000
	ds_read_b128 v[210:213], v210 offset:3072
	global_load_lds_dwordx4 v184, s[2:3]
	s_barrier
	s_waitcnt lgkmcnt(0)
	v_mfma_f32_16x16x32_bf16 v[144:147], v[198:201], v[112:115], v[144:147]
	v_mfma_f32_16x16x32_bf16 v[60:63], v[206:209], v[112:115], v[60:63]
	v_mfma_f32_16x16x32_bf16 v[56:59], v[206:209], v[120:123], v[56:59]
	v_mfma_f32_16x16x32_bf16 v[36:39], v[206:209], v[160:163], v[36:39]
	v_mfma_f32_16x16x32_bf16 v[32:35], v[206:209], v[190:193], v[32:35]
	v_mfma_f32_16x16x32_bf16 v[144:147], v[202:205], v[116:119], v[144:147]
	v_mfma_f32_16x16x32_bf16 v[60:63], v[210:213], v[116:119], v[60:63]
	v_mfma_f32_16x16x32_bf16 v[112:115], v[198:201], v[120:123], v[140:143]
	v_mfma_f32_16x16x32_bf16 v[56:59], v[210:213], v[156:159], v[56:59]
	v_mfma_f32_16x16x32_bf16 v[116:119], v[198:201], v[160:163], v[132:135]
	v_mfma_f32_16x16x32_bf16 v[36:39], v[210:213], v[164:167], v[36:39]
	v_mfma_f32_16x16x32_bf16 v[120:123], v[198:201], v[190:193], v[124:127]
	v_mfma_f32_16x16x32_bf16 v[32:35], v[210:213], v[194:197], v[32:35]
	v_mfma_f32_16x16x32_bf16 v[112:115], v[202:205], v[156:159], v[112:115]
	v_mfma_f32_16x16x32_bf16 v[116:119], v[202:205], v[164:167], v[116:119]
	v_mfma_f32_16x16x32_bf16 v[120:123], v[202:205], v[194:197], v[120:123]
	s_mov_b32 m0, s54
	s_add_u32 s100, s12, 0x80
	s_addc_u32 s101, s13, 0
	s_barrier
	ds_read_b128 v[124:127], v238 offset:16384
	ds_read_b128 v[132:135], v238 offset:17408
	ds_read_b128 v[140:143], v238 offset:18432
	ds_read_b128 v[156:159], v238 offset:19456
	ds_read_b128 v[160:163], v238 offset:20480
	ds_read_b128 v[164:167], v238 offset:21504
	ds_read_b128 v[190:193], v238 offset:22528
	global_load_lds_dwordx4 v180, s[12:13]
	s_mov_b32 m0, s55
	ds_read_b128 v[194:197], v238 offset:23552
	global_load_lds_dwordx4 v182, s[12:13]
	s_barrier
	s_waitcnt lgkmcnt(0)
	s_barrier
	s_add_i32 s70, s70, s53
	s_mov_b32 m0, s70
	s_add_u32 s68, s2, 0x40000
	s_addc_u32 s69, s3, 0
	global_load_lds_dwordx4 v168, s[68:69]
	s_add_i32 m0, s70, 0x2000
	s_nop 0
	global_load_lds_dwordx4 v184, s[68:69]
	s_waitcnt vmcnt(6)
	s_barrier
	s_add_i32 s68, 0, 0x18000
	v_add_u32_e32 v108, s68, v237
	s_barrier
	ds_read_b128 v[76:79], v108
	ds_read_b128 v[92:95], v108 offset:1024
	ds_read_b128 v[104:107], v108 offset:2048
	ds_read_b128 v[108:111], v108 offset:3072
	s_add_u32 s12, s12, 0x40000
	s_addc_u32 s13, s13, 0
	s_mov_b32 m0, s56
	ds_read_b128 v[124:127], v238 offset:32768
	ds_read_b128 v[132:135], v238 offset:33792
	ds_read_b128 v[156:159], v238 offset:34816
	ds_read_b128 v[160:163], v238 offset:35840
	ds_read_b128 v[164:167], v238 offset:36864
	ds_read_b128 v[190:193], v238 offset:37888
	ds_read_b128 v[194:197], v238 offset:38912
	global_load_lds_dwordx4 v180, s[12:13]
	s_mov_b32 m0, s57
	ds_read_b128 v[198:201], v238 offset:39936
	global_load_lds_dwordx4 v182, s[12:13]
	s_waitcnt lgkmcnt(8)
	s_barrier
	s_waitcnt lgkmcnt(0)
	v_mfma_f32_16x16x32_bf16 v[140:143], v[76:79], v[124:127], v[152:155]
	v_mfma_f32_16x16x32_bf16 v[152:155], v[92:95], v[132:135], v[140:143]
	v_mfma_f32_16x16x32_bf16 v[68:71], v[104:107], v[124:127], v[68:71]
	v_mfma_f32_16x16x32_bf16 v[140:143], v[76:79], v[156:159], v[148:151]
	v_mfma_f32_16x16x32_bf16 v[64:67], v[104:107], v[156:159], v[64:67]
	v_mfma_f32_16x16x32_bf16 v[136:139], v[76:79], v[164:167], v[136:139]
	v_mfma_f32_16x16x32_bf16 v[44:47], v[104:107], v[164:167], v[44:47]
	v_mfma_f32_16x16x32_bf16 v[128:131], v[76:79], v[194:197], v[128:131]
	v_mfma_f32_16x16x32_bf16 v[40:43], v[104:107], v[194:197], v[40:43]
	v_mfma_f32_16x16x32_bf16 v[68:71], v[108:111], v[132:135], v[68:71]
	v_mfma_f32_16x16x32_bf16 v[148:151], v[92:95], v[160:163], v[140:143]
	v_mfma_f32_16x16x32_bf16 v[64:67], v[108:111], v[160:163], v[64:67]
	v_mfma_f32_16x16x32_bf16 v[136:139], v[92:95], v[190:193], v[136:139]
	v_mfma_f32_16x16x32_bf16 v[44:47], v[108:111], v[190:193], v[44:47]
	v_mfma_f32_16x16x32_bf16 v[128:131], v[92:95], v[198:201], v[128:131]
	v_mfma_f32_16x16x32_bf16 v[40:43], v[108:111], v[198:201], v[40:43]
	s_barrier
	s_add_i32 s12, 0, 0x1c000
	v_add_u32_e32 v140, s12, v237
	s_add_i32 s13, s68, s53
	ds_read_b128 v[202:205], v140
	ds_read_b128 v[206:209], v140 offset:1024
	ds_read_b128 v[210:213], v140 offset:2048
	s_mov_b32 m0, s13
	ds_read_b128 v[214:217], v140 offset:3072
	global_load_lds_dwordx4 v168, s[98:99]
	s_add_i32 m0, s13, 0x2000
	s_nop 0
	global_load_lds_dwordx4 v184, s[98:99]
	s_barrier
	s_waitcnt lgkmcnt(0)
	v_mfma_f32_16x16x32_bf16 v[140:143], v[202:205], v[124:127], v[144:147]
	v_mfma_f32_16x16x32_bf16 v[112:115], v[202:205], v[156:159], v[112:115]
	v_mfma_f32_16x16x32_bf16 v[144:147], v[206:209], v[132:135], v[140:143]
	v_mfma_f32_16x16x32_bf16 v[60:63], v[210:213], v[124:127], v[60:63]
	v_mfma_f32_16x16x32_bf16 v[140:143], v[206:209], v[160:163], v[112:115]
	v_mfma_f32_16x16x32_bf16 v[112:115], v[202:205], v[164:167], v[116:119]
	v_mfma_f32_16x16x32_bf16 v[60:63], v[214:217], v[132:135], v[60:63]
	v_mfma_f32_16x16x32_bf16 v[56:59], v[210:213], v[156:159], v[56:59]
	v_mfma_f32_16x16x32_bf16 v[132:135], v[206:209], v[190:193], v[112:115]
	v_mfma_f32_16x16x32_bf16 v[36:39], v[210:213], v[164:167], v[36:39]
	v_mfma_f32_16x16x32_bf16 v[112:115], v[202:205], v[194:197], v[120:123]
	v_mfma_f32_16x16x32_bf16 v[32:35], v[210:213], v[194:197], v[32:35]
	v_mfma_f32_16x16x32_bf16 v[56:59], v[214:217], v[160:163], v[56:59]
	v_mfma_f32_16x16x32_bf16 v[36:39], v[214:217], v[190:193], v[36:39]
	v_mfma_f32_16x16x32_bf16 v[124:127], v[206:209], v[198:201], v[112:115]
	v_mfma_f32_16x16x32_bf16 v[32:35], v[214:217], v[198:201], v[32:35]
	s_mov_b32 m0, s62
	s_barrier
	ds_read_b128 v[112:115], v238 offset:49152
	ds_read_b128 v[116:119], v238 offset:50176
	ds_read_b128 v[120:123], v238 offset:51200
	ds_read_b128 v[156:159], v238 offset:52224
	ds_read_b128 v[160:163], v238 offset:53248
	ds_read_b128 v[164:167], v238 offset:54272
	ds_read_b128 v[190:193], v238 offset:55296
	global_load_lds_dwordx4 v180, s[100:101]
	s_mov_b32 m0, s63
	ds_read_b128 v[194:197], v238 offset:56320
	global_load_lds_dwordx4 v182, s[100:101]
	s_barrier
	s_waitcnt lgkmcnt(0)
	s_barrier
	s_add_i32 s12, s12, s53
	s_mov_b32 m0, s12
	s_add_u32 s2, s2, 0x40080
	s_addc_u32 s3, s3, 0
	global_load_lds_dwordx4 v168, s[2:3]
	s_add_i32 m0, s12, 0x2000
	s_nop 0
	global_load_lds_dwordx4 v184, s[2:3]
	s_waitcnt vmcnt(6)
	s_barrier
	s_add_i32 s67, s67, 2
	s_add_u32 s10, s10, 0x100
	s_addc_u32 s11, s11, 0
	s_add_u32 s37, s37, 0x100
	s_addc_u32 s39, s39, 0
	s_cmp_gt_u32 s67, 13
	s_barrier
	s_cbranch_scc0 .Lup_half_loop
	s_branch .Lup_epi

.LBB0_1048:
	s_add_u32 s56, s2, 0x100
	s_addc_u32 s57, s3, 0
	s_mov_b32 s58, -2
	s_add_u32 s2, s24, 0x100
	s_addc_u32 s3, s25, 0
	s_add_i32 s59, 0, 0x10000
	v_add_u32_e32 v52, s59, v194
	ds_read_b128 v[40:43], v52
	ds_read_b128 v[44:47], v52 offset:1024
	ds_read_b128 v[48:51], v52 offset:2048
	ds_read_b128 v[52:55], v52 offset:3072
	s_cmp_eq_u32 s58, 40
	s_cselect_b32 s27, s1, s3
	s_cselect_b32 s26, s0, s2
	s_cselect_b32 s9, s23, s57
	s_cselect_b32 s8, s22, s56
	s_add_i32 m0, s37, 0xc000
	ds_read_b128 v[56:59], v195
	ds_read_b128 v[60:63], v195 offset:1024
	ds_read_b128 v[72:75], v195 offset:2048
	ds_read_b128 v[84:87], v195 offset:3072
	ds_read_b128 v[182:185], v195 offset:4096
	ds_read_b128 v[186:189], v195 offset:5120
	ds_read_b128 v[196:199], v195 offset:6144
	global_load_lds_dwordx4 v166, s[24:25]
	s_add_i32 m0, s37, 0xe000
	ds_read_b128 v[200:203], v195 offset:7168
	global_load_lds_dwordx4 v180, s[24:25]
	s_waitcnt lgkmcnt(8)
	s_barrier
	s_waitcnt lgkmcnt(0)
	v_mfma_f32_16x16x32_bf16 v[156:159], v[40:43], v[56:59], 0
	v_mfma_f32_16x16x32_bf16 v[152:155], v[48:51], v[56:59], 0
	v_mfma_f32_16x16x32_bf16 v[140:143], v[40:43], v[72:75], 0
	v_mfma_f32_16x16x32_bf16 v[136:139], v[48:51], v[72:75], 0
	v_mfma_f32_16x16x32_bf16 v[124:127], v[40:43], v[182:185], 0
	v_mfma_f32_16x16x32_bf16 v[120:123], v[48:51], v[182:185], 0
	v_mfma_f32_16x16x32_bf16 v[108:111], v[40:43], v[196:199], 0
	v_mfma_f32_16x16x32_bf16 v[104:107], v[48:51], v[196:199], 0
	v_mfma_f32_16x16x32_bf16 v[156:159], v[44:47], v[60:63], v[156:159]
	v_mfma_f32_16x16x32_bf16 v[152:155], v[52:55], v[60:63], v[152:155]
	v_mfma_f32_16x16x32_bf16 v[140:143], v[44:47], v[84:87], v[140:143]
	v_mfma_f32_16x16x32_bf16 v[136:139], v[52:55], v[84:87], v[136:139]
	v_mfma_f32_16x16x32_bf16 v[124:127], v[44:47], v[186:189], v[124:127]
	v_mfma_f32_16x16x32_bf16 v[120:123], v[52:55], v[186:189], v[120:123]
	v_mfma_f32_16x16x32_bf16 v[108:111], v[44:47], v[200:203], v[108:111]
	v_mfma_f32_16x16x32_bf16 v[104:107], v[52:55], v[200:203], v[104:107]
	s_barrier
	s_add_i32 s60, 0, 0x14000
	v_add_u32_e32 v190, s60, v194
	s_add_i32 s24, s59, s36
	ds_read_b128 v[204:207], v190
	ds_read_b128 v[208:211], v190 offset:1024
	ds_read_b128 v[212:215], v190 offset:2048
	ds_read_b128 v[216:219], v190 offset:3072
	s_mov_b32 m0, s24
	s_add_u32 s98, s8, 0x80
	s_addc_u32 s99, s9, 0
	global_load_lds_dwordx4 v168, s[8:9]
	s_add_i32 m0, s24, 0x2000
	s_nop 0
	global_load_lds_dwordx4 v164, s[8:9]
	s_barrier
	s_waitcnt lgkmcnt(0)
	v_mfma_f32_16x16x32_bf16 v[148:151], v[204:207], v[56:59], 0
	v_mfma_f32_16x16x32_bf16 v[56:59], v[212:215], v[56:59], 0
	v_mfma_f32_16x16x32_bf16 v[148:151], v[208:211], v[60:63], v[148:151]
	v_mfma_f32_16x16x32_bf16 v[56:59], v[216:219], v[60:63], v[56:59]
	v_mfma_f32_16x16x32_bf16 v[60:63], v[204:207], v[72:75], 0
	v_mfma_f32_16x16x32_bf16 v[72:75], v[212:215], v[72:75], 0
	v_mfma_f32_16x16x32_bf16 v[112:115], v[212:215], v[182:185], 0
	v_mfma_f32_16x16x32_bf16 v[100:103], v[204:207], v[196:199], 0
	v_mfma_f32_16x16x32_bf16 v[96:99], v[212:215], v[196:199], 0
	v_mfma_f32_16x16x32_bf16 v[60:63], v[208:211], v[84:87], v[60:63]
	v_mfma_f32_16x16x32_bf16 v[72:75], v[216:219], v[84:87], v[72:75]
	v_mfma_f32_16x16x32_bf16 v[84:87], v[204:207], v[182:185], 0
	v_mfma_f32_16x16x32_bf16 v[112:115], v[216:219], v[186:189], v[112:115]
	v_mfma_f32_16x16x32_bf16 v[100:103], v[208:211], v[200:203], v[100:103]
	v_mfma_f32_16x16x32_bf16 v[96:99], v[216:219], v[200:203], v[96:99]
	v_mfma_f32_16x16x32_bf16 v[84:87], v[208:211], v[186:189], v[84:87]
	s_mov_b32 m0, s37
	s_add_u32 s100, s26, 0x80
	s_addc_u32 s101, s27, 0
	s_barrier
	ds_read_b128 v[116:119], v195 offset:16384
	ds_read_b128 v[128:131], v195 offset:17408
	ds_read_b128 v[132:135], v195 offset:18432
	ds_read_b128 v[144:147], v195 offset:19456
	ds_read_b128 v[182:185], v195 offset:20480
	ds_read_b128 v[186:189], v195 offset:21504
	ds_read_b128 v[196:199], v195 offset:22528
	global_load_lds_dwordx4 v160, s[26:27]
	s_mov_b32 m0, s38
	ds_read_b128 v[200:203], v195 offset:23552
	global_load_lds_dwordx4 v162, s[26:27]
	s_barrier
	s_waitcnt lgkmcnt(0)
	v_mfma_f32_16x16x32_bf16 v[92:95], v[40:43], v[116:119], 0
	v_mfma_f32_16x16x32_bf16 v[88:91], v[48:51], v[116:119], 0
	v_mfma_f32_16x16x32_bf16 v[68:71], v[40:43], v[132:135], 0
	v_mfma_f32_16x16x32_bf16 v[64:67], v[48:51], v[132:135], 0
	v_mfma_f32_16x16x32_bf16 v[28:31], v[40:43], v[182:185], 0
	v_mfma_f32_16x16x32_bf16 v[24:27], v[48:51], v[182:185], 0
	v_mfma_f32_16x16x32_bf16 v[12:15], v[40:43], v[196:199], 0
	v_mfma_f32_16x16x32_bf16 v[8:11], v[48:51], v[196:199], 0
	v_mfma_f32_16x16x32_bf16 v[92:95], v[44:47], v[128:131], v[92:95]
	v_mfma_f32_16x16x32_bf16 v[88:91], v[52:55], v[128:131], v[88:91]
	v_mfma_f32_16x16x32_bf16 v[68:71], v[44:47], v[144:147], v[68:71]
	v_mfma_f32_16x16x32_bf16 v[64:67], v[52:55], v[144:147], v[64:67]
	v_mfma_f32_16x16x32_bf16 v[28:31], v[44:47], v[186:189], v[28:31]
	v_mfma_f32_16x16x32_bf16 v[24:27], v[52:55], v[186:189], v[24:27]
	v_mfma_f32_16x16x32_bf16 v[12:15], v[44:47], v[200:203], v[12:15]
	v_mfma_f32_16x16x32_bf16 v[8:11], v[52:55], v[200:203], v[8:11]
	s_barrier
	s_add_i32 s59, s60, s36
	s_mov_b32 m0, s59
	s_add_u32 s24, s8, 0xb0000
	s_addc_u32 s25, s9, 0
	global_load_lds_dwordx4 v168, s[24:25]
	s_add_i32 m0, s59, 0x2000
	s_nop 0
	global_load_lds_dwordx4 v164, s[24:25]
	s_waitcnt vmcnt(6)
	s_barrier
	v_mfma_f32_16x16x32_bf16 v[36:39], v[204:207], v[132:135], 0
	v_mfma_f32_16x16x32_bf16 v[32:35], v[212:215], v[132:135], 0
	v_mfma_f32_16x16x32_bf16 v[20:23], v[204:207], v[182:185], 0
	v_mfma_f32_16x16x32_bf16 v[16:19], v[212:215], v[182:185], 0
	v_mfma_f32_16x16x32_bf16 v[4:7], v[204:207], v[196:199], 0
	v_mfma_f32_16x16x32_bf16 v[0:3], v[212:215], v[196:199], 0
	v_mfma_f32_16x16x32_bf16 v[40:43], v[204:207], v[116:119], 0
	v_mfma_f32_16x16x32_bf16 v[44:47], v[212:215], v[116:119], 0
	v_mfma_f32_16x16x32_bf16 v[36:39], v[208:211], v[144:147], v[36:39]
	v_mfma_f32_16x16x32_bf16 v[32:35], v[216:219], v[144:147], v[32:35]
	v_mfma_f32_16x16x32_bf16 v[20:23], v[208:211], v[186:189], v[20:23]
	v_mfma_f32_16x16x32_bf16 v[16:19], v[216:219], v[186:189], v[16:19]
	v_mfma_f32_16x16x32_bf16 v[4:7], v[208:211], v[200:203], v[4:7]
	v_mfma_f32_16x16x32_bf16 v[0:3], v[216:219], v[200:203], v[0:3]
	v_mfma_f32_16x16x32_bf16 v[40:43], v[208:211], v[128:131], v[40:43]
	v_mfma_f32_16x16x32_bf16 v[44:47], v[216:219], v[128:131], v[44:47]
	s_add_i32 s59, 0, 0x18000
	v_add_u32_e32 v80, s59, v194
	s_barrier
	ds_read_b128 v[48:51], v80
	ds_read_b128 v[52:55], v80 offset:1024
	ds_read_b128 v[76:79], v80 offset:2048
	ds_read_b128 v[80:83], v80 offset:3072
	s_add_u32 s24, s26, 0xb0000
	s_addc_u32 s25, s27, 0
	s_mov_b32 m0, s39
	ds_read_b128 v[116:119], v195 offset:32768
	ds_read_b128 v[128:131], v195 offset:33792
	ds_read_b128 v[182:185], v195 offset:34816
	ds_read_b128 v[186:189], v195 offset:35840
	ds_read_b128 v[196:199], v195 offset:36864
	ds_read_b128 v[200:203], v195 offset:37888
	ds_read_b128 v[204:207], v195 offset:38912
	global_load_lds_dwordx4 v160, s[24:25]
	s_mov_b32 m0, s40
	ds_read_b128 v[208:211], v195 offset:39936
	global_load_lds_dwordx4 v162, s[24:25]
	s_waitcnt lgkmcnt(8)
	s_barrier
	s_waitcnt lgkmcnt(0)
	v_mfma_f32_16x16x32_bf16 v[132:135], v[48:51], v[116:119], v[156:159]
	v_mfma_f32_16x16x32_bf16 v[156:159], v[52:55], v[128:131], v[132:135]
	v_mfma_f32_16x16x32_bf16 v[132:135], v[76:79], v[116:119], v[152:155]
	v_mfma_f32_16x16x32_bf16 v[152:155], v[80:83], v[128:131], v[132:135]
	v_mfma_f32_16x16x32_bf16 v[132:135], v[48:51], v[182:185], v[140:143]
	v_mfma_f32_16x16x32_bf16 v[140:143], v[52:55], v[186:189], v[132:135]
	v_mfma_f32_16x16x32_bf16 v[132:135], v[76:79], v[182:185], v[136:139]
	v_mfma_f32_16x16x32_bf16 v[124:127], v[48:51], v[196:199], v[124:127]
	v_mfma_f32_16x16x32_bf16 v[120:123], v[76:79], v[196:199], v[120:123]
	v_mfma_f32_16x16x32_bf16 v[108:111], v[48:51], v[204:207], v[108:111]
	v_mfma_f32_16x16x32_bf16 v[104:107], v[76:79], v[204:207], v[104:107]
	v_mfma_f32_16x16x32_bf16 v[136:139], v[80:83], v[186:189], v[132:135]
	v_mfma_f32_16x16x32_bf16 v[124:127], v[52:55], v[200:203], v[124:127]
	v_mfma_f32_16x16x32_bf16 v[120:123], v[80:83], v[200:203], v[120:123]
	v_mfma_f32_16x16x32_bf16 v[108:111], v[52:55], v[208:211], v[108:111]
	v_mfma_f32_16x16x32_bf16 v[104:107], v[80:83], v[208:211], v[104:107]
	s_barrier
	s_add_i32 s24, 0, 0x1c000
	v_add_u32_e32 v132, s24, v194
	s_add_i32 s25, s59, s36
	ds_read_b128 v[212:215], v132
	ds_read_b128 v[216:219], v132 offset:1024
	ds_read_b128 v[220:223], v132 offset:2048
	s_mov_b32 m0, s25
	ds_read_b128 v[236:239], v132 offset:3072
	global_load_lds_dwordx4 v168, s[98:99]
	s_add_i32 m0, s25, 0x2000
	s_nop 0
	global_load_lds_dwordx4 v164, s[98:99]
	s_barrier
	s_waitcnt lgkmcnt(0)
	v_mfma_f32_16x16x32_bf16 v[56:59], v[220:223], v[116:119], v[56:59]
	v_mfma_f32_16x16x32_bf16 v[132:135], v[212:215], v[116:119], v[148:151]
	v_mfma_f32_16x16x32_bf16 v[144:147], v[236:239], v[128:131], v[56:59]
	v_mfma_f32_16x16x32_bf16 v[56:59], v[212:215], v[182:185], v[60:63]
	v_mfma_f32_16x16x32_bf16 v[148:151], v[216:219], v[128:131], v[132:135]
	v_mfma_f32_16x16x32_bf16 v[132:135], v[216:219], v[186:189], v[56:59]
	v_mfma_f32_16x16x32_bf16 v[56:59], v[220:223], v[182:185], v[72:75]
	v_mfma_f32_16x16x32_bf16 v[128:131], v[236:239], v[186:189], v[56:59]
	v_mfma_f32_16x16x32_bf16 v[56:59], v[212:215], v[196:199], v[84:87]
	v_mfma_f32_16x16x32_bf16 v[116:119], v[216:219], v[200:203], v[56:59]
	v_mfma_f32_16x16x32_bf16 v[56:59], v[220:223], v[196:199], v[112:115]
	v_mfma_f32_16x16x32_bf16 v[112:115], v[236:239], v[200:203], v[56:59]
	v_mfma_f32_16x16x32_bf16 v[56:59], v[212:215], v[204:207], v[100:103]
	v_mfma_f32_16x16x32_bf16 v[100:103], v[216:219], v[208:211], v[56:59]
	v_mfma_f32_16x16x32_bf16 v[56:59], v[220:223], v[204:207], v[96:99]
	v_mfma_f32_16x16x32_bf16 v[96:99], v[236:239], v[208:211], v[56:59]
	s_mov_b32 m0, s47
	s_barrier
	s_nop 2
	ds_read_b128 v[56:59], v195 offset:49152
	ds_read_b128 v[60:63], v195 offset:50176
	ds_read_b128 v[72:75], v195 offset:51200
	ds_read_b128 v[84:87], v195 offset:52224
	ds_read_b128 v[182:185], v195 offset:53248
	ds_read_b128 v[186:189], v195 offset:54272
	ds_read_b128 v[196:199], v195 offset:55296
	global_load_lds_dwordx4 v160, s[100:101]
	s_mov_b32 m0, s49
	ds_read_b128 v[200:203], v195 offset:56320
	global_load_lds_dwordx4 v162, s[100:101]
	s_barrier
	s_waitcnt lgkmcnt(0)
	v_mfma_f32_16x16x32_bf16 v[92:95], v[48:51], v[56:59], v[92:95]
	v_mfma_f32_16x16x32_bf16 v[88:91], v[76:79], v[56:59], v[88:91]
	v_mfma_f32_16x16x32_bf16 v[68:71], v[48:51], v[72:75], v[68:71]
	v_mfma_f32_16x16x32_bf16 v[64:67], v[76:79], v[72:75], v[64:67]
	v_mfma_f32_16x16x32_bf16 v[28:31], v[48:51], v[182:185], v[28:31]
	v_mfma_f32_16x16x32_bf16 v[24:27], v[76:79], v[182:185], v[24:27]
	v_mfma_f32_16x16x32_bf16 v[12:15], v[48:51], v[196:199], v[12:15]
	v_mfma_f32_16x16x32_bf16 v[8:11], v[76:79], v[196:199], v[8:11]
	v_mfma_f32_16x16x32_bf16 v[92:95], v[52:55], v[60:63], v[92:95]
	v_mfma_f32_16x16x32_bf16 v[88:91], v[80:83], v[60:63], v[88:91]
	v_mfma_f32_16x16x32_bf16 v[68:71], v[52:55], v[84:87], v[68:71]
	v_mfma_f32_16x16x32_bf16 v[64:67], v[80:83], v[84:87], v[64:67]
	v_mfma_f32_16x16x32_bf16 v[28:31], v[52:55], v[186:189], v[28:31]
	v_mfma_f32_16x16x32_bf16 v[24:27], v[80:83], v[186:189], v[24:27]
	v_mfma_f32_16x16x32_bf16 v[12:15], v[52:55], v[200:203], v[12:15]
	v_mfma_f32_16x16x32_bf16 v[8:11], v[80:83], v[200:203], v[8:11]
	s_barrier
	s_add_i32 s24, s24, s36
	s_mov_b32 m0, s24
	s_add_u32 s8, s8, 0xb0080
	s_addc_u32 s9, s9, 0
	global_load_lds_dwordx4 v168, s[8:9]
	s_add_i32 m0, s24, 0x2000
	s_nop 0
	global_load_lds_dwordx4 v164, s[8:9]
	s_waitcnt vmcnt(6)
	s_barrier
	v_mfma_f32_16x16x32_bf16 v[40:43], v[212:215], v[56:59], v[40:43]
	v_mfma_f32_16x16x32_bf16 v[80:83], v[216:219], v[60:63], v[40:43]
	v_mfma_f32_16x16x32_bf16 v[40:43], v[220:223], v[56:59], v[44:47]
	v_mfma_f32_16x16x32_bf16 v[36:39], v[212:215], v[72:75], v[36:39]
	v_mfma_f32_16x16x32_bf16 v[32:35], v[220:223], v[72:75], v[32:35]
	v_mfma_f32_16x16x32_bf16 v[20:23], v[212:215], v[182:185], v[20:23]
	v_mfma_f32_16x16x32_bf16 v[16:19], v[220:223], v[182:185], v[16:19]
	v_mfma_f32_16x16x32_bf16 v[4:7], v[212:215], v[196:199], v[4:7]
	v_mfma_f32_16x16x32_bf16 v[0:3], v[220:223], v[196:199], v[0:3]
	v_mfma_f32_16x16x32_bf16 v[76:79], v[236:239], v[60:63], v[40:43]
	v_mfma_f32_16x16x32_bf16 v[36:39], v[216:219], v[84:87], v[36:39]
	v_mfma_f32_16x16x32_bf16 v[32:35], v[236:239], v[84:87], v[32:35]
	v_mfma_f32_16x16x32_bf16 v[20:23], v[216:219], v[186:189], v[20:23]
	v_mfma_f32_16x16x32_bf16 v[16:19], v[236:239], v[186:189], v[16:19]
	v_mfma_f32_16x16x32_bf16 v[4:7], v[216:219], v[200:203], v[4:7]
	v_mfma_f32_16x16x32_bf16 v[0:3], v[236:239], v[200:203], v[0:3]
	s_add_i32 s58, s58, 2
	s_add_u32 s56, s56, 0x100
	s_addc_u32 s57, s57, 0
	s_cmp_gt_u32 s58, 41
	s_mov_b64 s[24:25], s[2:3]
	s_barrier
.LBB0_1049:
	s_add_u32 s2, s24, 0x100
	s_addc_u32 s3, s25, 0
	s_add_i32 s59, 0, 0x10000
	v_add_u32_e32 v52, s59, v194
	ds_read_b128 v[40:43], v52
	ds_read_b128 v[44:47], v52 offset:1024
	ds_read_b128 v[48:51], v52 offset:2048
	ds_read_b128 v[52:55], v52 offset:3072
	s_cmp_eq_u32 s58, 40
	s_cselect_b32 s27, s1, s3
	s_cselect_b32 s26, s0, s2
	s_cselect_b32 s9, s23, s57
	s_cselect_b32 s8, s22, s56
	s_add_i32 m0, s37, 0xc000
	ds_read_b128 v[56:59], v195
	ds_read_b128 v[60:63], v195 offset:1024
	ds_read_b128 v[72:75], v195 offset:2048
	ds_read_b128 v[84:87], v195 offset:3072
	ds_read_b128 v[182:185], v195 offset:4096
	ds_read_b128 v[186:189], v195 offset:5120
	ds_read_b128 v[196:199], v195 offset:6144
	global_load_lds_dwordx4 v166, s[24:25]
	s_add_i32 m0, s37, 0xe000
	ds_read_b128 v[200:203], v195 offset:7168
	global_load_lds_dwordx4 v180, s[24:25]
	s_waitcnt lgkmcnt(8)
	s_barrier
	s_waitcnt lgkmcnt(0)
	v_mfma_f32_16x16x32_bf16 v[156:159], v[40:43], v[56:59], v[156:159]
	v_mfma_f32_16x16x32_bf16 v[152:155], v[48:51], v[56:59], v[152:155]
	v_mfma_f32_16x16x32_bf16 v[140:143], v[40:43], v[72:75], v[140:143]
	v_mfma_f32_16x16x32_bf16 v[136:139], v[48:51], v[72:75], v[136:139]
	v_mfma_f32_16x16x32_bf16 v[124:127], v[40:43], v[182:185], v[124:127]
	v_mfma_f32_16x16x32_bf16 v[120:123], v[48:51], v[182:185], v[120:123]
	v_mfma_f32_16x16x32_bf16 v[108:111], v[40:43], v[196:199], v[108:111]
	v_mfma_f32_16x16x32_bf16 v[104:107], v[48:51], v[196:199], v[104:107]
	v_mfma_f32_16x16x32_bf16 v[156:159], v[44:47], v[60:63], v[156:159]
	v_mfma_f32_16x16x32_bf16 v[152:155], v[52:55], v[60:63], v[152:155]
	v_mfma_f32_16x16x32_bf16 v[140:143], v[44:47], v[84:87], v[140:143]
	v_mfma_f32_16x16x32_bf16 v[136:139], v[52:55], v[84:87], v[136:139]
	v_mfma_f32_16x16x32_bf16 v[124:127], v[44:47], v[186:189], v[124:127]
	v_mfma_f32_16x16x32_bf16 v[120:123], v[52:55], v[186:189], v[120:123]
	v_mfma_f32_16x16x32_bf16 v[108:111], v[44:47], v[200:203], v[108:111]
	v_mfma_f32_16x16x32_bf16 v[104:107], v[52:55], v[200:203], v[104:107]
	s_barrier
	s_add_i32 s60, 0, 0x14000
	v_add_u32_e32 v190, s60, v194
	s_add_i32 s24, s59, s36
	ds_read_b128 v[204:207], v190
	ds_read_b128 v[208:211], v190 offset:1024
	ds_read_b128 v[212:215], v190 offset:2048
	ds_read_b128 v[216:219], v190 offset:3072
	s_mov_b32 m0, s24
	s_add_u32 s98, s8, 0x80
	s_addc_u32 s99, s9, 0
	global_load_lds_dwordx4 v168, s[8:9]
	s_add_i32 m0, s24, 0x2000
	s_nop 0
	global_load_lds_dwordx4 v164, s[8:9]
	s_barrier
	s_waitcnt lgkmcnt(0)
	v_mfma_f32_16x16x32_bf16 v[148:151], v[204:207], v[56:59], v[148:151]
	v_mfma_f32_16x16x32_bf16 v[56:59], v[212:215], v[56:59], v[144:147]
	v_mfma_f32_16x16x32_bf16 v[148:151], v[208:211], v[60:63], v[148:151]
	v_mfma_f32_16x16x32_bf16 v[56:59], v[216:219], v[60:63], v[56:59]
	v_mfma_f32_16x16x32_bf16 v[60:63], v[204:207], v[72:75], v[132:135]
	v_mfma_f32_16x16x32_bf16 v[72:75], v[212:215], v[72:75], v[128:131]
	v_mfma_f32_16x16x32_bf16 v[112:115], v[212:215], v[182:185], v[112:115]
	v_mfma_f32_16x16x32_bf16 v[100:103], v[204:207], v[196:199], v[100:103]
	v_mfma_f32_16x16x32_bf16 v[96:99], v[212:215], v[196:199], v[96:99]
	v_mfma_f32_16x16x32_bf16 v[60:63], v[208:211], v[84:87], v[60:63]
	v_mfma_f32_16x16x32_bf16 v[72:75], v[216:219], v[84:87], v[72:75]
	v_mfma_f32_16x16x32_bf16 v[84:87], v[204:207], v[182:185], v[116:119]
	v_mfma_f32_16x16x32_bf16 v[112:115], v[216:219], v[186:189], v[112:115]
	v_mfma_f32_16x16x32_bf16 v[100:103], v[208:211], v[200:203], v[100:103]
	v_mfma_f32_16x16x32_bf16 v[96:99], v[216:219], v[200:203], v[96:99]
	v_mfma_f32_16x16x32_bf16 v[84:87], v[208:211], v[186:189], v[84:87]
	s_mov_b32 m0, s37
	s_add_u32 s100, s26, 0x80
	s_addc_u32 s101, s27, 0
	s_barrier
	ds_read_b128 v[116:119], v195 offset:16384
	ds_read_b128 v[128:131], v195 offset:17408
	ds_read_b128 v[132:135], v195 offset:18432
	ds_read_b128 v[144:147], v195 offset:19456
	ds_read_b128 v[182:185], v195 offset:20480
	ds_read_b128 v[186:189], v195 offset:21504
	ds_read_b128 v[196:199], v195 offset:22528
	global_load_lds_dwordx4 v160, s[26:27]
	s_mov_b32 m0, s38
	ds_read_b128 v[200:203], v195 offset:23552
	global_load_lds_dwordx4 v162, s[26:27]
	s_barrier
	s_waitcnt lgkmcnt(0)
	v_mfma_f32_16x16x32_bf16 v[92:95], v[40:43], v[116:119], v[92:95]
	v_mfma_f32_16x16x32_bf16 v[88:91], v[48:51], v[116:119], v[88:91]
	v_mfma_f32_16x16x32_bf16 v[68:71], v[40:43], v[132:135], v[68:71]
	v_mfma_f32_16x16x32_bf16 v[64:67], v[48:51], v[132:135], v[64:67]
	v_mfma_f32_16x16x32_bf16 v[28:31], v[40:43], v[182:185], v[28:31]
	v_mfma_f32_16x16x32_bf16 v[24:27], v[48:51], v[182:185], v[24:27]
	v_mfma_f32_16x16x32_bf16 v[12:15], v[40:43], v[196:199], v[12:15]
	v_mfma_f32_16x16x32_bf16 v[8:11], v[48:51], v[196:199], v[8:11]
	v_mfma_f32_16x16x32_bf16 v[92:95], v[44:47], v[128:131], v[92:95]
	v_mfma_f32_16x16x32_bf16 v[88:91], v[52:55], v[128:131], v[88:91]
	v_mfma_f32_16x16x32_bf16 v[68:71], v[44:47], v[144:147], v[68:71]
	v_mfma_f32_16x16x32_bf16 v[64:67], v[52:55], v[144:147], v[64:67]
	v_mfma_f32_16x16x32_bf16 v[28:31], v[44:47], v[186:189], v[28:31]
	v_mfma_f32_16x16x32_bf16 v[24:27], v[52:55], v[186:189], v[24:27]
	v_mfma_f32_16x16x32_bf16 v[12:15], v[44:47], v[200:203], v[12:15]
	v_mfma_f32_16x16x32_bf16 v[8:11], v[52:55], v[200:203], v[8:11]
	s_barrier
	s_add_i32 s59, s60, s36
	s_mov_b32 m0, s59
	s_add_u32 s24, s8, 0xb0000
	s_addc_u32 s25, s9, 0
	global_load_lds_dwordx4 v168, s[24:25]
	s_add_i32 m0, s59, 0x2000
	s_nop 0
	global_load_lds_dwordx4 v164, s[24:25]
	s_waitcnt vmcnt(6)
	s_barrier
	v_mfma_f32_16x16x32_bf16 v[36:39], v[204:207], v[132:135], v[36:39]
	v_mfma_f32_16x16x32_bf16 v[32:35], v[212:215], v[132:135], v[32:35]
	v_mfma_f32_16x16x32_bf16 v[20:23], v[204:207], v[182:185], v[20:23]
	v_mfma_f32_16x16x32_bf16 v[16:19], v[212:215], v[182:185], v[16:19]
	v_mfma_f32_16x16x32_bf16 v[4:7], v[204:207], v[196:199], v[4:7]
	v_mfma_f32_16x16x32_bf16 v[0:3], v[212:215], v[196:199], v[0:3]
	v_mfma_f32_16x16x32_bf16 v[40:43], v[204:207], v[116:119], v[80:83]
	v_mfma_f32_16x16x32_bf16 v[44:47], v[212:215], v[116:119], v[76:79]
	v_mfma_f32_16x16x32_bf16 v[36:39], v[208:211], v[144:147], v[36:39]
	v_mfma_f32_16x16x32_bf16 v[32:35], v[216:219], v[144:147], v[32:35]
	v_mfma_f32_16x16x32_bf16 v[20:23], v[208:211], v[186:189], v[20:23]
	v_mfma_f32_16x16x32_bf16 v[16:19], v[216:219], v[186:189], v[16:19]
	v_mfma_f32_16x16x32_bf16 v[4:7], v[208:211], v[200:203], v[4:7]
	v_mfma_f32_16x16x32_bf16 v[0:3], v[216:219], v[200:203], v[0:3]
	v_mfma_f32_16x16x32_bf16 v[40:43], v[208:211], v[128:131], v[40:43]
	v_mfma_f32_16x16x32_bf16 v[44:47], v[216:219], v[128:131], v[44:47]
	s_add_i32 s59, 0, 0x18000
	v_add_u32_e32 v80, s59, v194
	s_barrier
	ds_read_b128 v[48:51], v80
	ds_read_b128 v[52:55], v80 offset:1024
	ds_read_b128 v[76:79], v80 offset:2048
	ds_read_b128 v[80:83], v80 offset:3072
	s_add_u32 s24, s26, 0xb0000
	s_addc_u32 s25, s27, 0
	s_mov_b32 m0, s39
	ds_read_b128 v[116:119], v195 offset:32768
	ds_read_b128 v[128:131], v195 offset:33792
	ds_read_b128 v[182:185], v195 offset:34816
	ds_read_b128 v[186:189], v195 offset:35840
	ds_read_b128 v[196:199], v195 offset:36864
	ds_read_b128 v[200:203], v195 offset:37888
	ds_read_b128 v[204:207], v195 offset:38912
	global_load_lds_dwordx4 v160, s[24:25]
	s_mov_b32 m0, s40
	ds_read_b128 v[208:211], v195 offset:39936
	global_load_lds_dwordx4 v162, s[24:25]
	s_waitcnt lgkmcnt(8)
	s_barrier
	s_waitcnt lgkmcnt(0)
	v_mfma_f32_16x16x32_bf16 v[132:135], v[48:51], v[116:119], v[156:159]
	v_mfma_f32_16x16x32_bf16 v[156:159], v[52:55], v[128:131], v[132:135]
	v_mfma_f32_16x16x32_bf16 v[132:135], v[76:79], v[116:119], v[152:155]
	v_mfma_f32_16x16x32_bf16 v[152:155], v[80:83], v[128:131], v[132:135]
	v_mfma_f32_16x16x32_bf16 v[132:135], v[48:51], v[182:185], v[140:143]
	v_mfma_f32_16x16x32_bf16 v[140:143], v[52:55], v[186:189], v[132:135]
	v_mfma_f32_16x16x32_bf16 v[132:135], v[76:79], v[182:185], v[136:139]
	v_mfma_f32_16x16x32_bf16 v[124:127], v[48:51], v[196:199], v[124:127]
	v_mfma_f32_16x16x32_bf16 v[120:123], v[76:79], v[196:199], v[120:123]
	v_mfma_f32_16x16x32_bf16 v[108:111], v[48:51], v[204:207], v[108:111]
	v_mfma_f32_16x16x32_bf16 v[104:107], v[76:79], v[204:207], v[104:107]
	v_mfma_f32_16x16x32_bf16 v[136:139], v[80:83], v[186:189], v[132:135]
	v_mfma_f32_16x16x32_bf16 v[124:127], v[52:55], v[200:203], v[124:127]
	v_mfma_f32_16x16x32_bf16 v[120:123], v[80:83], v[200:203], v[120:123]
	v_mfma_f32_16x16x32_bf16 v[108:111], v[52:55], v[208:211], v[108:111]
	v_mfma_f32_16x16x32_bf16 v[104:107], v[80:83], v[208:211], v[104:107]
	s_barrier
	s_add_i32 s24, 0, 0x1c000
	v_add_u32_e32 v132, s24, v194
	s_add_i32 s25, s59, s36
	ds_read_b128 v[212:215], v132
	ds_read_b128 v[216:219], v132 offset:1024
	ds_read_b128 v[220:223], v132 offset:2048
	s_mov_b32 m0, s25
	ds_read_b128 v[236:239], v132 offset:3072
	global_load_lds_dwordx4 v168, s[98:99]
	s_add_i32 m0, s25, 0x2000
	s_nop 0
	global_load_lds_dwordx4 v164, s[98:99]
	s_barrier
	s_waitcnt lgkmcnt(0)
	v_mfma_f32_16x16x32_bf16 v[56:59], v[220:223], v[116:119], v[56:59]
	v_mfma_f32_16x16x32_bf16 v[132:135], v[212:215], v[116:119], v[148:151]
	v_mfma_f32_16x16x32_bf16 v[144:147], v[236:239], v[128:131], v[56:59]
	v_mfma_f32_16x16x32_bf16 v[56:59], v[212:215], v[182:185], v[60:63]
	v_mfma_f32_16x16x32_bf16 v[148:151], v[216:219], v[128:131], v[132:135]
	v_mfma_f32_16x16x32_bf16 v[132:135], v[216:219], v[186:189], v[56:59]
	v_mfma_f32_16x16x32_bf16 v[56:59], v[220:223], v[182:185], v[72:75]
	v_mfma_f32_16x16x32_bf16 v[128:131], v[236:239], v[186:189], v[56:59]
	v_mfma_f32_16x16x32_bf16 v[56:59], v[212:215], v[196:199], v[84:87]
	v_mfma_f32_16x16x32_bf16 v[116:119], v[216:219], v[200:203], v[56:59]
	v_mfma_f32_16x16x32_bf16 v[56:59], v[220:223], v[196:199], v[112:115]
	v_mfma_f32_16x16x32_bf16 v[112:115], v[236:239], v[200:203], v[56:59]
	v_mfma_f32_16x16x32_bf16 v[56:59], v[212:215], v[204:207], v[100:103]
	v_mfma_f32_16x16x32_bf16 v[100:103], v[216:219], v[208:211], v[56:59]
	v_mfma_f32_16x16x32_bf16 v[56:59], v[220:223], v[204:207], v[96:99]
	v_mfma_f32_16x16x32_bf16 v[96:99], v[236:239], v[208:211], v[56:59]
	s_mov_b32 m0, s47
	s_barrier
	s_nop 2
	ds_read_b128 v[56:59], v195 offset:49152
	ds_read_b128 v[60:63], v195 offset:50176
	ds_read_b128 v[72:75], v195 offset:51200
	ds_read_b128 v[84:87], v195 offset:52224
	ds_read_b128 v[182:185], v195 offset:53248
	ds_read_b128 v[186:189], v195 offset:54272
	ds_read_b128 v[196:199], v195 offset:55296
	global_load_lds_dwordx4 v160, s[100:101]
	s_mov_b32 m0, s49
	ds_read_b128 v[200:203], v195 offset:56320
	global_load_lds_dwordx4 v162, s[100:101]
	s_barrier
	s_waitcnt lgkmcnt(0)
	v_mfma_f32_16x16x32_bf16 v[92:95], v[48:51], v[56:59], v[92:95]
	v_mfma_f32_16x16x32_bf16 v[88:91], v[76:79], v[56:59], v[88:91]
	v_mfma_f32_16x16x32_bf16 v[68:71], v[48:51], v[72:75], v[68:71]
	v_mfma_f32_16x16x32_bf16 v[64:67], v[76:79], v[72:75], v[64:67]
	v_mfma_f32_16x16x32_bf16 v[28:31], v[48:51], v[182:185], v[28:31]
	v_mfma_f32_16x16x32_bf16 v[24:27], v[76:79], v[182:185], v[24:27]
	v_mfma_f32_16x16x32_bf16 v[12:15], v[48:51], v[196:199], v[12:15]
	v_mfma_f32_16x16x32_bf16 v[8:11], v[76:79], v[196:199], v[8:11]
	v_mfma_f32_16x16x32_bf16 v[92:95], v[52:55], v[60:63], v[92:95]
	v_mfma_f32_16x16x32_bf16 v[88:91], v[80:83], v[60:63], v[88:91]
	v_mfma_f32_16x16x32_bf16 v[68:71], v[52:55], v[84:87], v[68:71]
	v_mfma_f32_16x16x32_bf16 v[64:67], v[80:83], v[84:87], v[64:67]
	v_mfma_f32_16x16x32_bf16 v[28:31], v[52:55], v[186:189], v[28:31]
	v_mfma_f32_16x16x32_bf16 v[24:27], v[80:83], v[186:189], v[24:27]
	v_mfma_f32_16x16x32_bf16 v[12:15], v[52:55], v[200:203], v[12:15]
	v_mfma_f32_16x16x32_bf16 v[8:11], v[80:83], v[200:203], v[8:11]
	s_barrier
	s_add_i32 s24, s24, s36
	s_mov_b32 m0, s24
	s_add_u32 s8, s8, 0xb0080
	s_addc_u32 s9, s9, 0
	global_load_lds_dwordx4 v168, s[8:9]
	s_add_i32 m0, s24, 0x2000
	s_nop 0
	global_load_lds_dwordx4 v164, s[8:9]
	s_waitcnt vmcnt(6)
	s_barrier
	v_mfma_f32_16x16x32_bf16 v[40:43], v[212:215], v[56:59], v[40:43]
	v_mfma_f32_16x16x32_bf16 v[80:83], v[216:219], v[60:63], v[40:43]
	v_mfma_f32_16x16x32_bf16 v[40:43], v[220:223], v[56:59], v[44:47]
	v_mfma_f32_16x16x32_bf16 v[36:39], v[212:215], v[72:75], v[36:39]
	v_mfma_f32_16x16x32_bf16 v[32:35], v[220:223], v[72:75], v[32:35]
	v_mfma_f32_16x16x32_bf16 v[20:23], v[212:215], v[182:185], v[20:23]
	v_mfma_f32_16x16x32_bf16 v[16:19], v[220:223], v[182:185], v[16:19]
	v_mfma_f32_16x16x32_bf16 v[4:7], v[212:215], v[196:199], v[4:7]
	v_mfma_f32_16x16x32_bf16 v[0:3], v[220:223], v[196:199], v[0:3]
	v_mfma_f32_16x16x32_bf16 v[76:79], v[236:239], v[60:63], v[40:43]
	v_mfma_f32_16x16x32_bf16 v[36:39], v[216:219], v[84:87], v[36:39]
	v_mfma_f32_16x16x32_bf16 v[32:35], v[236:239], v[84:87], v[32:35]
	v_mfma_f32_16x16x32_bf16 v[20:23], v[216:219], v[186:189], v[20:23]
	v_mfma_f32_16x16x32_bf16 v[16:19], v[236:239], v[186:189], v[16:19]
	v_mfma_f32_16x16x32_bf16 v[4:7], v[216:219], v[200:203], v[4:7]
	v_mfma_f32_16x16x32_bf16 v[0:3], v[236:239], v[200:203], v[0:3]
	s_add_i32 s58, s58, 2
	s_add_u32 s56, s56, 0x100
	s_addc_u32 s57, s57, 0
	s_cmp_gt_u32 s58, 41
	s_mov_b64 s[24:25], s[2:3]
	s_barrier
	s_cbranch_scc0 .LBB0_1049
	s_lshl_b32 s2, s55, 8
	v_mov_b32_e32 v186, v193
	v_mov_b32_e32 v196, v192
	s_or_b32 s2, s2, s46
	v_mov_b32_e32 v52, 0
	v_lshl_add_u32 v182, v196, 3, s2
	s_add_i32 s2, s54, -16
	s_lshr_b32 s2, s2, 3
	s_add_i32 s2, s2, 1
	s_cmp_gt_i32 s54, 15
	s_cselect_b32 s8, s2, 0
	s_mul_i32 s96, s8, 0x1800
	s_lshl_b64 s[2:3], s[96:97], 2
	s_add_u32 s2, s41, s2
	v_ashrrev_i32_e32 v183, 31, v182
	s_addc_u32 s3, s42, s3
	v_lshlrev_b64 v[40:41], 2, v[182:183]
	v_lshl_add_u64 v[42:43], s[2:3], 0, v[40:41]
	global_load_dwordx4 v[72:75], v[42:43], off
	s_lshl_b32 s96, s8, 10
	s_lshl_b64 s[2:3], s[96:97], 2
	s_add_u32 s2, s43, s2
	s_addc_u32 s3, s44, s3
	v_lshl_add_u64 v[184:185], s[2:3], 0, v[40:41]
	s_and_b64 vcc, exec, s[4:5]
	v_mov_b32_e32 v60, 0
	v_mov_b32_e32 v61, v52
	v_mov_b32_e32 v62, 0
	v_mov_b32_e32 v63, 0
	s_cbranch_vccnz .LBB0_1052
	global_load_dwordx4 v[60:63], v[184:185], off

	.amdhsa_kernel _Z4mega5KArgs
		.amdhsa_group_segment_fixed_size 0
		.amdhsa_private_segment_fixed_size 0
		.amdhsa_kernarg_size 472
		.amdhsa_user_sgpr_count 2
		.amdhsa_user_sgpr_dispatch_ptr 0
		.amdhsa_user_sgpr_queue_ptr 0
		.amdhsa_user_sgpr_kernarg_segment_ptr 1
		.amdhsa_user_sgpr_dispatch_id 0
		.amdhsa_user_sgpr_kernarg_preload_length 0
		.amdhsa_user_sgpr_kernarg_preload_offset 0
		.amdhsa_user_sgpr_private_segment_size 0
		.amdhsa_uses_dynamic_stack 0
		.amdhsa_enable_private_segment 0
		.amdhsa_system_sgpr_workgroup_id_x 1
		.amdhsa_system_sgpr_workgroup_id_y 0
		.amdhsa_system_sgpr_workgroup_id_z 0
		.amdhsa_system_sgpr_workgroup_info 0
		.amdhsa_system_vgpr_workitem_id 2
		.amdhsa_next_free_vgpr 256
		.amdhsa_next_free_sgpr 102
		.amdhsa_accum_offset 256
		.amdhsa_reserve_vcc 1
		.amdhsa_float_round_mode_32 0
		.amdhsa_float_round_mode_16_64 0
		.amdhsa_float_denorm_mode_32 3
		.amdhsa_float_denorm_mode_16_64 3
		.amdhsa_dx10_clamp 1
		.amdhsa_ieee_mode 1
		.amdhsa_fp16_overflow 0
		.amdhsa_tg_split 0
		.amdhsa_exception_fp_ieee_invalid_op 0
		.amdhsa_exception_fp_denorm_src 0
		.amdhsa_exception_fp_ieee_div_zero 0
		.amdhsa_exception_fp_ieee_overflow 0
		.amdhsa_exception_fp_ieee_underflow 0
		.amdhsa_exception_fp_ieee_inexact 0
		.amdhsa_exception_int_div_zero 0
	.end_amdhsa_kernel

amdhsa.kernels:
  - .agpr_count:     0
    .args:
      - .offset:         0
        .size:           216
        .value_kind:     by_value
      - .offset:         216
        .size:           4
        .value_kind:     hidden_block_count_x
      - .offset:         220
        .size:           4
        .value_kind:     hidden_block_count_y
      - .offset:         224
        .size:           4
        .value_kind:     hidden_block_count_z
      - .offset:         228
        .size:           2
        .value_kind:     hidden_group_size_x
      - .offset:         230
        .size:           2
        .value_kind:     hidden_group_size_y
      - .offset:         232
        .size:           2
        .value_kind:     hidden_group_size_z
      - .offset:         234
        .size:           2
        .value_kind:     hidden_remainder_x
      - .offset:         236
        .size:           2
        .value_kind:     hidden_remainder_y
      - .offset:         238
        .size:           2
        .value_kind:     hidden_remainder_z
      - .offset:         256
        .size:           8
        .value_kind:     hidden_global_offset_x
      - .offset:         264
        .size:           8
        .value_kind:     hidden_global_offset_y
      - .offset:         272
        .size:           8
        .value_kind:     hidden_global_offset_z
      - .offset:         280
        .size:           2
        .value_kind:     hidden_grid_dims
      - .offset:         304
        .size:           8
        .value_kind:     hidden_multigrid_sync_arg
      - .offset:         336
        .size:           4
        .value_kind:     hidden_dynamic_lds_size
    .group_segment_fixed_size: 0
    .kernarg_segment_align: 8
    .kernarg_segment_size: 472
    .language:       OpenCL C
    .language_version:
      - 2
      - 0
    .max_flat_workgroup_size: 512
    .name:           _Z4mega5KArgs
    .private_segment_fixed_size: 0
    .sgpr_count:     108
    .sgpr_spill_count: 74
    .symbol:         _Z4mega5KArgs.kd
    .uniform_work_group_size: 1
    .uses_dynamic_stack: false
    .vgpr_count:     256
    .vgpr_spill_count: 0
    .wavefront_size: 64
